# attention job loop rewritten by hand; d=1 and d=4 tiles processed as dilated-adjacent pairs sharing one K/V stream (22 row pieces per two tiles instead of 38)
# speedup vs baseline: 1.0287x; 1.0287x over previous
.LBB0_296:
	v_writelane_b32 v244, s2, 31
	v_writelane_b32 v244, s84, 32
	v_writelane_b32 v244, s85, 33
	v_writelane_b32 v244, s86, 34
	v_writelane_b32 v244, s87, 35
	v_writelane_b32 v244, s96, 36
	v_writelane_b32 v244, s97, 37
	v_writelane_b32 v244, s50, 38
	v_writelane_b32 v244, s51, 39
	s_mov_b64 s[46:47], s[86:87]
	s_mov_b32 s10, s72
	v_readlane_b32 s11, v244, 0
	s_add_u32 s48, s46, 0x18800200
	s_addc_u32 s49, s47, 0
	s_add_u32 s50, s46, 0x1b00000
	s_addc_u32 s51, s47, 0
	s_mul_i32 s90, s10, 0x2800
	s_add_i32 s90, s90, 0x10800
	s_add_i32 s12, s90, 0x0
	s_add_i32 s13, s90, 0x800
	s_add_i32 s14, s90, 0x1000
	s_add_i32 s15, s90, 0x1800
	s_add_i32 s16, s90, 0x2000
	v_and_b32_e32 v146, 63, v214
	v_and_b32_e32 v216, 15, v146
	v_lshrrev_b32_e32 v217, 4, v146
	v_lshrrev_b32_e32 v218, 3, v146
	v_and_b32_e32 v219, 7, v146
	v_lshlrev_b32_e32 v229, 2, v217
	v_mov_b32_e32 v230, 0xff800000
	v_lshrrev_b32_e32 v147, 1, v218
	v_xor_b32_e32 v220, v219, v147
	v_xor_b32_e32 v221, 4, v220
	v_lshlrev_b32_e32 v220, 4, v220
	v_lshlrev_b32_e32 v221, 4, v221
	v_lshlrev_b32_e32 v148, 1, v147
	v_xor_b32_e32 v222, v219, v148
	v_lshlrev_b32_e32 v222, 4, v222
	v_lshrrev_b32_e32 v147, 1, v216
	v_xor_b32_e32 v148, v217, v147
	v_or_b32_e32 v149, 4, v217
	v_xor_b32_e32 v149, v149, v147
	v_lshlrev_b32_e32 v150, 7, v216
	v_lshl_add_u32 v223, v148, 4, v150
	v_lshl_add_u32 v224, v149, 4, v150
	v_lshrrev_b32_e32 v147, 2, v216
	v_lshl_add_u32 v147, v217, 2, v147
	v_and_b32_e32 v148, 3, v216
	v_lshrrev_b32_e32 v149, 1, v148
	v_bfe_u32 v150, v147, 1, 2
	v_lshlrev_b32_e32 v150, 1, v150
	v_and_b32_e32 v151, 1, v148
	v_lshlrev_b32_e32 v151, 3, v151
	v_lshl_add_u32 v151, v147, 7, v151
	v_or_b32_e32 v152, 0, v149
	v_xor_b32_e32 v152, v152, v150
	v_lshl_add_u32 v225, v152, 4, v151
	v_or_b32_e32 v152, 2, v149
	v_xor_b32_e32 v152, v152, v150
	v_lshl_add_u32 v226, v152, 4, v151
	v_or_b32_e32 v152, 4, v149
	v_xor_b32_e32 v152, v152, v150
	v_lshl_add_u32 v227, v152, 4, v151
	v_or_b32_e32 v152, 6, v149
	v_xor_b32_e32 v152, v152, v150
	v_lshl_add_u32 v228, v152, 4, v151
	v_and_b32_e32 v147, 1, v217
	v_lshrrev_b32_e32 v148, 1, v217
	v_lshlrev_b32_e32 v147, 5, v147
	v_lshl_add_u32 v233, v148, 4, v147
	v_or_b32_e32 v147, 0, v229
	v_cmp_lt_u32_e64 s[52:53], v147, v216
	v_cmp_gt_u32_e64 s[62:63], v147, v216
	v_or_b32_e32 v147, 1, v229
	v_cmp_lt_u32_e64 s[56:57], v147, v216
	v_cmp_gt_u32_e64 s[64:65], v147, v216
	v_or_b32_e32 v147, 2, v229
	v_cmp_lt_u32_e64 s[58:59], v147, v216
	v_cmp_gt_u32_e64 s[70:71], v147, v216
	v_or_b32_e32 v147, 3, v229
	v_cmp_lt_u32_e64 s[60:61], v147, v216
	v_cmp_gt_u32_e64 s[72:73], v147, v216
	v_cmp_eq_u32_e64 s[74:75], 0, v217
	s_lshl_b32 s82, s10, 5
	s_lshr_b32 s90, s10, 2
	s_and_b32 s91, s10, 3
	s_lshl_b32 s90, s90, 7
	s_add_i32 s83, s90, s91
	s_mov_b32 s84, s10
	s_add_i32 s85, s10, 8
	s_mul_hi_u32 s43, s11, 0xaaaaaaab
	s_lshr_b32 s43, s43, 7
	s_mul_i32 s90, s43, 0xc0
	s_sub_i32 s90, s11, s90
	s_lshl_b32 s42, s90, 8
	s_cmp_lt_u32 s90, 64
	s_mov_b32 s91, 0x7fffc000
	s_cselect_b32 s91, 0xfffff800, s91
	s_movk_i32 s40, 0x3fff
	s_cselect_b32 s40, 0x7ff, s40
	s_and_b32 s91, s91, s42
	s_sub_i32 s38, s42, s91
	s_mul_i32 s90, s43, 0x600000
	s_lshl_b32 s91, s91, 7
	s_add_u32 s90, s90, s91
	s_add_u32 s18, s46, 0x9800000
	s_addc_u32 s19, s47, 0
	s_add_u32 s18, s18, s90
	s_addc_u32 s19, s19, 0
	s_add_u32 s20, s46, 0xe000000
	s_addc_u32 s21, s47, 0
	s_add_u32 s20, s20, s90
	s_addc_u32 s21, s21, 0
	s_add_u32 s24, s46, 0x12800000
	s_addc_u32 s25, s47, 0
	s_add_u32 s24, s24, s90
	s_addc_u32 s25, s25, 0
	s_add_i32 s76, s38, s82
	v_lshlrev_b32_e32 v231, 0, v218
	v_add_u32_e32 v232, 8, v218
	v_lshlrev_b32_e32 v232, 0, v232
	s_add_i32 s93, s76, 0
	s_mov_b32 m0, s12
	v_add_u32_e32 v164, s93, v231
	v_lshl_or_b32 v164, v164, 7, v220
	global_load_lds_dwordx4 v164, s[18:19]
	s_add_i32 m0, s12, 0x400
	v_add_u32_e32 v165, s93, v232
	v_lshl_or_b32 v165, v165, 7, v221
	global_load_lds_dwordx4 v165, s[18:19]
	s_add_i32 s93, s76, 16
	s_mov_b32 m0, s13
	v_add_u32_e32 v164, s93, v231
	v_lshl_or_b32 v164, v164, 7, v220
	global_load_lds_dwordx4 v164, s[18:19]
	s_add_i32 m0, s13, 0x400
	v_add_u32_e32 v165, s93, v232
	v_lshl_or_b32 v165, v165, 7, v221
	global_load_lds_dwordx4 v165, s[18:19]
	s_add_i32 s93, s76, 0xffffffc0
	s_mov_b32 m0, s14
	v_add_u32_e32 v164, s93, v231
	v_max_i32_e32 v164, 0, v164
	v_min_u32_e32 v164, s40, v164
	v_lshl_or_b32 v164, v164, 7, v220
	global_load_lds_dwordx4 v164, s[20:21]
	s_add_i32 m0, s14, 0x400
	v_add_u32_e32 v165, s93, v232
	v_max_i32_e32 v165, 0, v165
	v_min_u32_e32 v165, s40, v165
	v_lshl_or_b32 v165, v165, 7, v221
	global_load_lds_dwordx4 v165, s[20:21]
	s_add_i32 s93, s76, 0xffffffd0
	s_mov_b32 m0, s15
	v_add_u32_e32 v164, s93, v231
	v_max_i32_e32 v164, 0, v164
	v_min_u32_e32 v164, s40, v164
	v_lshl_or_b32 v164, v164, 7, v220
	global_load_lds_dwordx4 v164, s[20:21]
	s_add_i32 m0, s15, 0x400
	v_add_u32_e32 v165, s93, v232
	v_max_i32_e32 v165, 0, v165
	v_min_u32_e32 v165, s40, v165
	v_lshl_or_b32 v165, v165, 7, v221
	global_load_lds_dwordx4 v165, s[20:21]
.Latt_unit:
	s_add_i32 s92, s11, s66
	s_cmpk_lt_u32 s92, 0x900
	s_cselect_b32 s92, s92, s11
	s_mul_hi_u32 s45, s92, 0xaaaaaaab
	s_lshr_b32 s45, s45, 7
	s_mul_i32 s90, s45, 0xc0
	s_sub_i32 s90, s92, s90
	s_lshl_b32 s44, s90, 8
	s_cmp_lt_u32 s90, 64
	s_mov_b32 s91, 0x7fffc000
	s_cselect_b32 s91, 0xfffff800, s91
	s_movk_i32 s41, 0x3fff
	s_cselect_b32 s41, 0x7ff, s41
	s_and_b32 s91, s91, s44
	s_sub_i32 s39, s44, s91
	s_mul_i32 s90, s45, 0x600000
	s_lshl_b32 s91, s91, 7
	s_add_u32 s90, s90, s91
	s_add_u32 s30, s46, 0x9800000
	s_addc_u32 s31, s47, 0
	s_add_u32 s30, s30, s90
	s_addc_u32 s31, s31, 0
	s_add_u32 s34, s46, 0xe000000
	s_addc_u32 s35, s47, 0
	s_add_u32 s34, s34, s90
	s_addc_u32 s35, s35, 0
	s_add_u32 s36, s46, 0x12800000
	s_addc_u32 s37, s47, 0
	s_add_u32 s36, s36, s90
	s_addc_u32 s37, s37, 0
	s_add_i32 s76, s38, s82
	s_add_i32 s79, s38, s83
	v_lshlrev_b32_e32 v231, 0, v218
	v_add_u32_e32 v232, 8, v218
	v_lshlrev_b32_e32 v232, 0, v232
	v_lshlrev_b32_e32 v162, 2, v218
	v_add_u32_e32 v163, 8, v218
	v_lshlrev_b32_e32 v163, 2, v163
	s_waitcnt lgkmcnt(0)
	s_add_i32 s93, s76, 0xffffffe0
	s_mov_b32 m0, s16
	v_add_u32_e32 v164, s93, v231
	v_max_i32_e32 v164, 0, v164
	v_min_u32_e32 v164, s40, v164
	v_lshl_or_b32 v164, v164, 7, v220
	global_load_lds_dwordx4 v164, s[20:21]
	s_add_i32 m0, s16, 0x400
	v_add_u32_e32 v165, s93, v232
	v_max_i32_e32 v165, 0, v165
	v_min_u32_e32 v165, s40, v165
	v_lshl_or_b32 v165, v165, 7, v221
	global_load_lds_dwordx4 v165, s[20:21]
	s_waitcnt vmcnt(8)
	v_add_u32_e32 v146, s12, v223
	v_add_u32_e32 v147, s12, v224
	ds_read_b128 v[72:75], v146
	ds_read_b128 v[76:79], v147
	s_waitcnt lgkmcnt(0)
	s_add_i32 s93, s76, -16
	s_mov_b32 m0, s12
	v_add_u32_e32 v164, s93, v231
	v_max_i32_e32 v164, 0, v164
	v_min_u32_e32 v164, s40, v164
	v_lshl_or_b32 v164, v164, 7, v220
	global_load_lds_dwordx4 v164, s[20:21]
	s_add_i32 m0, s12, 0x400
	v_add_u32_e32 v165, s93, v232
	v_max_i32_e32 v165, 0, v165
	v_min_u32_e32 v165, s40, v165
	v_lshl_or_b32 v165, v165, 7, v221
	global_load_lds_dwordx4 v165, s[20:21]
	s_waitcnt vmcnt(8)
	v_add_u32_e32 v146, s13, v223
	v_add_u32_e32 v147, s13, v224
	ds_read_b128 v[80:83], v146
	ds_read_b128 v[84:87], v147
	s_waitcnt lgkmcnt(0)
	s_add_i32 s93, s76, 0
	s_mov_b32 m0, s13
	v_add_u32_e32 v164, s93, v231
	v_max_i32_e32 v164, 0, v164
	v_min_u32_e32 v164, s40, v164
	v_lshl_or_b32 v164, v164, 7, v220
	global_load_lds_dwordx4 v164, s[20:21]
	s_add_i32 m0, s13, 0x400
	v_add_u32_e32 v165, s93, v232
	v_max_i32_e32 v165, 0, v165
	v_min_u32_e32 v165, s40, v165
	v_lshl_or_b32 v165, v165, 7, v221
	global_load_lds_dwordx4 v165, s[20:21]
	s_waitcnt vmcnt(8)
	v_add_u32_e32 v146, s14, v223
	v_add_u32_e32 v147, s14, v224
	ds_read_b128 v[88:91], v146
	ds_read_b128 v[92:95], v147
	s_waitcnt lgkmcnt(0)
	v_mfma_f32_16x16x32_bf16 v[0:3], v[88:91], v[72:75], 0
	v_mfma_f32_16x16x32_bf16 v[0:3], v[92:95], v[76:79], v[0:3]
	s_waitcnt lgkmcnt(0)
	s_add_i32 s93, s76, 16
	s_mov_b32 m0, s14
	v_add_u32_e32 v164, s93, v231
	v_max_i32_e32 v164, 0, v164
	v_min_u32_e32 v164, s40, v164
	v_lshl_or_b32 v164, v164, 7, v220
	global_load_lds_dwordx4 v164, s[20:21]
	s_add_i32 m0, s14, 0x400
	v_add_u32_e32 v165, s93, v232
	v_max_i32_e32 v165, 0, v165
	v_min_u32_e32 v165, s40, v165
	v_lshl_or_b32 v165, v165, 7, v221
	global_load_lds_dwordx4 v165, s[20:21]
	s_waitcnt vmcnt(8)
	v_add_u32_e32 v146, s15, v223
	v_add_u32_e32 v147, s15, v224
	ds_read_b128 v[88:91], v146
	ds_read_b128 v[92:95], v147
	s_waitcnt lgkmcnt(0)
	v_mfma_f32_16x16x32_bf16 v[4:7], v[88:91], v[72:75], 0
	v_mfma_f32_16x16x32_bf16 v[36:39], v[88:91], v[80:83], 0
	v_mfma_f32_16x16x32_bf16 v[4:7], v[92:95], v[76:79], v[4:7]
	v_mfma_f32_16x16x32_bf16 v[36:39], v[92:95], v[84:87], v[36:39]
	s_waitcnt lgkmcnt(0)
	s_add_i32 s93, s76, 32
	s_mov_b32 m0, s15
	v_add_u32_e32 v164, s93, v231
	v_max_i32_e32 v164, 0, v164
	v_min_u32_e32 v164, s40, v164
	v_lshl_or_b32 v164, v164, 7, v220
	global_load_lds_dwordx4 v164, s[20:21]
	s_add_i32 m0, s15, 0x400
	v_add_u32_e32 v165, s93, v232
	v_max_i32_e32 v165, 0, v165
	v_min_u32_e32 v165, s40, v165
	v_lshl_or_b32 v165, v165, 7, v221
	global_load_lds_dwordx4 v165, s[20:21]
	s_waitcnt vmcnt(8)
	v_add_u32_e32 v146, s16, v223
	v_add_u32_e32 v147, s16, v224
	ds_read_b128 v[88:91], v146
	ds_read_b128 v[92:95], v147
	s_waitcnt lgkmcnt(0)
	v_mfma_f32_16x16x32_bf16 v[8:11], v[88:91], v[72:75], 0
	v_mfma_f32_16x16x32_bf16 v[40:43], v[88:91], v[80:83], 0
	v_mfma_f32_16x16x32_bf16 v[8:11], v[92:95], v[76:79], v[8:11]
	v_mfma_f32_16x16x32_bf16 v[40:43], v[92:95], v[84:87], v[40:43]
	s_waitcnt lgkmcnt(0)
	s_add_i32 s93, s76, 48
	s_mov_b32 m0, s16
	v_add_u32_e32 v164, s93, v231
	v_max_i32_e32 v164, 0, v164
	v_min_u32_e32 v164, s40, v164
	v_lshl_or_b32 v164, v164, 7, v220
	global_load_lds_dwordx4 v164, s[20:21]
	s_add_i32 m0, s16, 0x400
	v_add_u32_e32 v165, s93, v232
	v_max_i32_e32 v165, 0, v165
	v_min_u32_e32 v165, s40, v165
	v_lshl_or_b32 v165, v165, 7, v221
	global_load_lds_dwordx4 v165, s[20:21]
	s_waitcnt vmcnt(8)
	v_add_u32_e32 v146, s12, v223
	v_add_u32_e32 v147, s12, v224
	ds_read_b128 v[88:91], v146
	ds_read_b128 v[92:95], v147
	s_waitcnt lgkmcnt(0)
	v_mfma_f32_16x16x32_bf16 v[12:15], v[88:91], v[72:75], 0
	v_mfma_f32_16x16x32_bf16 v[44:47], v[88:91], v[80:83], 0
	v_mfma_f32_16x16x32_bf16 v[12:15], v[92:95], v[76:79], v[12:15]
	v_mfma_f32_16x16x32_bf16 v[44:47], v[92:95], v[84:87], v[44:47]
	s_waitcnt lgkmcnt(0)
	s_add_i32 s93, s76, 64
	s_mov_b32 m0, s12
	v_add_u32_e32 v164, s93, v231
	v_max_i32_e32 v164, 0, v164
	v_min_u32_e32 v164, s40, v164
	v_lshl_or_b32 v164, v164, 7, v220
	global_load_lds_dwordx4 v164, s[20:21]
	s_add_i32 m0, s12, 0x400
	v_add_u32_e32 v165, s93, v232
	v_max_i32_e32 v165, 0, v165
	v_min_u32_e32 v165, s40, v165
	v_lshl_or_b32 v165, v165, 7, v221
	global_load_lds_dwordx4 v165, s[20:21]
	s_waitcnt vmcnt(8)
	v_add_u32_e32 v146, s13, v223
	v_add_u32_e32 v147, s13, v224
	ds_read_b128 v[88:91], v146
	ds_read_b128 v[92:95], v147
	s_waitcnt lgkmcnt(0)
	v_mfma_f32_16x16x32_bf16 v[16:19], v[88:91], v[72:75], 0
	v_mfma_f32_16x16x32_bf16 v[48:51], v[88:91], v[80:83], 0
	v_mfma_f32_16x16x32_bf16 v[16:19], v[92:95], v[76:79], v[16:19]
	v_mfma_f32_16x16x32_bf16 v[48:51], v[92:95], v[84:87], v[48:51]
	s_waitcnt lgkmcnt(0)
	s_add_i32 s93, s76, 0x50
	s_mov_b32 m0, s13
	v_add_u32_e32 v164, s93, v231
	v_max_i32_e32 v164, 0, v164
	v_min_u32_e32 v164, s40, v164
	v_lshl_or_b32 v164, v164, 7, v220
	global_load_lds_dwordx4 v164, s[20:21]
	s_add_i32 m0, s13, 0x400
	v_add_u32_e32 v165, s93, v232
	v_max_i32_e32 v165, 0, v165
	v_min_u32_e32 v165, s40, v165
	v_lshl_or_b32 v165, v165, 7, v221
	global_load_lds_dwordx4 v165, s[20:21]
	s_waitcnt vmcnt(8)
	v_add_u32_e32 v146, s14, v223
	v_add_u32_e32 v147, s14, v224
	ds_read_b128 v[88:91], v146
	ds_read_b128 v[92:95], v147
	s_waitcnt lgkmcnt(0)
	v_mfma_f32_16x16x32_bf16 v[20:23], v[88:91], v[72:75], 0
	v_mfma_f32_16x16x32_bf16 v[52:55], v[88:91], v[80:83], 0
	v_mfma_f32_16x16x32_bf16 v[20:23], v[92:95], v[76:79], v[20:23]
	v_mfma_f32_16x16x32_bf16 v[52:55], v[92:95], v[84:87], v[52:55]
	s_waitcnt lgkmcnt(0)
	s_add_i32 s93, s76, 0xffffffc0
	s_mov_b32 m0, s14
	v_add_u32_e32 v164, s93, v231
	v_max_i32_e32 v164, 0, v164
	v_min_u32_e32 v164, s40, v164
	v_lshl_or_b32 v164, v164, 7, v222
	global_load_lds_dwordx4 v164, s[24:25]
	s_add_i32 m0, s14, 0x400
	v_add_u32_e32 v165, s93, v232
	v_max_i32_e32 v165, 0, v165
	v_min_u32_e32 v165, s40, v165
	v_lshl_or_b32 v165, v165, 7, v222
	global_load_lds_dwordx4 v165, s[24:25]
	s_waitcnt vmcnt(8)
	v_add_u32_e32 v146, s15, v223
	v_add_u32_e32 v147, s15, v224
	ds_read_b128 v[88:91], v146
	ds_read_b128 v[92:95], v147
	s_waitcnt lgkmcnt(0)
	v_mfma_f32_16x16x32_bf16 v[24:27], v[88:91], v[72:75], 0
	v_mfma_f32_16x16x32_bf16 v[56:59], v[88:91], v[80:83], 0
	v_mfma_f32_16x16x32_bf16 v[24:27], v[92:95], v[76:79], v[24:27]
	v_mfma_f32_16x16x32_bf16 v[56:59], v[92:95], v[84:87], v[56:59]
	s_waitcnt lgkmcnt(0)
	s_add_i32 s93, s76, 0xffffffd0
	s_mov_b32 m0, s15
	v_add_u32_e32 v164, s93, v231
	v_max_i32_e32 v164, 0, v164
	v_min_u32_e32 v164, s40, v164
	v_lshl_or_b32 v164, v164, 7, v222
	global_load_lds_dwordx4 v164, s[24:25]
	s_add_i32 m0, s15, 0x400
	v_add_u32_e32 v165, s93, v232
	v_max_i32_e32 v165, 0, v165
	v_min_u32_e32 v165, s40, v165
	v_lshl_or_b32 v165, v165, 7, v222
	global_load_lds_dwordx4 v165, s[24:25]
	s_waitcnt vmcnt(8)
	v_add_u32_e32 v146, s16, v223
	v_add_u32_e32 v147, s16, v224
	ds_read_b128 v[88:91], v146
	ds_read_b128 v[92:95], v147
	s_waitcnt lgkmcnt(0)
	v_mfma_f32_16x16x32_bf16 v[28:31], v[88:91], v[72:75], 0
	v_mfma_f32_16x16x32_bf16 v[60:63], v[88:91], v[80:83], 0
	v_mfma_f32_16x16x32_bf16 v[28:31], v[92:95], v[76:79], v[28:31]
	v_mfma_f32_16x16x32_bf16 v[60:63], v[92:95], v[84:87], v[60:63]
	s_waitcnt lgkmcnt(0)
	s_add_i32 s93, s76, 0xffffffe0
	s_mov_b32 m0, s16
	v_add_u32_e32 v164, s93, v231
	v_max_i32_e32 v164, 0, v164
	v_min_u32_e32 v164, s40, v164
	v_lshl_or_b32 v164, v164, 7, v222
	global_load_lds_dwordx4 v164, s[24:25]
	s_add_i32 m0, s16, 0x400
	v_add_u32_e32 v165, s93, v232
	v_max_i32_e32 v165, 0, v165
	v_min_u32_e32 v165, s40, v165
	v_lshl_or_b32 v165, v165, 7, v222
	global_load_lds_dwordx4 v165, s[24:25]
	s_waitcnt vmcnt(8)
	v_add_u32_e32 v146, s12, v223
	v_add_u32_e32 v147, s12, v224
	ds_read_b128 v[88:91], v146
	ds_read_b128 v[92:95], v147
	s_waitcnt lgkmcnt(0)
	v_mfma_f32_16x16x32_bf16 v[32:35], v[88:91], v[72:75], 0
	v_mfma_f32_16x16x32_bf16 v[64:67], v[88:91], v[80:83], 0
	v_mfma_f32_16x16x32_bf16 v[32:35], v[92:95], v[76:79], v[32:35]
	v_mfma_f32_16x16x32_bf16 v[64:67], v[92:95], v[84:87], v[64:67]
	s_waitcnt lgkmcnt(0)
	s_add_i32 s93, s76, -16
	s_mov_b32 m0, s12
	v_add_u32_e32 v164, s93, v231
	v_max_i32_e32 v164, 0, v164
	v_min_u32_e32 v164, s40, v164
	v_lshl_or_b32 v164, v164, 7, v222
	global_load_lds_dwordx4 v164, s[24:25]
	s_add_i32 m0, s12, 0x400
	v_add_u32_e32 v165, s93, v232
	v_max_i32_e32 v165, 0, v165
	v_min_u32_e32 v165, s40, v165
	v_lshl_or_b32 v165, v165, 7, v222
	global_load_lds_dwordx4 v165, s[24:25]
	s_waitcnt vmcnt(8)
	v_add_u32_e32 v146, s13, v223
	v_add_u32_e32 v147, s13, v224
	ds_read_b128 v[88:91], v146
	ds_read_b128 v[92:95], v147
	s_waitcnt lgkmcnt(0)
	v_mfma_f32_16x16x32_bf16 v[68:71], v[88:91], v[80:83], 0
	v_mfma_f32_16x16x32_bf16 v[68:71], v[92:95], v[84:87], v[68:71]
	v_mov_b32_e32 v188, s82
	v_add_u32_e32 v188, v216, v188
	v_lshrrev_b32_e32 v146, 4, v188
	v_xor_b32_e32 v146, v146, v188
	v_and_b32_e32 v146, 15, v146
	v_lshlrev_b32_e32 v147, 8, v188
	v_or_b32_e32 v148, 0, v217
	v_xor_b32_e32 v148, v148, v146
	v_lshl_add_u32 v190, v148, 4, v147
	v_or_b32_e32 v148, 4, v217
	v_xor_b32_e32 v148, v148, v146
	v_lshl_add_u32 v191, v148, 4, v147
	v_or_b32_e32 v148, 8, v217
	v_xor_b32_e32 v148, v148, v146
	v_lshl_add_u32 v192, v148, 4, v147
	v_or_b32_e32 v148, 12, v217
	v_xor_b32_e32 v148, v148, v146
	v_lshl_add_u32 v193, v148, 4, v147
	v_lshlrev_b32_e32 v194, 3, v188
	v_add_u32_e32 v194, 0x10000, v194
	v_mov_b32_e32 v189, s82
	v_add_u32_e32 v189, v216, v189
	v_add_u32_e32 v189, 16, v189
	v_lshrrev_b32_e32 v146, 4, v189
	v_xor_b32_e32 v146, v146, v189
	v_and_b32_e32 v146, 15, v146
	v_lshlrev_b32_e32 v147, 8, v189
	v_or_b32_e32 v148, 0, v217
	v_xor_b32_e32 v148, v148, v146
	v_lshl_add_u32 v195, v148, 4, v147
	v_or_b32_e32 v148, 4, v217
	v_xor_b32_e32 v148, v148, v146
	v_lshl_add_u32 v196, v148, 4, v147
	v_or_b32_e32 v148, 8, v217
	v_xor_b32_e32 v148, v148, v146
	v_lshl_add_u32 v197, v148, 4, v147
	v_or_b32_e32 v148, 12, v217
	v_xor_b32_e32 v148, v148, v146
	v_lshl_add_u32 v198, v148, 4, v147
	v_lshlrev_b32_e32 v199, 3, v189
	v_add_u32_e32 v199, 0x10000, v199
	s_add_i32 s90, s76, 0x5f
	s_cmp_gt_i32 s90, s40
	s_cselect_b32 s96, 1, 0
	s_cmp_lt_i32 s76, 64
	s_cselect_b32 s96, 1, s96
	s_ashr_i32 s77, s76, 0
	s_sub_i32 s77, 64, s77
	s_sub_i32 s78, s40, s76
	s_ashr_i32 s78, s78, 0
	s_add_i32 s78, s78, 64
	v_cndmask_b32_e64 v0, v0, v230, s[52:53]
	v_cndmask_b32_e64 v32, v32, v230, s[62:63]
	v_cndmask_b32_e64 v1, v1, v230, s[56:57]
	v_cndmask_b32_e64 v33, v33, v230, s[64:65]
	v_cndmask_b32_e64 v2, v2, v230, s[58:59]
	v_cndmask_b32_e64 v34, v34, v230, s[70:71]
	v_cndmask_b32_e64 v3, v3, v230, s[60:61]
	v_cndmask_b32_e64 v35, v35, v230, s[72:73]
	s_cmp_eq_u32 s96, 0
	s_cbranch_scc1 .Latt_noedge_1
	v_sub_u32_e32 v200, s77, v229
	s_sub_i32 s91, s78, s77
	v_sub_u32_e32 v150, 0, v200
	v_sub_u32_e32 v151, 1, v200
	v_sub_u32_e32 v152, 2, v200
	v_sub_u32_e32 v153, 3, v200
	v_cmp_lt_u32_e64 s[94:95], s91, v150
	v_cmp_lt_u32_e64 s[86:87], s91, v151
	v_cmp_lt_u32_e64 s[0:1], s91, v152
	v_cmp_lt_u32_e64 s[2:3], s91, v153
	v_cndmask_b32_e64 v0, v0, v230, s[94:95]
	v_cndmask_b32_e64 v1, v1, v230, s[86:87]
	v_cndmask_b32_e64 v2, v2, v230, s[0:1]
	v_cndmask_b32_e64 v3, v3, v230, s[2:3]
	v_sub_u32_e32 v150, 16, v200
	v_sub_u32_e32 v151, 17, v200
	v_sub_u32_e32 v152, 18, v200
	v_sub_u32_e32 v153, 19, v200
	v_cmp_lt_u32_e64 s[94:95], s91, v150
	v_cmp_lt_u32_e64 s[86:87], s91, v151
	v_cmp_lt_u32_e64 s[0:1], s91, v152
	v_cmp_lt_u32_e64 s[2:3], s91, v153
	v_cndmask_b32_e64 v4, v4, v230, s[94:95]
	v_cndmask_b32_e64 v5, v5, v230, s[86:87]
	v_cndmask_b32_e64 v6, v6, v230, s[0:1]
	v_cndmask_b32_e64 v7, v7, v230, s[2:3]
	v_sub_u32_e32 v150, 32, v200
	v_sub_u32_e32 v151, 33, v200
	v_sub_u32_e32 v152, 34, v200
	v_sub_u32_e32 v153, 35, v200
	v_cmp_lt_u32_e64 s[94:95], s91, v150
	v_cmp_lt_u32_e64 s[86:87], s91, v151
	v_cmp_lt_u32_e64 s[0:1], s91, v152
	v_cmp_lt_u32_e64 s[2:3], s91, v153
	v_cndmask_b32_e64 v8, v8, v230, s[94:95]
	v_cndmask_b32_e64 v9, v9, v230, s[86:87]
	v_cndmask_b32_e64 v10, v10, v230, s[0:1]
	v_cndmask_b32_e64 v11, v11, v230, s[2:3]
	v_sub_u32_e32 v150, 48, v200
	v_sub_u32_e32 v151, 49, v200
	v_sub_u32_e32 v152, 50, v200
	v_sub_u32_e32 v153, 51, v200
	v_cmp_lt_u32_e64 s[94:95], s91, v150
	v_cmp_lt_u32_e64 s[86:87], s91, v151
	v_cmp_lt_u32_e64 s[0:1], s91, v152
	v_cmp_lt_u32_e64 s[2:3], s91, v153
	v_cndmask_b32_e64 v12, v12, v230, s[94:95]
	v_cndmask_b32_e64 v13, v13, v230, s[86:87]
	v_cndmask_b32_e64 v14, v14, v230, s[0:1]
	v_cndmask_b32_e64 v15, v15, v230, s[2:3]
	v_sub_u32_e32 v150, 64, v200
	v_sub_u32_e32 v151, 0x41, v200
	v_sub_u32_e32 v152, 0x42, v200
	v_sub_u32_e32 v153, 0x43, v200
	v_cmp_lt_u32_e64 s[94:95], s91, v150
	v_cmp_lt_u32_e64 s[86:87], s91, v151
	v_cmp_lt_u32_e64 s[0:1], s91, v152
	v_cmp_lt_u32_e64 s[2:3], s91, v153
	v_cndmask_b32_e64 v16, v16, v230, s[94:95]
	v_cndmask_b32_e64 v17, v17, v230, s[86:87]
	v_cndmask_b32_e64 v18, v18, v230, s[0:1]
	v_cndmask_b32_e64 v19, v19, v230, s[2:3]
	v_sub_u32_e32 v150, 0x50, v200
	v_sub_u32_e32 v151, 0x51, v200
	v_sub_u32_e32 v152, 0x52, v200
	v_sub_u32_e32 v153, 0x53, v200
	v_cmp_lt_u32_e64 s[94:95], s91, v150
	v_cmp_lt_u32_e64 s[86:87], s91, v151
	v_cmp_lt_u32_e64 s[0:1], s91, v152
	v_cmp_lt_u32_e64 s[2:3], s91, v153
	v_cndmask_b32_e64 v20, v20, v230, s[94:95]
	v_cndmask_b32_e64 v21, v21, v230, s[86:87]
	v_cndmask_b32_e64 v22, v22, v230, s[0:1]
	v_cndmask_b32_e64 v23, v23, v230, s[2:3]
	v_sub_u32_e32 v150, 0x60, v200
	v_sub_u32_e32 v151, 0x61, v200
	v_sub_u32_e32 v152, 0x62, v200
	v_sub_u32_e32 v153, 0x63, v200
	v_cmp_lt_u32_e64 s[94:95], s91, v150
	v_cmp_lt_u32_e64 s[86:87], s91, v151
	v_cmp_lt_u32_e64 s[0:1], s91, v152
	v_cmp_lt_u32_e64 s[2:3], s91, v153
	v_cndmask_b32_e64 v24, v24, v230, s[94:95]
	v_cndmask_b32_e64 v25, v25, v230, s[86:87]
	v_cndmask_b32_e64 v26, v26, v230, s[0:1]
	v_cndmask_b32_e64 v27, v27, v230, s[2:3]
	v_sub_u32_e32 v150, 0x70, v200
	v_sub_u32_e32 v151, 0x71, v200
	v_sub_u32_e32 v152, 0x72, v200
	v_sub_u32_e32 v153, 0x73, v200
	v_cmp_lt_u32_e64 s[94:95], s91, v150
	v_cmp_lt_u32_e64 s[86:87], s91, v151
	v_cmp_lt_u32_e64 s[0:1], s91, v152
	v_cmp_lt_u32_e64 s[2:3], s91, v153
	v_cndmask_b32_e64 v28, v28, v230, s[94:95]
	v_cndmask_b32_e64 v29, v29, v230, s[86:87]
	v_cndmask_b32_e64 v30, v30, v230, s[0:1]
	v_cndmask_b32_e64 v31, v31, v230, s[2:3]
	v_sub_u32_e32 v150, 0x80, v200
	v_sub_u32_e32 v151, 0x81, v200
	v_sub_u32_e32 v152, 0x82, v200
	v_sub_u32_e32 v153, 0x83, v200
	v_cmp_lt_u32_e64 s[94:95], s91, v150
	v_cmp_lt_u32_e64 s[86:87], s91, v151
	v_cmp_lt_u32_e64 s[0:1], s91, v152
	v_cmp_lt_u32_e64 s[2:3], s91, v153
	v_cndmask_b32_e64 v32, v32, v230, s[94:95]
	v_cndmask_b32_e64 v33, v33, v230, s[86:87]
	v_cndmask_b32_e64 v34, v34, v230, s[0:1]
	v_cndmask_b32_e64 v35, v35, v230, s[2:3]
.Latt_noedge_1:
	s_nop 1
	v_max3_f32 v184, v0, v1, v2
	v_max3_f32 v184, v184, v3, v4
	v_max3_f32 v184, v184, v5, v6
	v_max3_f32 v184, v184, v7, v8
	v_max3_f32 v184, v184, v9, v10
	v_max3_f32 v184, v184, v11, v12
	v_max3_f32 v184, v184, v13, v14
	v_max3_f32 v184, v184, v15, v16
	v_max3_f32 v184, v184, v17, v18
	v_max3_f32 v184, v184, v19, v20
	v_max3_f32 v184, v184, v21, v22
	v_max3_f32 v184, v184, v23, v24
	v_max3_f32 v184, v184, v25, v26
	v_max3_f32 v184, v184, v27, v28
	v_max3_f32 v184, v184, v29, v30
	v_max3_f32 v184, v184, v31, v32
	v_max3_f32 v184, v184, v33, v34
	v_max_f32_e32 v184, v184, v35
	v_mov_b32_e32 v146, v184
	s_nop 1
	v_permlane16_swap_b32_e32 v184, v146
	v_max_f32_e32 v184, v184, v146
	v_mov_b32_e32 v146, v184
	s_nop 1
	v_permlane32_swap_b32_e32 v184, v146
	v_max_f32_e32 v184, v184, v146
	v_sub_f32_e32 v0, v0, v184
	v_sub_f32_e32 v1, v1, v184
	v_sub_f32_e32 v2, v2, v184
	v_sub_f32_e32 v3, v3, v184
	v_exp_f32_e32 v0, v0
	v_exp_f32_e32 v1, v1
	v_exp_f32_e32 v2, v2
	v_exp_f32_e32 v3, v3
	v_sub_f32_e32 v4, v4, v184
	v_sub_f32_e32 v5, v5, v184
	v_sub_f32_e32 v6, v6, v184
	v_sub_f32_e32 v7, v7, v184
	v_exp_f32_e32 v4, v4
	v_exp_f32_e32 v5, v5
	v_exp_f32_e32 v6, v6
	v_exp_f32_e32 v7, v7
	v_sub_f32_e32 v8, v8, v184
	v_sub_f32_e32 v9, v9, v184
	v_sub_f32_e32 v10, v10, v184
	v_sub_f32_e32 v11, v11, v184
	v_exp_f32_e32 v8, v8
	v_exp_f32_e32 v9, v9
	v_exp_f32_e32 v10, v10
	v_exp_f32_e32 v11, v11
	v_sub_f32_e32 v12, v12, v184
	v_sub_f32_e32 v13, v13, v184
	v_sub_f32_e32 v14, v14, v184
	v_sub_f32_e32 v15, v15, v184
	v_exp_f32_e32 v12, v12
	v_exp_f32_e32 v13, v13
	v_exp_f32_e32 v14, v14
	v_exp_f32_e32 v15, v15
	v_sub_f32_e32 v16, v16, v184
	v_sub_f32_e32 v17, v17, v184
	v_sub_f32_e32 v18, v18, v184
	v_sub_f32_e32 v19, v19, v184
	v_exp_f32_e32 v16, v16
	v_exp_f32_e32 v17, v17
	v_exp_f32_e32 v18, v18
	v_exp_f32_e32 v19, v19
	v_sub_f32_e32 v20, v20, v184
	v_sub_f32_e32 v21, v21, v184
	v_sub_f32_e32 v22, v22, v184
	v_sub_f32_e32 v23, v23, v184
	v_exp_f32_e32 v20, v20
	v_exp_f32_e32 v21, v21
	v_exp_f32_e32 v22, v22
	v_exp_f32_e32 v23, v23
	v_sub_f32_e32 v24, v24, v184
	v_sub_f32_e32 v25, v25, v184
	v_sub_f32_e32 v26, v26, v184
	v_sub_f32_e32 v27, v27, v184
	v_exp_f32_e32 v24, v24
	v_exp_f32_e32 v25, v25
	v_exp_f32_e32 v26, v26
	v_exp_f32_e32 v27, v27
	v_sub_f32_e32 v28, v28, v184
	v_sub_f32_e32 v29, v29, v184
	v_sub_f32_e32 v30, v30, v184
	v_sub_f32_e32 v31, v31, v184
	v_exp_f32_e32 v28, v28
	v_exp_f32_e32 v29, v29
	v_exp_f32_e32 v30, v30
	v_exp_f32_e32 v31, v31
	v_sub_f32_e32 v32, v32, v184
	v_sub_f32_e32 v33, v33, v184
	v_sub_f32_e32 v34, v34, v184
	v_sub_f32_e32 v35, v35, v184
	v_exp_f32_e32 v32, v32
	v_exp_f32_e32 v33, v33
	v_exp_f32_e32 v34, v34
	v_exp_f32_e32 v35, v35
	s_nop 0
	v_add_f32_e32 v185, v0, v1
	v_add_f32_e32 v185, v185, v2
	v_add_f32_e32 v185, v185, v3
	v_add_f32_e32 v185, v185, v4
	v_add_f32_e32 v185, v185, v5
	v_add_f32_e32 v185, v185, v6
	v_add_f32_e32 v185, v185, v7
	v_add_f32_e32 v185, v185, v8
	v_add_f32_e32 v185, v185, v9
	v_add_f32_e32 v185, v185, v10
	v_add_f32_e32 v185, v185, v11
	v_add_f32_e32 v185, v185, v12
	v_add_f32_e32 v185, v185, v13
	v_add_f32_e32 v185, v185, v14
	v_add_f32_e32 v185, v185, v15
	v_add_f32_e32 v185, v185, v16
	v_add_f32_e32 v185, v185, v17
	v_add_f32_e32 v185, v185, v18
	v_add_f32_e32 v185, v185, v19
	v_add_f32_e32 v185, v185, v20
	v_add_f32_e32 v185, v185, v21
	v_add_f32_e32 v185, v185, v22
	v_add_f32_e32 v185, v185, v23
	v_add_f32_e32 v185, v185, v24
	v_add_f32_e32 v185, v185, v25
	v_add_f32_e32 v185, v185, v26
	v_add_f32_e32 v185, v185, v27
	v_add_f32_e32 v185, v185, v28
	v_add_f32_e32 v185, v185, v29
	v_add_f32_e32 v185, v185, v30
	v_add_f32_e32 v185, v185, v31
	v_add_f32_e32 v185, v185, v32
	v_add_f32_e32 v185, v185, v33
	v_add_f32_e32 v185, v185, v34
	v_add_f32_e32 v185, v185, v35
	v_cvt_pk_bf16_f32 v0, v0, v1
	v_cvt_pk_bf16_f32 v1, v2, v3
	v_cvt_pk_bf16_f32 v4, v4, v5
	v_cvt_pk_bf16_f32 v5, v6, v7
	v_cvt_pk_bf16_f32 v8, v8, v9
	v_cvt_pk_bf16_f32 v9, v10, v11
	v_cvt_pk_bf16_f32 v12, v12, v13
	v_cvt_pk_bf16_f32 v13, v14, v15
	v_cvt_pk_bf16_f32 v16, v16, v17
	v_cvt_pk_bf16_f32 v17, v18, v19
	v_cvt_pk_bf16_f32 v20, v20, v21
	v_cvt_pk_bf16_f32 v21, v22, v23
	v_cvt_pk_bf16_f32 v24, v24, v25
	v_cvt_pk_bf16_f32 v25, v26, v27
	v_cvt_pk_bf16_f32 v28, v28, v29
	v_cvt_pk_bf16_f32 v29, v30, v31
	v_cvt_pk_bf16_f32 v32, v32, v33
	v_cvt_pk_bf16_f32 v33, v34, v35
	v_mov_b32_e32 v146, v185
	s_nop 1
	v_permlane16_swap_b32_e32 v185, v146
	v_add_f32_e32 v185, v185, v146
	v_mov_b32_e32 v146, v185
	s_nop 1
	v_permlane32_swap_b32_e32 v185, v146
	v_add_f32_e32 v185, v185, v146
	v_cndmask_b32_e64 v36, v36, v230, s[52:53]
	v_cndmask_b32_e64 v68, v68, v230, s[62:63]
	v_cndmask_b32_e64 v37, v37, v230, s[56:57]
	v_cndmask_b32_e64 v69, v69, v230, s[64:65]
	v_cndmask_b32_e64 v38, v38, v230, s[58:59]
	v_cndmask_b32_e64 v70, v70, v230, s[70:71]
	v_cndmask_b32_e64 v39, v39, v230, s[60:61]
	v_cndmask_b32_e64 v71, v71, v230, s[72:73]
	s_cmp_eq_u32 s96, 0
	s_cbranch_scc1 .Latt_noedge_2
	v_sub_u32_e32 v200, s77, v229
	v_add_u32_e32 v200, -16, v200
	s_sub_i32 s91, s78, s77
	v_sub_u32_e32 v150, 0, v200
	v_sub_u32_e32 v151, 1, v200
	v_sub_u32_e32 v152, 2, v200
	v_sub_u32_e32 v153, 3, v200
	v_cmp_lt_u32_e64 s[94:95], s91, v150
	v_cmp_lt_u32_e64 s[86:87], s91, v151
	v_cmp_lt_u32_e64 s[0:1], s91, v152
	v_cmp_lt_u32_e64 s[2:3], s91, v153
	v_cndmask_b32_e64 v36, v36, v230, s[94:95]
	v_cndmask_b32_e64 v37, v37, v230, s[86:87]
	v_cndmask_b32_e64 v38, v38, v230, s[0:1]
	v_cndmask_b32_e64 v39, v39, v230, s[2:3]
	v_sub_u32_e32 v150, 16, v200
	v_sub_u32_e32 v151, 17, v200
	v_sub_u32_e32 v152, 18, v200
	v_sub_u32_e32 v153, 19, v200
	v_cmp_lt_u32_e64 s[94:95], s91, v150
	v_cmp_lt_u32_e64 s[86:87], s91, v151
	v_cmp_lt_u32_e64 s[0:1], s91, v152
	v_cmp_lt_u32_e64 s[2:3], s91, v153
	v_cndmask_b32_e64 v40, v40, v230, s[94:95]
	v_cndmask_b32_e64 v41, v41, v230, s[86:87]
	v_cndmask_b32_e64 v42, v42, v230, s[0:1]
	v_cndmask_b32_e64 v43, v43, v230, s[2:3]
	v_sub_u32_e32 v150, 32, v200
	v_sub_u32_e32 v151, 33, v200
	v_sub_u32_e32 v152, 34, v200
	v_sub_u32_e32 v153, 35, v200
	v_cmp_lt_u32_e64 s[94:95], s91, v150
	v_cmp_lt_u32_e64 s[86:87], s91, v151
	v_cmp_lt_u32_e64 s[0:1], s91, v152
	v_cmp_lt_u32_e64 s[2:3], s91, v153
	v_cndmask_b32_e64 v44, v44, v230, s[94:95]
	v_cndmask_b32_e64 v45, v45, v230, s[86:87]
	v_cndmask_b32_e64 v46, v46, v230, s[0:1]
	v_cndmask_b32_e64 v47, v47, v230, s[2:3]
	v_sub_u32_e32 v150, 48, v200
	v_sub_u32_e32 v151, 49, v200
	v_sub_u32_e32 v152, 50, v200
	v_sub_u32_e32 v153, 51, v200
	v_cmp_lt_u32_e64 s[94:95], s91, v150
	v_cmp_lt_u32_e64 s[86:87], s91, v151
	v_cmp_lt_u32_e64 s[0:1], s91, v152
	v_cmp_lt_u32_e64 s[2:3], s91, v153
	v_cndmask_b32_e64 v48, v48, v230, s[94:95]
	v_cndmask_b32_e64 v49, v49, v230, s[86:87]
	v_cndmask_b32_e64 v50, v50, v230, s[0:1]
	v_cndmask_b32_e64 v51, v51, v230, s[2:3]
	v_sub_u32_e32 v150, 64, v200
	v_sub_u32_e32 v151, 0x41, v200
	v_sub_u32_e32 v152, 0x42, v200
	v_sub_u32_e32 v153, 0x43, v200
	v_cmp_lt_u32_e64 s[94:95], s91, v150
	v_cmp_lt_u32_e64 s[86:87], s91, v151
	v_cmp_lt_u32_e64 s[0:1], s91, v152
	v_cmp_lt_u32_e64 s[2:3], s91, v153
	v_cndmask_b32_e64 v52, v52, v230, s[94:95]
	v_cndmask_b32_e64 v53, v53, v230, s[86:87]
	v_cndmask_b32_e64 v54, v54, v230, s[0:1]
	v_cndmask_b32_e64 v55, v55, v230, s[2:3]
	v_sub_u32_e32 v150, 0x50, v200
	v_sub_u32_e32 v151, 0x51, v200
	v_sub_u32_e32 v152, 0x52, v200
	v_sub_u32_e32 v153, 0x53, v200
	v_cmp_lt_u32_e64 s[94:95], s91, v150
	v_cmp_lt_u32_e64 s[86:87], s91, v151
	v_cmp_lt_u32_e64 s[0:1], s91, v152
	v_cmp_lt_u32_e64 s[2:3], s91, v153
	v_cndmask_b32_e64 v56, v56, v230, s[94:95]
	v_cndmask_b32_e64 v57, v57, v230, s[86:87]
	v_cndmask_b32_e64 v58, v58, v230, s[0:1]
	v_cndmask_b32_e64 v59, v59, v230, s[2:3]
	v_sub_u32_e32 v150, 0x60, v200
	v_sub_u32_e32 v151, 0x61, v200
	v_sub_u32_e32 v152, 0x62, v200
	v_sub_u32_e32 v153, 0x63, v200
	v_cmp_lt_u32_e64 s[94:95], s91, v150
	v_cmp_lt_u32_e64 s[86:87], s91, v151
	v_cmp_lt_u32_e64 s[0:1], s91, v152
	v_cmp_lt_u32_e64 s[2:3], s91, v153
	v_cndmask_b32_e64 v60, v60, v230, s[94:95]
	v_cndmask_b32_e64 v61, v61, v230, s[86:87]
	v_cndmask_b32_e64 v62, v62, v230, s[0:1]
	v_cndmask_b32_e64 v63, v63, v230, s[2:3]
	v_sub_u32_e32 v150, 0x70, v200
	v_sub_u32_e32 v151, 0x71, v200
	v_sub_u32_e32 v152, 0x72, v200
	v_sub_u32_e32 v153, 0x73, v200
	v_cmp_lt_u32_e64 s[94:95], s91, v150
	v_cmp_lt_u32_e64 s[86:87], s91, v151
	v_cmp_lt_u32_e64 s[0:1], s91, v152
	v_cmp_lt_u32_e64 s[2:3], s91, v153
	v_cndmask_b32_e64 v64, v64, v230, s[94:95]
	v_cndmask_b32_e64 v65, v65, v230, s[86:87]
	v_cndmask_b32_e64 v66, v66, v230, s[0:1]
	v_cndmask_b32_e64 v67, v67, v230, s[2:3]
	v_sub_u32_e32 v150, 0x80, v200
	v_sub_u32_e32 v151, 0x81, v200
	v_sub_u32_e32 v152, 0x82, v200
	v_sub_u32_e32 v153, 0x83, v200
	v_cmp_lt_u32_e64 s[94:95], s91, v150
	v_cmp_lt_u32_e64 s[86:87], s91, v151
	v_cmp_lt_u32_e64 s[0:1], s91, v152
	v_cmp_lt_u32_e64 s[2:3], s91, v153
	v_cndmask_b32_e64 v68, v68, v230, s[94:95]
	v_cndmask_b32_e64 v69, v69, v230, s[86:87]
	v_cndmask_b32_e64 v70, v70, v230, s[0:1]
	v_cndmask_b32_e64 v71, v71, v230, s[2:3]
.Latt_noedge_2:
	s_nop 1
	v_max3_f32 v186, v36, v37, v38
	v_max3_f32 v186, v186, v39, v40
	v_max3_f32 v186, v186, v41, v42
	v_max3_f32 v186, v186, v43, v44
	v_max3_f32 v186, v186, v45, v46
	v_max3_f32 v186, v186, v47, v48
	v_max3_f32 v186, v186, v49, v50
	v_max3_f32 v186, v186, v51, v52
	v_max3_f32 v186, v186, v53, v54
	v_max3_f32 v186, v186, v55, v56
	v_max3_f32 v186, v186, v57, v58
	v_max3_f32 v186, v186, v59, v60
	v_max3_f32 v186, v186, v61, v62
	v_max3_f32 v186, v186, v63, v64
	v_max3_f32 v186, v186, v65, v66
	v_max3_f32 v186, v186, v67, v68
	v_max3_f32 v186, v186, v69, v70
	v_max_f32_e32 v186, v186, v71
	v_mov_b32_e32 v146, v186
	s_nop 1
	v_permlane16_swap_b32_e32 v186, v146
	v_max_f32_e32 v186, v186, v146
	v_mov_b32_e32 v146, v186
	s_nop 1
	v_permlane32_swap_b32_e32 v186, v146
	v_max_f32_e32 v186, v186, v146
	v_sub_f32_e32 v36, v36, v186
	v_sub_f32_e32 v37, v37, v186
	v_sub_f32_e32 v38, v38, v186
	v_sub_f32_e32 v39, v39, v186
	v_exp_f32_e32 v36, v36
	v_exp_f32_e32 v37, v37
	v_exp_f32_e32 v38, v38
	v_exp_f32_e32 v39, v39
	v_sub_f32_e32 v40, v40, v186
	v_sub_f32_e32 v41, v41, v186
	v_sub_f32_e32 v42, v42, v186
	v_sub_f32_e32 v43, v43, v186
	v_exp_f32_e32 v40, v40
	v_exp_f32_e32 v41, v41
	v_exp_f32_e32 v42, v42
	v_exp_f32_e32 v43, v43
	v_sub_f32_e32 v44, v44, v186
	v_sub_f32_e32 v45, v45, v186
	v_sub_f32_e32 v46, v46, v186
	v_sub_f32_e32 v47, v47, v186
	v_exp_f32_e32 v44, v44
	v_exp_f32_e32 v45, v45
	v_exp_f32_e32 v46, v46
	v_exp_f32_e32 v47, v47
	v_sub_f32_e32 v48, v48, v186
	v_sub_f32_e32 v49, v49, v186
	v_sub_f32_e32 v50, v50, v186
	v_sub_f32_e32 v51, v51, v186
	v_exp_f32_e32 v48, v48
	v_exp_f32_e32 v49, v49
	v_exp_f32_e32 v50, v50
	v_exp_f32_e32 v51, v51
	v_sub_f32_e32 v52, v52, v186
	v_sub_f32_e32 v53, v53, v186
	v_sub_f32_e32 v54, v54, v186
	v_sub_f32_e32 v55, v55, v186
	v_exp_f32_e32 v52, v52
	v_exp_f32_e32 v53, v53
	v_exp_f32_e32 v54, v54
	v_exp_f32_e32 v55, v55
	v_sub_f32_e32 v56, v56, v186
	v_sub_f32_e32 v57, v57, v186
	v_sub_f32_e32 v58, v58, v186
	v_sub_f32_e32 v59, v59, v186
	v_exp_f32_e32 v56, v56
	v_exp_f32_e32 v57, v57
	v_exp_f32_e32 v58, v58
	v_exp_f32_e32 v59, v59
	v_sub_f32_e32 v60, v60, v186
	v_sub_f32_e32 v61, v61, v186
	v_sub_f32_e32 v62, v62, v186
	v_sub_f32_e32 v63, v63, v186
	v_exp_f32_e32 v60, v60
	v_exp_f32_e32 v61, v61
	v_exp_f32_e32 v62, v62
	v_exp_f32_e32 v63, v63
	v_sub_f32_e32 v64, v64, v186
	v_sub_f32_e32 v65, v65, v186
	v_sub_f32_e32 v66, v66, v186
	v_sub_f32_e32 v67, v67, v186
	v_exp_f32_e32 v64, v64
	v_exp_f32_e32 v65, v65
	v_exp_f32_e32 v66, v66
	v_exp_f32_e32 v67, v67
	v_sub_f32_e32 v68, v68, v186
	v_sub_f32_e32 v69, v69, v186
	v_sub_f32_e32 v70, v70, v186
	v_sub_f32_e32 v71, v71, v186
	v_exp_f32_e32 v68, v68
	v_exp_f32_e32 v69, v69
	v_exp_f32_e32 v70, v70
	v_exp_f32_e32 v71, v71
	s_nop 0
	v_add_f32_e32 v187, v36, v37
	v_add_f32_e32 v187, v187, v38
	v_add_f32_e32 v187, v187, v39
	v_add_f32_e32 v187, v187, v40
	v_add_f32_e32 v187, v187, v41
	v_add_f32_e32 v187, v187, v42
	v_add_f32_e32 v187, v187, v43
	v_add_f32_e32 v187, v187, v44
	v_add_f32_e32 v187, v187, v45
	v_add_f32_e32 v187, v187, v46
	v_add_f32_e32 v187, v187, v47
	v_add_f32_e32 v187, v187, v48
	v_add_f32_e32 v187, v187, v49
	v_add_f32_e32 v187, v187, v50
	v_add_f32_e32 v187, v187, v51
	v_add_f32_e32 v187, v187, v52
	v_add_f32_e32 v187, v187, v53
	v_add_f32_e32 v187, v187, v54
	v_add_f32_e32 v187, v187, v55
	v_add_f32_e32 v187, v187, v56
	v_add_f32_e32 v187, v187, v57
	v_add_f32_e32 v187, v187, v58
	v_add_f32_e32 v187, v187, v59
	v_add_f32_e32 v187, v187, v60
	v_add_f32_e32 v187, v187, v61
	v_add_f32_e32 v187, v187, v62
	v_add_f32_e32 v187, v187, v63
	v_add_f32_e32 v187, v187, v64
	v_add_f32_e32 v187, v187, v65
	v_add_f32_e32 v187, v187, v66
	v_add_f32_e32 v187, v187, v67
	v_add_f32_e32 v187, v187, v68
	v_add_f32_e32 v187, v187, v69
	v_add_f32_e32 v187, v187, v70
	v_add_f32_e32 v187, v187, v71
	v_cvt_pk_bf16_f32 v36, v36, v37
	v_cvt_pk_bf16_f32 v37, v38, v39
	v_cvt_pk_bf16_f32 v40, v40, v41
	v_cvt_pk_bf16_f32 v41, v42, v43
	v_cvt_pk_bf16_f32 v44, v44, v45
	v_cvt_pk_bf16_f32 v45, v46, v47
	v_cvt_pk_bf16_f32 v48, v48, v49
	v_cvt_pk_bf16_f32 v49, v50, v51
	v_cvt_pk_bf16_f32 v52, v52, v53
	v_cvt_pk_bf16_f32 v53, v54, v55
	v_cvt_pk_bf16_f32 v56, v56, v57
	v_cvt_pk_bf16_f32 v57, v58, v59
	v_cvt_pk_bf16_f32 v60, v60, v61
	v_cvt_pk_bf16_f32 v61, v62, v63
	v_cvt_pk_bf16_f32 v64, v64, v65
	v_cvt_pk_bf16_f32 v65, v66, v67
	v_cvt_pk_bf16_f32 v68, v68, v69
	v_cvt_pk_bf16_f32 v69, v70, v71
	v_mov_b32_e32 v146, v187
	s_nop 1
	v_permlane16_swap_b32_e32 v187, v146
	v_add_f32_e32 v187, v187, v146
	v_mov_b32_e32 v146, v187
	s_nop 1
	v_permlane32_swap_b32_e32 v187, v146
	v_add_f32_e32 v187, v187, v146
	s_waitcnt lgkmcnt(0)
	s_add_i32 s93, s76, 0
	s_mov_b32 m0, s13
	v_add_u32_e32 v164, s93, v231
	v_max_i32_e32 v164, 0, v164
	v_min_u32_e32 v164, s40, v164
	v_lshl_or_b32 v164, v164, 7, v222
	global_load_lds_dwordx4 v164, s[24:25]
	s_add_i32 m0, s13, 0x400
	v_add_u32_e32 v165, s93, v232
	v_max_i32_e32 v165, 0, v165
	v_min_u32_e32 v165, s40, v165
	v_lshl_or_b32 v165, v165, 7, v222
	global_load_lds_dwordx4 v165, s[24:25]
	s_waitcnt vmcnt(8)
	v_add_u32_e32 v146, s14, v225
	v_add_u32_e32 v147, s14, v226
	v_add_u32_e32 v148, s14, v227
	v_add_u32_e32 v149, s14, v228
	ds_read_b64_tr_b16 v[88:89], v146
	ds_read_b64_tr_b16 v[90:91], v147
	ds_read_b64_tr_b16 v[92:93], v148
	ds_read_b64_tr_b16 v[94:95], v149
	s_waitcnt lgkmcnt(0)
	v_mfma_f32_16x16x16_bf16 v[96:99], v[88:89], v[0:1], 0
	v_mfma_f32_16x16x16_bf16 v[100:103], v[90:91], v[0:1], 0
	v_mfma_f32_16x16x16_bf16 v[104:107], v[92:93], v[0:1], 0
	v_mfma_f32_16x16x16_bf16 v[108:111], v[94:95], v[0:1], 0
	s_waitcnt lgkmcnt(0)
	s_add_i32 s93, s76, 16
	s_mov_b32 m0, s14
	v_add_u32_e32 v164, s93, v231
	v_max_i32_e32 v164, 0, v164
	v_min_u32_e32 v164, s40, v164
	v_lshl_or_b32 v164, v164, 7, v222
	global_load_lds_dwordx4 v164, s[24:25]
	s_add_i32 m0, s14, 0x400
	v_add_u32_e32 v165, s93, v232
	v_max_i32_e32 v165, 0, v165
	v_min_u32_e32 v165, s40, v165
	v_lshl_or_b32 v165, v165, 7, v222
	global_load_lds_dwordx4 v165, s[24:25]
	s_waitcnt vmcnt(8)
	v_add_u32_e32 v146, s15, v225
	v_add_u32_e32 v147, s15, v226
	v_add_u32_e32 v148, s15, v227
	v_add_u32_e32 v149, s15, v228
	ds_read_b64_tr_b16 v[88:89], v146
	ds_read_b64_tr_b16 v[90:91], v147
	ds_read_b64_tr_b16 v[92:93], v148
	ds_read_b64_tr_b16 v[94:95], v149
	s_waitcnt lgkmcnt(0)
	v_mfma_f32_16x16x16_bf16 v[96:99], v[88:89], v[4:5], v[96:99]
	v_mfma_f32_16x16x16_bf16 v[112:115], v[88:89], v[36:37], 0
	v_mfma_f32_16x16x16_bf16 v[100:103], v[90:91], v[4:5], v[100:103]
	v_mfma_f32_16x16x16_bf16 v[116:119], v[90:91], v[36:37], 0
	v_mfma_f32_16x16x16_bf16 v[104:107], v[92:93], v[4:5], v[104:107]
	v_mfma_f32_16x16x16_bf16 v[120:123], v[92:93], v[36:37], 0
	v_mfma_f32_16x16x16_bf16 v[108:111], v[94:95], v[4:5], v[108:111]
	v_mfma_f32_16x16x16_bf16 v[124:127], v[94:95], v[36:37], 0
	s_waitcnt lgkmcnt(0)
	s_add_i32 s93, s76, 32
	s_mov_b32 m0, s15
	v_add_u32_e32 v164, s93, v231
	v_max_i32_e32 v164, 0, v164
	v_min_u32_e32 v164, s40, v164
	v_lshl_or_b32 v164, v164, 7, v222
	global_load_lds_dwordx4 v164, s[24:25]
	s_add_i32 m0, s15, 0x400
	v_add_u32_e32 v165, s93, v232
	v_max_i32_e32 v165, 0, v165
	v_min_u32_e32 v165, s40, v165
	v_lshl_or_b32 v165, v165, 7, v222
	global_load_lds_dwordx4 v165, s[24:25]
	s_waitcnt vmcnt(8)
	v_add_u32_e32 v146, s16, v225
	v_add_u32_e32 v147, s16, v226
	v_add_u32_e32 v148, s16, v227
	v_add_u32_e32 v149, s16, v228
	ds_read_b64_tr_b16 v[88:89], v146
	ds_read_b64_tr_b16 v[90:91], v147
	ds_read_b64_tr_b16 v[92:93], v148
	ds_read_b64_tr_b16 v[94:95], v149
	s_waitcnt lgkmcnt(0)
	v_mfma_f32_16x16x16_bf16 v[96:99], v[88:89], v[8:9], v[96:99]
	v_mfma_f32_16x16x16_bf16 v[112:115], v[88:89], v[40:41], v[112:115]
	v_mfma_f32_16x16x16_bf16 v[100:103], v[90:91], v[8:9], v[100:103]
	v_mfma_f32_16x16x16_bf16 v[116:119], v[90:91], v[40:41], v[116:119]
	v_mfma_f32_16x16x16_bf16 v[104:107], v[92:93], v[8:9], v[104:107]
	v_mfma_f32_16x16x16_bf16 v[120:123], v[92:93], v[40:41], v[120:123]
	v_mfma_f32_16x16x16_bf16 v[108:111], v[94:95], v[8:9], v[108:111]
	v_mfma_f32_16x16x16_bf16 v[124:127], v[94:95], v[40:41], v[124:127]
	s_waitcnt lgkmcnt(0)
	s_add_i32 s93, s76, 48
	s_mov_b32 m0, s16
	v_add_u32_e32 v164, s93, v231
	v_max_i32_e32 v164, 0, v164
	v_min_u32_e32 v164, s40, v164
	v_lshl_or_b32 v164, v164, 7, v222
	global_load_lds_dwordx4 v164, s[24:25]
	s_add_i32 m0, s16, 0x400
	v_add_u32_e32 v165, s93, v232
	v_max_i32_e32 v165, 0, v165
	v_min_u32_e32 v165, s40, v165
	v_lshl_or_b32 v165, v165, 7, v222
	global_load_lds_dwordx4 v165, s[24:25]
	s_waitcnt vmcnt(8)
	v_add_u32_e32 v146, s12, v225
	v_add_u32_e32 v147, s12, v226
	v_add_u32_e32 v148, s12, v227
	v_add_u32_e32 v149, s12, v228
	ds_read_b64_tr_b16 v[88:89], v146
	ds_read_b64_tr_b16 v[90:91], v147
	ds_read_b64_tr_b16 v[92:93], v148
	ds_read_b64_tr_b16 v[94:95], v149
	s_waitcnt lgkmcnt(0)
	v_mfma_f32_16x16x16_bf16 v[96:99], v[88:89], v[12:13], v[96:99]
	v_mfma_f32_16x16x16_bf16 v[112:115], v[88:89], v[44:45], v[112:115]
	v_mfma_f32_16x16x16_bf16 v[100:103], v[90:91], v[12:13], v[100:103]
	v_mfma_f32_16x16x16_bf16 v[116:119], v[90:91], v[44:45], v[116:119]
	v_mfma_f32_16x16x16_bf16 v[104:107], v[92:93], v[12:13], v[104:107]
	v_mfma_f32_16x16x16_bf16 v[120:123], v[92:93], v[44:45], v[120:123]
	v_mfma_f32_16x16x16_bf16 v[108:111], v[94:95], v[12:13], v[108:111]
	v_mfma_f32_16x16x16_bf16 v[124:127], v[94:95], v[44:45], v[124:127]
	s_waitcnt lgkmcnt(0)
	s_add_i32 s93, s76, 64
	s_mov_b32 m0, s12
	v_add_u32_e32 v164, s93, v231
	v_max_i32_e32 v164, 0, v164
	v_min_u32_e32 v164, s40, v164
	v_lshl_or_b32 v164, v164, 7, v222
	global_load_lds_dwordx4 v164, s[24:25]
	s_add_i32 m0, s12, 0x400
	v_add_u32_e32 v165, s93, v232
	v_max_i32_e32 v165, 0, v165
	v_min_u32_e32 v165, s40, v165
	v_lshl_or_b32 v165, v165, 7, v222
	global_load_lds_dwordx4 v165, s[24:25]
	s_waitcnt vmcnt(8)
	v_add_u32_e32 v146, s13, v225
	v_add_u32_e32 v147, s13, v226
	v_add_u32_e32 v148, s13, v227
	v_add_u32_e32 v149, s13, v228
	ds_read_b64_tr_b16 v[88:89], v146
	ds_read_b64_tr_b16 v[90:91], v147
	ds_read_b64_tr_b16 v[92:93], v148
	ds_read_b64_tr_b16 v[94:95], v149
	s_waitcnt lgkmcnt(0)
	v_mfma_f32_16x16x16_bf16 v[96:99], v[88:89], v[16:17], v[96:99]
	v_mfma_f32_16x16x16_bf16 v[112:115], v[88:89], v[48:49], v[112:115]
	v_mfma_f32_16x16x16_bf16 v[100:103], v[90:91], v[16:17], v[100:103]
	v_mfma_f32_16x16x16_bf16 v[116:119], v[90:91], v[48:49], v[116:119]
	v_mfma_f32_16x16x16_bf16 v[104:107], v[92:93], v[16:17], v[104:107]
	v_mfma_f32_16x16x16_bf16 v[120:123], v[92:93], v[48:49], v[120:123]
	v_mfma_f32_16x16x16_bf16 v[108:111], v[94:95], v[16:17], v[108:111]
	v_mfma_f32_16x16x16_bf16 v[124:127], v[94:95], v[48:49], v[124:127]
	s_waitcnt lgkmcnt(0)
	s_add_i32 s93, s76, 0x50
	s_mov_b32 m0, s13
	v_add_u32_e32 v164, s93, v231
	v_max_i32_e32 v164, 0, v164
	v_min_u32_e32 v164, s40, v164
	v_lshl_or_b32 v164, v164, 7, v222
	global_load_lds_dwordx4 v164, s[24:25]
	s_add_i32 m0, s13, 0x400
	v_add_u32_e32 v165, s93, v232
	v_max_i32_e32 v165, 0, v165
	v_min_u32_e32 v165, s40, v165
	v_lshl_or_b32 v165, v165, 7, v222
	global_load_lds_dwordx4 v165, s[24:25]
	s_waitcnt vmcnt(8)
	v_add_u32_e32 v146, s14, v225
	v_add_u32_e32 v147, s14, v226
	v_add_u32_e32 v148, s14, v227
	v_add_u32_e32 v149, s14, v228
	ds_read_b64_tr_b16 v[88:89], v146
	ds_read_b64_tr_b16 v[90:91], v147
	ds_read_b64_tr_b16 v[92:93], v148
	ds_read_b64_tr_b16 v[94:95], v149
	s_waitcnt lgkmcnt(0)
	v_mfma_f32_16x16x16_bf16 v[96:99], v[88:89], v[20:21], v[96:99]
	v_mfma_f32_16x16x16_bf16 v[112:115], v[88:89], v[52:53], v[112:115]
	v_mfma_f32_16x16x16_bf16 v[100:103], v[90:91], v[20:21], v[100:103]
	v_mfma_f32_16x16x16_bf16 v[116:119], v[90:91], v[52:53], v[116:119]
	v_mfma_f32_16x16x16_bf16 v[104:107], v[92:93], v[20:21], v[104:107]
	v_mfma_f32_16x16x16_bf16 v[120:123], v[92:93], v[52:53], v[120:123]
	v_mfma_f32_16x16x16_bf16 v[108:111], v[94:95], v[20:21], v[108:111]
	v_mfma_f32_16x16x16_bf16 v[124:127], v[94:95], v[52:53], v[124:127]
	s_waitcnt lgkmcnt(0)
	s_add_i32 s93, s79, 0
	s_mov_b32 m0, s14
	v_add_u32_e32 v164, s93, v162
	v_lshl_or_b32 v164, v164, 7, v220
	global_load_lds_dwordx4 v164, s[18:19]
	s_add_i32 m0, s14, 0x400
	v_add_u32_e32 v165, s93, v163
	v_lshl_or_b32 v165, v165, 7, v221
	global_load_lds_dwordx4 v165, s[18:19]
	s_waitcnt vmcnt(8)
	v_add_u32_e32 v146, s15, v225
	v_add_u32_e32 v147, s15, v226
	v_add_u32_e32 v148, s15, v227
	v_add_u32_e32 v149, s15, v228
	ds_read_b64_tr_b16 v[88:89], v146
	ds_read_b64_tr_b16 v[90:91], v147
	ds_read_b64_tr_b16 v[92:93], v148
	ds_read_b64_tr_b16 v[94:95], v149
	s_waitcnt lgkmcnt(0)
	v_mfma_f32_16x16x16_bf16 v[96:99], v[88:89], v[24:25], v[96:99]
	v_mfma_f32_16x16x16_bf16 v[112:115], v[88:89], v[56:57], v[112:115]
	v_mfma_f32_16x16x16_bf16 v[100:103], v[90:91], v[24:25], v[100:103]
	v_mfma_f32_16x16x16_bf16 v[116:119], v[90:91], v[56:57], v[116:119]
	v_mfma_f32_16x16x16_bf16 v[104:107], v[92:93], v[24:25], v[104:107]
	v_mfma_f32_16x16x16_bf16 v[120:123], v[92:93], v[56:57], v[120:123]
	v_mfma_f32_16x16x16_bf16 v[108:111], v[94:95], v[24:25], v[108:111]
	v_mfma_f32_16x16x16_bf16 v[124:127], v[94:95], v[56:57], v[124:127]
	s_waitcnt lgkmcnt(0)
	s_add_i32 s93, s79, 64
	s_mov_b32 m0, s15
	v_add_u32_e32 v164, s93, v162
	v_lshl_or_b32 v164, v164, 7, v220
	global_load_lds_dwordx4 v164, s[18:19]
	s_add_i32 m0, s15, 0x400
	v_add_u32_e32 v165, s93, v163
	v_lshl_or_b32 v165, v165, 7, v221
	global_load_lds_dwordx4 v165, s[18:19]
	s_waitcnt vmcnt(8)
	v_add_u32_e32 v146, s16, v225
	v_add_u32_e32 v147, s16, v226
	v_add_u32_e32 v148, s16, v227
	v_add_u32_e32 v149, s16, v228
	ds_read_b64_tr_b16 v[88:89], v146
	ds_read_b64_tr_b16 v[90:91], v147
	ds_read_b64_tr_b16 v[92:93], v148
	ds_read_b64_tr_b16 v[94:95], v149
	s_waitcnt lgkmcnt(0)
	v_mfma_f32_16x16x16_bf16 v[96:99], v[88:89], v[28:29], v[96:99]
	v_mfma_f32_16x16x16_bf16 v[112:115], v[88:89], v[60:61], v[112:115]
	v_mfma_f32_16x16x16_bf16 v[100:103], v[90:91], v[28:29], v[100:103]
	v_mfma_f32_16x16x16_bf16 v[116:119], v[90:91], v[60:61], v[116:119]
	v_mfma_f32_16x16x16_bf16 v[104:107], v[92:93], v[28:29], v[104:107]
	v_mfma_f32_16x16x16_bf16 v[120:123], v[92:93], v[60:61], v[120:123]
	v_mfma_f32_16x16x16_bf16 v[108:111], v[94:95], v[28:29], v[108:111]
	v_mfma_f32_16x16x16_bf16 v[124:127], v[94:95], v[60:61], v[124:127]
	s_waitcnt lgkmcnt(0)
	s_add_i32 s93, s79, 0xffffff00
	s_mov_b32 m0, s16
	v_add_u32_e32 v164, s93, v162
	v_max_i32_e32 v164, 0, v164
	v_min_u32_e32 v164, s40, v164
	v_lshl_or_b32 v164, v164, 7, v220
	global_load_lds_dwordx4 v164, s[20:21]
	s_add_i32 m0, s16, 0x400
	v_add_u32_e32 v165, s93, v163
	v_max_i32_e32 v165, 0, v165
	v_min_u32_e32 v165, s40, v165
	v_lshl_or_b32 v165, v165, 7, v221
	global_load_lds_dwordx4 v165, s[20:21]
	s_waitcnt vmcnt(8)
	v_add_u32_e32 v146, s12, v225
	v_add_u32_e32 v147, s12, v226
	v_add_u32_e32 v148, s12, v227
	v_add_u32_e32 v149, s12, v228
	ds_read_b64_tr_b16 v[88:89], v146
	ds_read_b64_tr_b16 v[90:91], v147
	ds_read_b64_tr_b16 v[92:93], v148
	ds_read_b64_tr_b16 v[94:95], v149
	s_waitcnt lgkmcnt(0)
	v_mfma_f32_16x16x16_bf16 v[96:99], v[88:89], v[32:33], v[96:99]
	v_mfma_f32_16x16x16_bf16 v[112:115], v[88:89], v[64:65], v[112:115]
	v_mfma_f32_16x16x16_bf16 v[100:103], v[90:91], v[32:33], v[100:103]
	v_mfma_f32_16x16x16_bf16 v[116:119], v[90:91], v[64:65], v[116:119]
	v_mfma_f32_16x16x16_bf16 v[104:107], v[92:93], v[32:33], v[104:107]
	v_mfma_f32_16x16x16_bf16 v[120:123], v[92:93], v[64:65], v[120:123]
	v_mfma_f32_16x16x16_bf16 v[108:111], v[94:95], v[32:33], v[108:111]
	v_mfma_f32_16x16x16_bf16 v[124:127], v[94:95], v[64:65], v[124:127]
	s_waitcnt lgkmcnt(0)
	s_add_i32 s93, s79, 0xffffff40
	s_mov_b32 m0, s12
	v_add_u32_e32 v164, s93, v162
	v_max_i32_e32 v164, 0, v164
	v_min_u32_e32 v164, s40, v164
	v_lshl_or_b32 v164, v164, 7, v220
	global_load_lds_dwordx4 v164, s[20:21]
	s_add_i32 m0, s12, 0x400
	v_add_u32_e32 v165, s93, v163
	v_max_i32_e32 v165, 0, v165
	v_min_u32_e32 v165, s40, v165
	v_lshl_or_b32 v165, v165, 7, v221
	global_load_lds_dwordx4 v165, s[20:21]
	s_waitcnt vmcnt(8)
	v_add_u32_e32 v146, s13, v225
	v_add_u32_e32 v147, s13, v226
	v_add_u32_e32 v148, s13, v227
	v_add_u32_e32 v149, s13, v228
	ds_read_b64_tr_b16 v[88:89], v146
	ds_read_b64_tr_b16 v[90:91], v147
	ds_read_b64_tr_b16 v[92:93], v148
	ds_read_b64_tr_b16 v[94:95], v149
	s_waitcnt lgkmcnt(0)
	v_mfma_f32_16x16x16_bf16 v[112:115], v[88:89], v[68:69], v[112:115]
	v_mfma_f32_16x16x16_bf16 v[116:119], v[90:91], v[68:69], v[116:119]
	v_mfma_f32_16x16x16_bf16 v[120:123], v[92:93], v[68:69], v[120:123]
	v_mfma_f32_16x16x16_bf16 v[124:127], v[94:95], v[68:69], v[124:127]
	s_and_saveexec_b64 s[80:81], s[74:75]
	ds_write_b64 v194, v[184:185]
	s_mov_b64 exec, s[80:81]
	ds_write_b128 v190, v[96:99]
	ds_write_b128 v191, v[100:103]
	ds_write_b128 v192, v[104:107]
	ds_write_b128 v193, v[108:111]
	s_and_saveexec_b64 s[80:81], s[74:75]
	ds_write_b64 v199, v[186:187]
	s_mov_b64 exec, s[80:81]
	ds_write_b128 v195, v[112:115]
	ds_write_b128 v196, v[116:119]
	ds_write_b128 v197, v[120:123]
	ds_write_b128 v198, v[124:127]
	s_waitcnt lgkmcnt(0)
	s_barrier
	s_add_i32 s76, s38, s83
	s_add_i32 s79, s38, s84
	v_lshlrev_b32_e32 v231, 2, v218
	v_add_u32_e32 v232, 8, v218
	v_lshlrev_b32_e32 v232, 2, v232
	v_lshlrev_b32_e32 v162, 4, v218
	v_add_u32_e32 v163, 8, v218
	v_lshlrev_b32_e32 v163, 4, v163
	s_waitcnt lgkmcnt(0)
	s_add_i32 s93, s76, 0xffffff80
	s_mov_b32 m0, s13
	v_add_u32_e32 v164, s93, v231
	v_max_i32_e32 v164, 0, v164
	v_min_u32_e32 v164, s40, v164
	v_lshl_or_b32 v164, v164, 7, v220
	global_load_lds_dwordx4 v164, s[20:21]
	s_add_i32 m0, s13, 0x400
	v_add_u32_e32 v165, s93, v232
	v_max_i32_e32 v165, 0, v165
	v_min_u32_e32 v165, s40, v165
	v_lshl_or_b32 v165, v165, 7, v221
	global_load_lds_dwordx4 v165, s[20:21]
	s_waitcnt vmcnt(8)
	v_add_u32_e32 v146, s14, v223
	v_add_u32_e32 v147, s14, v224
	ds_read_b128 v[72:75], v146
	ds_read_b128 v[76:79], v147
	s_waitcnt lgkmcnt(0)
	s_add_i32 s93, s76, 0xffffffc0
	s_mov_b32 m0, s14
	v_add_u32_e32 v164, s93, v231
	v_max_i32_e32 v164, 0, v164
	v_min_u32_e32 v164, s40, v164
	v_lshl_or_b32 v164, v164, 7, v220
	global_load_lds_dwordx4 v164, s[20:21]
	s_add_i32 m0, s14, 0x400
	v_add_u32_e32 v165, s93, v232
	v_max_i32_e32 v165, 0, v165
	v_min_u32_e32 v165, s40, v165
	v_lshl_or_b32 v165, v165, 7, v221
	global_load_lds_dwordx4 v165, s[20:21]
	s_waitcnt vmcnt(8)
	v_add_u32_e32 v146, s15, v223
	v_add_u32_e32 v147, s15, v224
	ds_read_b128 v[80:83], v146
	ds_read_b128 v[84:87], v147
	s_waitcnt lgkmcnt(0)
	s_add_i32 s93, s76, 0
	s_mov_b32 m0, s15
	v_add_u32_e32 v164, s93, v231
	v_max_i32_e32 v164, 0, v164
	v_min_u32_e32 v164, s40, v164
	v_lshl_or_b32 v164, v164, 7, v220
	global_load_lds_dwordx4 v164, s[20:21]
	s_add_i32 m0, s15, 0x400
	v_add_u32_e32 v165, s93, v232
	v_max_i32_e32 v165, 0, v165
	v_min_u32_e32 v165, s40, v165
	v_lshl_or_b32 v165, v165, 7, v221
	global_load_lds_dwordx4 v165, s[20:21]
	s_waitcnt vmcnt(8)
	v_add_u32_e32 v146, s16, v223
	v_add_u32_e32 v147, s16, v224
	ds_read_b128 v[88:91], v146
	ds_read_b128 v[92:95], v147
	s_waitcnt lgkmcnt(0)
	v_mfma_f32_16x16x32_bf16 v[0:3], v[88:91], v[72:75], 0
	v_mfma_f32_16x16x32_bf16 v[0:3], v[92:95], v[76:79], v[0:3]
	s_waitcnt lgkmcnt(0)
	s_add_i32 s93, s76, 64
	s_mov_b32 m0, s16
	v_add_u32_e32 v164, s93, v231
	v_max_i32_e32 v164, 0, v164
	v_min_u32_e32 v164, s40, v164
	v_lshl_or_b32 v164, v164, 7, v220
	global_load_lds_dwordx4 v164, s[20:21]
	s_add_i32 m0, s16, 0x400
	v_add_u32_e32 v165, s93, v232
	v_max_i32_e32 v165, 0, v165
	v_min_u32_e32 v165, s40, v165
	v_lshl_or_b32 v165, v165, 7, v221
	global_load_lds_dwordx4 v165, s[20:21]
	s_waitcnt vmcnt(8)
	v_add_u32_e32 v146, s12, v223
	v_add_u32_e32 v147, s12, v224
	ds_read_b128 v[88:91], v146
	ds_read_b128 v[92:95], v147
	s_waitcnt lgkmcnt(0)
	v_mfma_f32_16x16x32_bf16 v[4:7], v[88:91], v[72:75], 0
	v_mfma_f32_16x16x32_bf16 v[36:39], v[88:91], v[80:83], 0
	v_mfma_f32_16x16x32_bf16 v[4:7], v[92:95], v[76:79], v[4:7]
	v_mfma_f32_16x16x32_bf16 v[36:39], v[92:95], v[84:87], v[36:39]
	s_waitcnt lgkmcnt(0)
	s_add_i32 s93, s76, 0x80
	s_mov_b32 m0, s12
	v_add_u32_e32 v164, s93, v231
	v_max_i32_e32 v164, 0, v164
	v_min_u32_e32 v164, s40, v164
	v_lshl_or_b32 v164, v164, 7, v220
	global_load_lds_dwordx4 v164, s[20:21]
	s_add_i32 m0, s12, 0x400
	v_add_u32_e32 v165, s93, v232
	v_max_i32_e32 v165, 0, v165
	v_min_u32_e32 v165, s40, v165
	v_lshl_or_b32 v165, v165, 7, v221
	global_load_lds_dwordx4 v165, s[20:21]
	s_waitcnt vmcnt(8)
	v_add_u32_e32 v146, s13, v223
	v_add_u32_e32 v147, s13, v224
	ds_read_b128 v[88:91], v146
	ds_read_b128 v[92:95], v147
	s_waitcnt lgkmcnt(0)
	v_mfma_f32_16x16x32_bf16 v[8:11], v[88:91], v[72:75], 0
	v_mfma_f32_16x16x32_bf16 v[40:43], v[88:91], v[80:83], 0
	v_mfma_f32_16x16x32_bf16 v[8:11], v[92:95], v[76:79], v[8:11]
	v_mfma_f32_16x16x32_bf16 v[40:43], v[92:95], v[84:87], v[40:43]
	s_waitcnt lgkmcnt(0)
	s_add_i32 s93, s76, 0xc0
	s_mov_b32 m0, s13
	v_add_u32_e32 v164, s93, v231
	v_max_i32_e32 v164, 0, v164
	v_min_u32_e32 v164, s40, v164
	v_lshl_or_b32 v164, v164, 7, v220
	global_load_lds_dwordx4 v164, s[20:21]
	s_add_i32 m0, s13, 0x400
	v_add_u32_e32 v165, s93, v232
	v_max_i32_e32 v165, 0, v165
	v_min_u32_e32 v165, s40, v165
	v_lshl_or_b32 v165, v165, 7, v221
	global_load_lds_dwordx4 v165, s[20:21]
	s_waitcnt vmcnt(8)
	v_add_u32_e32 v146, s14, v223
	v_add_u32_e32 v147, s14, v224
	ds_read_b128 v[88:91], v146
	ds_read_b128 v[92:95], v147
	s_waitcnt lgkmcnt(0)
	v_mfma_f32_16x16x32_bf16 v[12:15], v[88:91], v[72:75], 0
	v_mfma_f32_16x16x32_bf16 v[44:47], v[88:91], v[80:83], 0
	v_mfma_f32_16x16x32_bf16 v[12:15], v[92:95], v[76:79], v[12:15]
	v_mfma_f32_16x16x32_bf16 v[44:47], v[92:95], v[84:87], v[44:47]
	s_waitcnt lgkmcnt(0)
	s_add_i32 s93, s76, 0x100
	s_mov_b32 m0, s14
	v_add_u32_e32 v164, s93, v231
	v_max_i32_e32 v164, 0, v164
	v_min_u32_e32 v164, s40, v164
	v_lshl_or_b32 v164, v164, 7, v220
	global_load_lds_dwordx4 v164, s[20:21]
	s_add_i32 m0, s14, 0x400
	v_add_u32_e32 v165, s93, v232
	v_max_i32_e32 v165, 0, v165
	v_min_u32_e32 v165, s40, v165
	v_lshl_or_b32 v165, v165, 7, v221
	global_load_lds_dwordx4 v165, s[20:21]
	s_waitcnt vmcnt(8)
	v_add_u32_e32 v146, s15, v223
	v_add_u32_e32 v147, s15, v224
	ds_read_b128 v[88:91], v146
	ds_read_b128 v[92:95], v147
	s_waitcnt lgkmcnt(0)
	v_mfma_f32_16x16x32_bf16 v[16:19], v[88:91], v[72:75], 0
	v_mfma_f32_16x16x32_bf16 v[48:51], v[88:91], v[80:83], 0
	v_mfma_f32_16x16x32_bf16 v[16:19], v[92:95], v[76:79], v[16:19]
	v_mfma_f32_16x16x32_bf16 v[48:51], v[92:95], v[84:87], v[48:51]
	s_waitcnt lgkmcnt(0)
	s_add_i32 s93, s76, 0x140
	s_mov_b32 m0, s15
	v_add_u32_e32 v164, s93, v231
	v_max_i32_e32 v164, 0, v164
	v_min_u32_e32 v164, s40, v164
	v_lshl_or_b32 v164, v164, 7, v220
	global_load_lds_dwordx4 v164, s[20:21]
	s_add_i32 m0, s15, 0x400
	v_add_u32_e32 v165, s93, v232
	v_max_i32_e32 v165, 0, v165
	v_min_u32_e32 v165, s40, v165
	v_lshl_or_b32 v165, v165, 7, v221
	global_load_lds_dwordx4 v165, s[20:21]
	s_waitcnt vmcnt(8)
	v_add_u32_e32 v146, s16, v223
	v_add_u32_e32 v147, s16, v224
	ds_read_b128 v[88:91], v146
	ds_read_b128 v[92:95], v147
	s_waitcnt lgkmcnt(0)
	v_mfma_f32_16x16x32_bf16 v[20:23], v[88:91], v[72:75], 0
	v_mfma_f32_16x16x32_bf16 v[52:55], v[88:91], v[80:83], 0
	v_mfma_f32_16x16x32_bf16 v[20:23], v[92:95], v[76:79], v[20:23]
	v_mfma_f32_16x16x32_bf16 v[52:55], v[92:95], v[84:87], v[52:55]
	s_waitcnt lgkmcnt(0)
	s_add_i32 s93, s76, 0xffffff00
	s_mov_b32 m0, s16
	v_add_u32_e32 v164, s93, v231
	v_max_i32_e32 v164, 0, v164
	v_min_u32_e32 v164, s40, v164
	v_lshl_or_b32 v164, v164, 7, v222
	global_load_lds_dwordx4 v164, s[24:25]
	s_add_i32 m0, s16, 0x400
	v_add_u32_e32 v165, s93, v232
	v_max_i32_e32 v165, 0, v165
	v_min_u32_e32 v165, s40, v165
	v_lshl_or_b32 v165, v165, 7, v222
	global_load_lds_dwordx4 v165, s[24:25]
	s_waitcnt vmcnt(8)
	v_add_u32_e32 v146, s12, v223
	v_add_u32_e32 v147, s12, v224
	ds_read_b128 v[88:91], v146
	ds_read_b128 v[92:95], v147
	s_waitcnt lgkmcnt(0)
	v_mfma_f32_16x16x32_bf16 v[24:27], v[88:91], v[72:75], 0
	v_mfma_f32_16x16x32_bf16 v[56:59], v[88:91], v[80:83], 0
	v_mfma_f32_16x16x32_bf16 v[24:27], v[92:95], v[76:79], v[24:27]
	v_mfma_f32_16x16x32_bf16 v[56:59], v[92:95], v[84:87], v[56:59]
	s_waitcnt lgkmcnt(0)
	s_add_i32 s93, s76, 0xffffff40
	s_mov_b32 m0, s12
	v_add_u32_e32 v164, s93, v231
	v_max_i32_e32 v164, 0, v164
	v_min_u32_e32 v164, s40, v164
	v_lshl_or_b32 v164, v164, 7, v222
	global_load_lds_dwordx4 v164, s[24:25]
	s_add_i32 m0, s12, 0x400
	v_add_u32_e32 v165, s93, v232
	v_max_i32_e32 v165, 0, v165
	v_min_u32_e32 v165, s40, v165
	v_lshl_or_b32 v165, v165, 7, v222
	global_load_lds_dwordx4 v165, s[24:25]
	s_waitcnt vmcnt(8)
	v_add_u32_e32 v146, s13, v223
	v_add_u32_e32 v147, s13, v224
	ds_read_b128 v[88:91], v146
	ds_read_b128 v[92:95], v147
	s_waitcnt lgkmcnt(0)
	v_mfma_f32_16x16x32_bf16 v[28:31], v[88:91], v[72:75], 0
	v_mfma_f32_16x16x32_bf16 v[60:63], v[88:91], v[80:83], 0
	v_mfma_f32_16x16x32_bf16 v[28:31], v[92:95], v[76:79], v[28:31]
	v_mfma_f32_16x16x32_bf16 v[60:63], v[92:95], v[84:87], v[60:63]
	s_waitcnt lgkmcnt(0)
	s_add_i32 s93, s76, 0xffffff80
	s_mov_b32 m0, s13
	v_add_u32_e32 v164, s93, v231
	v_max_i32_e32 v164, 0, v164
	v_min_u32_e32 v164, s40, v164
	v_lshl_or_b32 v164, v164, 7, v222
	global_load_lds_dwordx4 v164, s[24:25]
	s_add_i32 m0, s13, 0x400
	v_add_u32_e32 v165, s93, v232
	v_max_i32_e32 v165, 0, v165
	v_min_u32_e32 v165, s40, v165
	v_lshl_or_b32 v165, v165, 7, v222
	global_load_lds_dwordx4 v165, s[24:25]
	s_waitcnt vmcnt(8)
	v_add_u32_e32 v146, s14, v223
	v_add_u32_e32 v147, s14, v224
	ds_read_b128 v[88:91], v146
	ds_read_b128 v[92:95], v147
	s_waitcnt lgkmcnt(0)
	v_mfma_f32_16x16x32_bf16 v[32:35], v[88:91], v[72:75], 0
	v_mfma_f32_16x16x32_bf16 v[64:67], v[88:91], v[80:83], 0
	v_mfma_f32_16x16x32_bf16 v[32:35], v[92:95], v[76:79], v[32:35]
	v_mfma_f32_16x16x32_bf16 v[64:67], v[92:95], v[84:87], v[64:67]
	s_waitcnt lgkmcnt(0)
	s_add_i32 s93, s76, 0xffffffc0
	s_mov_b32 m0, s14
	v_add_u32_e32 v164, s93, v231
	v_max_i32_e32 v164, 0, v164
	v_min_u32_e32 v164, s40, v164
	v_lshl_or_b32 v164, v164, 7, v222
	global_load_lds_dwordx4 v164, s[24:25]
	s_add_i32 m0, s14, 0x400
	v_add_u32_e32 v165, s93, v232
	v_max_i32_e32 v165, 0, v165
	v_min_u32_e32 v165, s40, v165
	v_lshl_or_b32 v165, v165, 7, v222
	global_load_lds_dwordx4 v165, s[24:25]
	s_waitcnt vmcnt(8)
	v_add_u32_e32 v146, s15, v223
	v_add_u32_e32 v147, s15, v224
	ds_read_b128 v[88:91], v146
	ds_read_b128 v[92:95], v147
	s_waitcnt lgkmcnt(0)
	v_mfma_f32_16x16x32_bf16 v[68:71], v[88:91], v[80:83], 0
	v_mfma_f32_16x16x32_bf16 v[68:71], v[92:95], v[84:87], v[68:71]
	v_mov_b32_e32 v188, s83
	v_lshl_add_u32 v188, v216, 2, v188
	v_lshrrev_b32_e32 v146, 4, v188
	v_xor_b32_e32 v146, v146, v188
	v_and_b32_e32 v146, 15, v146
	v_lshlrev_b32_e32 v147, 8, v188
	v_or_b32_e32 v148, 0, v217
	v_xor_b32_e32 v148, v148, v146
	v_lshl_add_u32 v190, v148, 4, v147
	v_or_b32_e32 v148, 4, v217
	v_xor_b32_e32 v148, v148, v146
	v_lshl_add_u32 v191, v148, 4, v147
	v_or_b32_e32 v148, 8, v217
	v_xor_b32_e32 v148, v148, v146
	v_lshl_add_u32 v192, v148, 4, v147
	v_or_b32_e32 v148, 12, v217
	v_xor_b32_e32 v148, v148, v146
	v_lshl_add_u32 v193, v148, 4, v147
	v_lshlrev_b32_e32 v194, 3, v188
	v_add_u32_e32 v194, 0x10000, v194
	ds_read_b64 v[144:145], v194
	ds_read_b128 v[128:131], v190
	ds_read_b128 v[132:135], v191
	ds_read_b128 v[136:139], v192
	ds_read_b128 v[140:143], v193
	v_mov_b32_e32 v189, s83
	v_lshl_add_u32 v189, v216, 2, v189
	v_add_u32_e32 v189, 64, v189
	v_lshrrev_b32_e32 v146, 4, v189
	v_xor_b32_e32 v146, v146, v189
	v_and_b32_e32 v146, 15, v146
	v_lshlrev_b32_e32 v147, 8, v189
	v_or_b32_e32 v148, 0, v217
	v_xor_b32_e32 v148, v148, v146
	v_lshl_add_u32 v195, v148, 4, v147
	v_or_b32_e32 v148, 4, v217
	v_xor_b32_e32 v148, v148, v146
	v_lshl_add_u32 v196, v148, 4, v147
	v_or_b32_e32 v148, 8, v217
	v_xor_b32_e32 v148, v148, v146
	v_lshl_add_u32 v197, v148, 4, v147
	v_or_b32_e32 v148, 12, v217
	v_xor_b32_e32 v148, v148, v146
	v_lshl_add_u32 v198, v148, 4, v147
	v_lshlrev_b32_e32 v199, 3, v189
	v_add_u32_e32 v199, 0x10000, v199
	ds_read_b64 v[182:183], v199
	ds_read_b128 v[166:169], v195
	ds_read_b128 v[170:173], v196
	ds_read_b128 v[174:177], v197
	ds_read_b128 v[178:181], v198
	s_add_i32 s90, s76, 0x17c
	s_cmp_gt_i32 s90, s40
	s_cselect_b32 s96, 1, 0
	s_cmp_lt_i32 s76, 0x100
	s_cselect_b32 s96, 1, s96
	s_ashr_i32 s77, s76, 2
	s_sub_i32 s77, 64, s77
	s_sub_i32 s78, s40, s76
	s_ashr_i32 s78, s78, 2
	s_add_i32 s78, s78, 64
	v_cndmask_b32_e64 v0, v0, v230, s[52:53]
	v_cndmask_b32_e64 v32, v32, v230, s[62:63]
	v_cndmask_b32_e64 v1, v1, v230, s[56:57]
	v_cndmask_b32_e64 v33, v33, v230, s[64:65]
	v_cndmask_b32_e64 v2, v2, v230, s[58:59]
	v_cndmask_b32_e64 v34, v34, v230, s[70:71]
	v_cndmask_b32_e64 v3, v3, v230, s[60:61]
	v_cndmask_b32_e64 v35, v35, v230, s[72:73]
	s_cmp_eq_u32 s96, 0
	s_cbranch_scc1 .Latt_noedge_3
	v_sub_u32_e32 v200, s77, v229
	s_sub_i32 s91, s78, s77
	v_sub_u32_e32 v150, 0, v200
	v_sub_u32_e32 v151, 1, v200
	v_sub_u32_e32 v152, 2, v200
	v_sub_u32_e32 v153, 3, v200
	v_cmp_lt_u32_e64 s[94:95], s91, v150
	v_cmp_lt_u32_e64 s[86:87], s91, v151
	v_cmp_lt_u32_e64 s[0:1], s91, v152
	v_cmp_lt_u32_e64 s[2:3], s91, v153
	v_cndmask_b32_e64 v0, v0, v230, s[94:95]
	v_cndmask_b32_e64 v1, v1, v230, s[86:87]
	v_cndmask_b32_e64 v2, v2, v230, s[0:1]
	v_cndmask_b32_e64 v3, v3, v230, s[2:3]
	v_sub_u32_e32 v150, 16, v200
	v_sub_u32_e32 v151, 17, v200
	v_sub_u32_e32 v152, 18, v200
	v_sub_u32_e32 v153, 19, v200
	v_cmp_lt_u32_e64 s[94:95], s91, v150
	v_cmp_lt_u32_e64 s[86:87], s91, v151
	v_cmp_lt_u32_e64 s[0:1], s91, v152
	v_cmp_lt_u32_e64 s[2:3], s91, v153
	v_cndmask_b32_e64 v4, v4, v230, s[94:95]
	v_cndmask_b32_e64 v5, v5, v230, s[86:87]
	v_cndmask_b32_e64 v6, v6, v230, s[0:1]
	v_cndmask_b32_e64 v7, v7, v230, s[2:3]
	v_sub_u32_e32 v150, 32, v200
	v_sub_u32_e32 v151, 33, v200
	v_sub_u32_e32 v152, 34, v200
	v_sub_u32_e32 v153, 35, v200
	v_cmp_lt_u32_e64 s[94:95], s91, v150
	v_cmp_lt_u32_e64 s[86:87], s91, v151
	v_cmp_lt_u32_e64 s[0:1], s91, v152
	v_cmp_lt_u32_e64 s[2:3], s91, v153
	v_cndmask_b32_e64 v8, v8, v230, s[94:95]
	v_cndmask_b32_e64 v9, v9, v230, s[86:87]
	v_cndmask_b32_e64 v10, v10, v230, s[0:1]
	v_cndmask_b32_e64 v11, v11, v230, s[2:3]
	v_sub_u32_e32 v150, 48, v200
	v_sub_u32_e32 v151, 49, v200
	v_sub_u32_e32 v152, 50, v200
	v_sub_u32_e32 v153, 51, v200
	v_cmp_lt_u32_e64 s[94:95], s91, v150
	v_cmp_lt_u32_e64 s[86:87], s91, v151
	v_cmp_lt_u32_e64 s[0:1], s91, v152
	v_cmp_lt_u32_e64 s[2:3], s91, v153
	v_cndmask_b32_e64 v12, v12, v230, s[94:95]
	v_cndmask_b32_e64 v13, v13, v230, s[86:87]
	v_cndmask_b32_e64 v14, v14, v230, s[0:1]
	v_cndmask_b32_e64 v15, v15, v230, s[2:3]
	v_sub_u32_e32 v150, 64, v200
	v_sub_u32_e32 v151, 0x41, v200
	v_sub_u32_e32 v152, 0x42, v200
	v_sub_u32_e32 v153, 0x43, v200
	v_cmp_lt_u32_e64 s[94:95], s91, v150
	v_cmp_lt_u32_e64 s[86:87], s91, v151
	v_cmp_lt_u32_e64 s[0:1], s91, v152
	v_cmp_lt_u32_e64 s[2:3], s91, v153
	v_cndmask_b32_e64 v16, v16, v230, s[94:95]
	v_cndmask_b32_e64 v17, v17, v230, s[86:87]
	v_cndmask_b32_e64 v18, v18, v230, s[0:1]
	v_cndmask_b32_e64 v19, v19, v230, s[2:3]
	v_sub_u32_e32 v150, 0x50, v200
	v_sub_u32_e32 v151, 0x51, v200
	v_sub_u32_e32 v152, 0x52, v200
	v_sub_u32_e32 v153, 0x53, v200
	v_cmp_lt_u32_e64 s[94:95], s91, v150
	v_cmp_lt_u32_e64 s[86:87], s91, v151
	v_cmp_lt_u32_e64 s[0:1], s91, v152
	v_cmp_lt_u32_e64 s[2:3], s91, v153
	v_cndmask_b32_e64 v20, v20, v230, s[94:95]
	v_cndmask_b32_e64 v21, v21, v230, s[86:87]
	v_cndmask_b32_e64 v22, v22, v230, s[0:1]
	v_cndmask_b32_e64 v23, v23, v230, s[2:3]
	v_sub_u32_e32 v150, 0x60, v200
	v_sub_u32_e32 v151, 0x61, v200
	v_sub_u32_e32 v152, 0x62, v200
	v_sub_u32_e32 v153, 0x63, v200
	v_cmp_lt_u32_e64 s[94:95], s91, v150
	v_cmp_lt_u32_e64 s[86:87], s91, v151
	v_cmp_lt_u32_e64 s[0:1], s91, v152
	v_cmp_lt_u32_e64 s[2:3], s91, v153
	v_cndmask_b32_e64 v24, v24, v230, s[94:95]
	v_cndmask_b32_e64 v25, v25, v230, s[86:87]
	v_cndmask_b32_e64 v26, v26, v230, s[0:1]
	v_cndmask_b32_e64 v27, v27, v230, s[2:3]
	v_sub_u32_e32 v150, 0x70, v200
	v_sub_u32_e32 v151, 0x71, v200
	v_sub_u32_e32 v152, 0x72, v200
	v_sub_u32_e32 v153, 0x73, v200
	v_cmp_lt_u32_e64 s[94:95], s91, v150
	v_cmp_lt_u32_e64 s[86:87], s91, v151
	v_cmp_lt_u32_e64 s[0:1], s91, v152
	v_cmp_lt_u32_e64 s[2:3], s91, v153
	v_cndmask_b32_e64 v28, v28, v230, s[94:95]
	v_cndmask_b32_e64 v29, v29, v230, s[86:87]
	v_cndmask_b32_e64 v30, v30, v230, s[0:1]
	v_cndmask_b32_e64 v31, v31, v230, s[2:3]
	v_sub_u32_e32 v150, 0x80, v200
	v_sub_u32_e32 v151, 0x81, v200
	v_sub_u32_e32 v152, 0x82, v200
	v_sub_u32_e32 v153, 0x83, v200
	v_cmp_lt_u32_e64 s[94:95], s91, v150
	v_cmp_lt_u32_e64 s[86:87], s91, v151
	v_cmp_lt_u32_e64 s[0:1], s91, v152
	v_cmp_lt_u32_e64 s[2:3], s91, v153
	v_cndmask_b32_e64 v32, v32, v230, s[94:95]
	v_cndmask_b32_e64 v33, v33, v230, s[86:87]
	v_cndmask_b32_e64 v34, v34, v230, s[0:1]
	v_cndmask_b32_e64 v35, v35, v230, s[2:3]

.Latt_noedge_4:
	s_nop 1
	v_max3_f32 v186, v36, v37, v38
	v_max3_f32 v186, v186, v39, v40
	v_max3_f32 v186, v186, v41, v42
	v_max3_f32 v186, v186, v43, v44
	v_max3_f32 v186, v186, v45, v46
	v_max3_f32 v186, v186, v47, v48
	v_max3_f32 v186, v186, v49, v50
	v_max3_f32 v186, v186, v51, v52
	v_max3_f32 v186, v186, v53, v54
	v_max3_f32 v186, v186, v55, v56
	v_max3_f32 v186, v186, v57, v58
	v_max3_f32 v186, v186, v59, v60
	v_max3_f32 v186, v186, v61, v62
	v_max3_f32 v186, v186, v63, v64
	v_max3_f32 v186, v186, v65, v66
	v_max3_f32 v186, v186, v67, v68
	v_max3_f32 v186, v186, v69, v70
	v_max_f32_e32 v186, v186, v71
	v_mov_b32_e32 v146, v186
	s_nop 1
	v_permlane16_swap_b32_e32 v186, v146
	v_max_f32_e32 v186, v186, v146
	v_mov_b32_e32 v146, v186
	s_nop 1
	v_permlane32_swap_b32_e32 v186, v146
	v_max_f32_e32 v186, v186, v146
	v_sub_f32_e32 v36, v36, v186
	v_sub_f32_e32 v37, v37, v186
	v_sub_f32_e32 v38, v38, v186
	v_sub_f32_e32 v39, v39, v186
	v_exp_f32_e32 v36, v36
	v_exp_f32_e32 v37, v37
	v_exp_f32_e32 v38, v38
	v_exp_f32_e32 v39, v39
	v_sub_f32_e32 v40, v40, v186
	v_sub_f32_e32 v41, v41, v186
	v_sub_f32_e32 v42, v42, v186
	v_sub_f32_e32 v43, v43, v186
	v_exp_f32_e32 v40, v40
	v_exp_f32_e32 v41, v41
	v_exp_f32_e32 v42, v42
	v_exp_f32_e32 v43, v43
	v_sub_f32_e32 v44, v44, v186
	v_sub_f32_e32 v45, v45, v186
	v_sub_f32_e32 v46, v46, v186
	v_sub_f32_e32 v47, v47, v186
	v_exp_f32_e32 v44, v44
	v_exp_f32_e32 v45, v45
	v_exp_f32_e32 v46, v46
	v_exp_f32_e32 v47, v47
	v_sub_f32_e32 v48, v48, v186
	v_sub_f32_e32 v49, v49, v186
	v_sub_f32_e32 v50, v50, v186
	v_sub_f32_e32 v51, v51, v186
	v_exp_f32_e32 v48, v48
	v_exp_f32_e32 v49, v49
	v_exp_f32_e32 v50, v50
	v_exp_f32_e32 v51, v51
	v_sub_f32_e32 v52, v52, v186
	v_sub_f32_e32 v53, v53, v186
	v_sub_f32_e32 v54, v54, v186
	v_sub_f32_e32 v55, v55, v186
	v_exp_f32_e32 v52, v52
	v_exp_f32_e32 v53, v53
	v_exp_f32_e32 v54, v54
	v_exp_f32_e32 v55, v55
	v_sub_f32_e32 v56, v56, v186
	v_sub_f32_e32 v57, v57, v186
	v_sub_f32_e32 v58, v58, v186
	v_sub_f32_e32 v59, v59, v186
	v_exp_f32_e32 v56, v56
	v_exp_f32_e32 v57, v57
	v_exp_f32_e32 v58, v58
	v_exp_f32_e32 v59, v59
	v_sub_f32_e32 v60, v60, v186
	v_sub_f32_e32 v61, v61, v186
	v_sub_f32_e32 v62, v62, v186
	v_sub_f32_e32 v63, v63, v186
	v_exp_f32_e32 v60, v60
	v_exp_f32_e32 v61, v61
	v_exp_f32_e32 v62, v62
	v_exp_f32_e32 v63, v63
	v_sub_f32_e32 v64, v64, v186
	v_sub_f32_e32 v65, v65, v186
	v_sub_f32_e32 v66, v66, v186
	v_sub_f32_e32 v67, v67, v186
	v_exp_f32_e32 v64, v64
	v_exp_f32_e32 v65, v65
	v_exp_f32_e32 v66, v66
	v_exp_f32_e32 v67, v67
	v_sub_f32_e32 v68, v68, v186
	v_sub_f32_e32 v69, v69, v186
	v_sub_f32_e32 v70, v70, v186
	v_sub_f32_e32 v71, v71, v186
	v_exp_f32_e32 v68, v68
	v_exp_f32_e32 v69, v69
	v_exp_f32_e32 v70, v70
	v_exp_f32_e32 v71, v71
	s_nop 0
	v_add_f32_e32 v187, v36, v37
	v_add_f32_e32 v187, v187, v38
	v_add_f32_e32 v187, v187, v39
	v_add_f32_e32 v187, v187, v40
	v_add_f32_e32 v187, v187, v41
	v_add_f32_e32 v187, v187, v42
	v_add_f32_e32 v187, v187, v43
	v_add_f32_e32 v187, v187, v44
	v_add_f32_e32 v187, v187, v45
	v_add_f32_e32 v187, v187, v46
	v_add_f32_e32 v187, v187, v47
	v_add_f32_e32 v187, v187, v48
	v_add_f32_e32 v187, v187, v49
	v_add_f32_e32 v187, v187, v50
	v_add_f32_e32 v187, v187, v51
	v_add_f32_e32 v187, v187, v52
	v_add_f32_e32 v187, v187, v53
	v_add_f32_e32 v187, v187, v54
	v_add_f32_e32 v187, v187, v55
	v_add_f32_e32 v187, v187, v56
	v_add_f32_e32 v187, v187, v57
	v_add_f32_e32 v187, v187, v58
	v_add_f32_e32 v187, v187, v59
	v_add_f32_e32 v187, v187, v60
	v_add_f32_e32 v187, v187, v61
	v_add_f32_e32 v187, v187, v62
	v_add_f32_e32 v187, v187, v63
	v_add_f32_e32 v187, v187, v64
	v_add_f32_e32 v187, v187, v65
	v_add_f32_e32 v187, v187, v66
	v_add_f32_e32 v187, v187, v67
	v_add_f32_e32 v187, v187, v68
	v_add_f32_e32 v187, v187, v69
	v_add_f32_e32 v187, v187, v70
	v_add_f32_e32 v187, v187, v71
	v_cvt_pk_bf16_f32 v36, v36, v37
	v_cvt_pk_bf16_f32 v37, v38, v39
	v_cvt_pk_bf16_f32 v40, v40, v41
	v_cvt_pk_bf16_f32 v41, v42, v43
	v_cvt_pk_bf16_f32 v44, v44, v45
	v_cvt_pk_bf16_f32 v45, v46, v47
	v_cvt_pk_bf16_f32 v48, v48, v49
	v_cvt_pk_bf16_f32 v49, v50, v51
	v_cvt_pk_bf16_f32 v52, v52, v53
	v_cvt_pk_bf16_f32 v53, v54, v55
	v_cvt_pk_bf16_f32 v56, v56, v57
	v_cvt_pk_bf16_f32 v57, v58, v59
	v_cvt_pk_bf16_f32 v60, v60, v61
	v_cvt_pk_bf16_f32 v61, v62, v63
	v_cvt_pk_bf16_f32 v64, v64, v65
	v_cvt_pk_bf16_f32 v65, v66, v67
	v_cvt_pk_bf16_f32 v68, v68, v69
	v_cvt_pk_bf16_f32 v69, v70, v71
	v_mov_b32_e32 v146, v187
	s_nop 1
	v_permlane16_swap_b32_e32 v187, v146
	v_add_f32_e32 v187, v187, v146
	v_mov_b32_e32 v146, v187
	s_nop 1
	v_permlane32_swap_b32_e32 v187, v146
	v_add_f32_e32 v187, v187, v146
	s_waitcnt lgkmcnt(0)
	s_add_i32 s93, s76, 0
	s_mov_b32 m0, s15
	v_add_u32_e32 v164, s93, v231
	v_max_i32_e32 v164, 0, v164
	v_min_u32_e32 v164, s40, v164
	v_lshl_or_b32 v164, v164, 7, v222
	global_load_lds_dwordx4 v164, s[24:25]
	s_add_i32 m0, s15, 0x400
	v_add_u32_e32 v165, s93, v232
	v_max_i32_e32 v165, 0, v165
	v_min_u32_e32 v165, s40, v165
	v_lshl_or_b32 v165, v165, 7, v222
	global_load_lds_dwordx4 v165, s[24:25]
	s_waitcnt vmcnt(8)
	v_add_u32_e32 v146, s16, v225
	v_add_u32_e32 v147, s16, v226
	v_add_u32_e32 v148, s16, v227
	v_add_u32_e32 v149, s16, v228
	ds_read_b64_tr_b16 v[88:89], v146
	ds_read_b64_tr_b16 v[90:91], v147
	ds_read_b64_tr_b16 v[92:93], v148
	ds_read_b64_tr_b16 v[94:95], v149
	s_waitcnt lgkmcnt(0)
	v_mfma_f32_16x16x16_bf16 v[96:99], v[88:89], v[0:1], 0
	v_mfma_f32_16x16x16_bf16 v[100:103], v[90:91], v[0:1], 0
	v_mfma_f32_16x16x16_bf16 v[104:107], v[92:93], v[0:1], 0
	v_mfma_f32_16x16x16_bf16 v[108:111], v[94:95], v[0:1], 0
	s_waitcnt lgkmcnt(0)
	s_add_i32 s93, s76, 64
	s_mov_b32 m0, s16
	v_add_u32_e32 v164, s93, v231
	v_max_i32_e32 v164, 0, v164
	v_min_u32_e32 v164, s40, v164
	v_lshl_or_b32 v164, v164, 7, v222
	global_load_lds_dwordx4 v164, s[24:25]
	s_add_i32 m0, s16, 0x400
	v_add_u32_e32 v165, s93, v232
	v_max_i32_e32 v165, 0, v165
	v_min_u32_e32 v165, s40, v165
	v_lshl_or_b32 v165, v165, 7, v222
	global_load_lds_dwordx4 v165, s[24:25]
	s_waitcnt vmcnt(8)
	v_add_u32_e32 v146, s12, v225
	v_add_u32_e32 v147, s12, v226
	v_add_u32_e32 v148, s12, v227
	v_add_u32_e32 v149, s12, v228
	ds_read_b64_tr_b16 v[88:89], v146
	ds_read_b64_tr_b16 v[90:91], v147
	ds_read_b64_tr_b16 v[92:93], v148
	ds_read_b64_tr_b16 v[94:95], v149
	s_waitcnt lgkmcnt(0)
	v_mfma_f32_16x16x16_bf16 v[96:99], v[88:89], v[4:5], v[96:99]
	v_mfma_f32_16x16x16_bf16 v[112:115], v[88:89], v[36:37], 0
	v_mfma_f32_16x16x16_bf16 v[100:103], v[90:91], v[4:5], v[100:103]
	v_mfma_f32_16x16x16_bf16 v[116:119], v[90:91], v[36:37], 0
	v_mfma_f32_16x16x16_bf16 v[104:107], v[92:93], v[4:5], v[104:107]
	v_mfma_f32_16x16x16_bf16 v[120:123], v[92:93], v[36:37], 0
	v_mfma_f32_16x16x16_bf16 v[108:111], v[94:95], v[4:5], v[108:111]
	v_mfma_f32_16x16x16_bf16 v[124:127], v[94:95], v[36:37], 0
	s_waitcnt lgkmcnt(0)
	s_add_i32 s93, s76, 0x80
	s_mov_b32 m0, s12
	v_add_u32_e32 v164, s93, v231
	v_max_i32_e32 v164, 0, v164
	v_min_u32_e32 v164, s40, v164
	v_lshl_or_b32 v164, v164, 7, v222
	global_load_lds_dwordx4 v164, s[24:25]
	s_add_i32 m0, s12, 0x400
	v_add_u32_e32 v165, s93, v232
	v_max_i32_e32 v165, 0, v165
	v_min_u32_e32 v165, s40, v165
	v_lshl_or_b32 v165, v165, 7, v222
	global_load_lds_dwordx4 v165, s[24:25]
	s_waitcnt vmcnt(8)
	v_add_u32_e32 v146, s13, v225
	v_add_u32_e32 v147, s13, v226
	v_add_u32_e32 v148, s13, v227
	v_add_u32_e32 v149, s13, v228
	ds_read_b64_tr_b16 v[88:89], v146
	ds_read_b64_tr_b16 v[90:91], v147
	ds_read_b64_tr_b16 v[92:93], v148
	ds_read_b64_tr_b16 v[94:95], v149
	s_waitcnt lgkmcnt(0)
	v_mfma_f32_16x16x16_bf16 v[96:99], v[88:89], v[8:9], v[96:99]
	v_mfma_f32_16x16x16_bf16 v[112:115], v[88:89], v[40:41], v[112:115]
	v_mfma_f32_16x16x16_bf16 v[100:103], v[90:91], v[8:9], v[100:103]
	v_mfma_f32_16x16x16_bf16 v[116:119], v[90:91], v[40:41], v[116:119]
	v_mfma_f32_16x16x16_bf16 v[104:107], v[92:93], v[8:9], v[104:107]
	v_mfma_f32_16x16x16_bf16 v[120:123], v[92:93], v[40:41], v[120:123]
	v_mfma_f32_16x16x16_bf16 v[108:111], v[94:95], v[8:9], v[108:111]
	v_mfma_f32_16x16x16_bf16 v[124:127], v[94:95], v[40:41], v[124:127]
	s_waitcnt lgkmcnt(0)
	s_add_i32 s93, s76, 0xc0
	s_mov_b32 m0, s13
	v_add_u32_e32 v164, s93, v231
	v_max_i32_e32 v164, 0, v164
	v_min_u32_e32 v164, s40, v164
	v_lshl_or_b32 v164, v164, 7, v222
	global_load_lds_dwordx4 v164, s[24:25]
	s_add_i32 m0, s13, 0x400
	v_add_u32_e32 v165, s93, v232
	v_max_i32_e32 v165, 0, v165
	v_min_u32_e32 v165, s40, v165
	v_lshl_or_b32 v165, v165, 7, v222
	global_load_lds_dwordx4 v165, s[24:25]
	s_waitcnt vmcnt(8)
	v_add_u32_e32 v146, s14, v225
	v_add_u32_e32 v147, s14, v226
	v_add_u32_e32 v148, s14, v227
	v_add_u32_e32 v149, s14, v228
	ds_read_b64_tr_b16 v[88:89], v146
	ds_read_b64_tr_b16 v[90:91], v147
	ds_read_b64_tr_b16 v[92:93], v148
	ds_read_b64_tr_b16 v[94:95], v149
	s_waitcnt lgkmcnt(0)
	v_mfma_f32_16x16x16_bf16 v[96:99], v[88:89], v[12:13], v[96:99]
	v_mfma_f32_16x16x16_bf16 v[112:115], v[88:89], v[44:45], v[112:115]
	v_mfma_f32_16x16x16_bf16 v[100:103], v[90:91], v[12:13], v[100:103]
	v_mfma_f32_16x16x16_bf16 v[116:119], v[90:91], v[44:45], v[116:119]
	v_mfma_f32_16x16x16_bf16 v[104:107], v[92:93], v[12:13], v[104:107]
	v_mfma_f32_16x16x16_bf16 v[120:123], v[92:93], v[44:45], v[120:123]
	v_mfma_f32_16x16x16_bf16 v[108:111], v[94:95], v[12:13], v[108:111]
	v_mfma_f32_16x16x16_bf16 v[124:127], v[94:95], v[44:45], v[124:127]
	s_waitcnt lgkmcnt(0)
	s_add_i32 s93, s76, 0x100
	s_mov_b32 m0, s14
	v_add_u32_e32 v164, s93, v231
	v_max_i32_e32 v164, 0, v164
	v_min_u32_e32 v164, s40, v164
	v_lshl_or_b32 v164, v164, 7, v222
	global_load_lds_dwordx4 v164, s[24:25]
	s_add_i32 m0, s14, 0x400
	v_add_u32_e32 v165, s93, v232
	v_max_i32_e32 v165, 0, v165
	v_min_u32_e32 v165, s40, v165
	v_lshl_or_b32 v165, v165, 7, v222
	global_load_lds_dwordx4 v165, s[24:25]
	s_waitcnt vmcnt(8)
	v_add_u32_e32 v146, s15, v225
	v_add_u32_e32 v147, s15, v226
	v_add_u32_e32 v148, s15, v227
	v_add_u32_e32 v149, s15, v228
	ds_read_b64_tr_b16 v[88:89], v146
	ds_read_b64_tr_b16 v[90:91], v147
	ds_read_b64_tr_b16 v[92:93], v148
	ds_read_b64_tr_b16 v[94:95], v149
	s_waitcnt lgkmcnt(0)
	v_mfma_f32_16x16x16_bf16 v[96:99], v[88:89], v[16:17], v[96:99]
	v_mfma_f32_16x16x16_bf16 v[112:115], v[88:89], v[48:49], v[112:115]
	v_mfma_f32_16x16x16_bf16 v[100:103], v[90:91], v[16:17], v[100:103]
	v_mfma_f32_16x16x16_bf16 v[116:119], v[90:91], v[48:49], v[116:119]
	v_mfma_f32_16x16x16_bf16 v[104:107], v[92:93], v[16:17], v[104:107]
	v_mfma_f32_16x16x16_bf16 v[120:123], v[92:93], v[48:49], v[120:123]
	v_mfma_f32_16x16x16_bf16 v[108:111], v[94:95], v[16:17], v[108:111]
	v_mfma_f32_16x16x16_bf16 v[124:127], v[94:95], v[48:49], v[124:127]
	s_waitcnt lgkmcnt(0)
	s_add_i32 s93, s76, 0x140
	s_mov_b32 m0, s15
	v_add_u32_e32 v164, s93, v231
	v_max_i32_e32 v164, 0, v164
	v_min_u32_e32 v164, s40, v164
	v_lshl_or_b32 v164, v164, 7, v222
	global_load_lds_dwordx4 v164, s[24:25]
	s_add_i32 m0, s15, 0x400
	v_add_u32_e32 v165, s93, v232
	v_max_i32_e32 v165, 0, v165
	v_min_u32_e32 v165, s40, v165
	v_lshl_or_b32 v165, v165, 7, v222
	global_load_lds_dwordx4 v165, s[24:25]
	s_waitcnt vmcnt(8)
	v_add_u32_e32 v146, s16, v225
	v_add_u32_e32 v147, s16, v226
	v_add_u32_e32 v148, s16, v227
	v_add_u32_e32 v149, s16, v228
	ds_read_b64_tr_b16 v[88:89], v146
	ds_read_b64_tr_b16 v[90:91], v147
	ds_read_b64_tr_b16 v[92:93], v148
	ds_read_b64_tr_b16 v[94:95], v149
	s_waitcnt lgkmcnt(0)
	v_mfma_f32_16x16x16_bf16 v[96:99], v[88:89], v[20:21], v[96:99]
	v_mfma_f32_16x16x16_bf16 v[112:115], v[88:89], v[52:53], v[112:115]
	v_mfma_f32_16x16x16_bf16 v[100:103], v[90:91], v[20:21], v[100:103]
	v_mfma_f32_16x16x16_bf16 v[116:119], v[90:91], v[52:53], v[116:119]
	v_mfma_f32_16x16x16_bf16 v[104:107], v[92:93], v[20:21], v[104:107]
	v_mfma_f32_16x16x16_bf16 v[120:123], v[92:93], v[52:53], v[120:123]
	v_mfma_f32_16x16x16_bf16 v[108:111], v[94:95], v[20:21], v[108:111]
	v_mfma_f32_16x16x16_bf16 v[124:127], v[94:95], v[52:53], v[124:127]
	s_waitcnt lgkmcnt(0)
	s_add_i32 s93, s79, 0
	s_mov_b32 m0, s16
	v_add_u32_e32 v164, s93, v162
	v_lshl_or_b32 v164, v164, 7, v220
	global_load_lds_dwordx4 v164, s[18:19]
	s_add_i32 m0, s16, 0x400
	v_add_u32_e32 v165, s93, v163
	v_lshl_or_b32 v165, v165, 7, v221
	global_load_lds_dwordx4 v165, s[18:19]
	s_waitcnt vmcnt(8)
	v_add_u32_e32 v146, s12, v225
	v_add_u32_e32 v147, s12, v226
	v_add_u32_e32 v148, s12, v227
	v_add_u32_e32 v149, s12, v228
	ds_read_b64_tr_b16 v[88:89], v146
	ds_read_b64_tr_b16 v[90:91], v147
	ds_read_b64_tr_b16 v[92:93], v148
	ds_read_b64_tr_b16 v[94:95], v149
	s_waitcnt lgkmcnt(0)
	v_mfma_f32_16x16x16_bf16 v[96:99], v[88:89], v[24:25], v[96:99]
	v_mfma_f32_16x16x16_bf16 v[112:115], v[88:89], v[56:57], v[112:115]
	v_mfma_f32_16x16x16_bf16 v[100:103], v[90:91], v[24:25], v[100:103]
	v_mfma_f32_16x16x16_bf16 v[116:119], v[90:91], v[56:57], v[116:119]
	v_mfma_f32_16x16x16_bf16 v[104:107], v[92:93], v[24:25], v[104:107]
	v_mfma_f32_16x16x16_bf16 v[120:123], v[92:93], v[56:57], v[120:123]
	v_mfma_f32_16x16x16_bf16 v[108:111], v[94:95], v[24:25], v[108:111]
	v_mfma_f32_16x16x16_bf16 v[124:127], v[94:95], v[56:57], v[124:127]
	s_waitcnt lgkmcnt(0)
	s_add_i32 s93, s79, 0xfffffc00
	s_mov_b32 m0, s12
	v_add_u32_e32 v164, s93, v162
	v_max_i32_e32 v164, 0, v164
	v_min_u32_e32 v164, s40, v164
	v_lshl_or_b32 v164, v164, 7, v220
	global_load_lds_dwordx4 v164, s[20:21]
	s_add_i32 m0, s12, 0x400
	v_add_u32_e32 v165, s93, v163
	v_max_i32_e32 v165, 0, v165
	v_min_u32_e32 v165, s40, v165
	v_lshl_or_b32 v165, v165, 7, v221
	global_load_lds_dwordx4 v165, s[20:21]
	s_waitcnt vmcnt(8)
	v_add_u32_e32 v146, s13, v225
	v_add_u32_e32 v147, s13, v226
	v_add_u32_e32 v148, s13, v227
	v_add_u32_e32 v149, s13, v228
	ds_read_b64_tr_b16 v[88:89], v146
	ds_read_b64_tr_b16 v[90:91], v147
	ds_read_b64_tr_b16 v[92:93], v148
	ds_read_b64_tr_b16 v[94:95], v149
	s_waitcnt lgkmcnt(0)
	v_mfma_f32_16x16x16_bf16 v[96:99], v[88:89], v[28:29], v[96:99]
	v_mfma_f32_16x16x16_bf16 v[112:115], v[88:89], v[60:61], v[112:115]
	v_mfma_f32_16x16x16_bf16 v[100:103], v[90:91], v[28:29], v[100:103]
	v_mfma_f32_16x16x16_bf16 v[116:119], v[90:91], v[60:61], v[116:119]
	v_mfma_f32_16x16x16_bf16 v[104:107], v[92:93], v[28:29], v[104:107]
	v_mfma_f32_16x16x16_bf16 v[120:123], v[92:93], v[60:61], v[120:123]
	v_mfma_f32_16x16x16_bf16 v[108:111], v[94:95], v[28:29], v[108:111]
	v_mfma_f32_16x16x16_bf16 v[124:127], v[94:95], v[60:61], v[124:127]
	s_waitcnt lgkmcnt(0)
	s_add_i32 s93, s79, 0xfffffd00
	s_mov_b32 m0, s13
	v_add_u32_e32 v164, s93, v162
	v_max_i32_e32 v164, 0, v164
	v_min_u32_e32 v164, s40, v164
	v_lshl_or_b32 v164, v164, 7, v220
	global_load_lds_dwordx4 v164, s[20:21]
	s_add_i32 m0, s13, 0x400
	v_add_u32_e32 v165, s93, v163
	v_max_i32_e32 v165, 0, v165
	v_min_u32_e32 v165, s40, v165
	v_lshl_or_b32 v165, v165, 7, v221
	global_load_lds_dwordx4 v165, s[20:21]
	s_waitcnt vmcnt(8)
	v_add_u32_e32 v146, s14, v225
	v_add_u32_e32 v147, s14, v226
	v_add_u32_e32 v148, s14, v227
	v_add_u32_e32 v149, s14, v228
	ds_read_b64_tr_b16 v[88:89], v146
	ds_read_b64_tr_b16 v[90:91], v147
	ds_read_b64_tr_b16 v[92:93], v148
	ds_read_b64_tr_b16 v[94:95], v149
	s_waitcnt lgkmcnt(0)
	v_mfma_f32_16x16x16_bf16 v[96:99], v[88:89], v[32:33], v[96:99]
	v_mfma_f32_16x16x16_bf16 v[112:115], v[88:89], v[64:65], v[112:115]
	v_mfma_f32_16x16x16_bf16 v[100:103], v[90:91], v[32:33], v[100:103]
	v_mfma_f32_16x16x16_bf16 v[116:119], v[90:91], v[64:65], v[116:119]
	v_mfma_f32_16x16x16_bf16 v[104:107], v[92:93], v[32:33], v[104:107]
	v_mfma_f32_16x16x16_bf16 v[120:123], v[92:93], v[64:65], v[120:123]
	v_mfma_f32_16x16x16_bf16 v[108:111], v[94:95], v[32:33], v[108:111]
	v_mfma_f32_16x16x16_bf16 v[124:127], v[94:95], v[64:65], v[124:127]
	s_waitcnt lgkmcnt(0)
	s_add_i32 s93, s79, 0xfffffe00
	s_mov_b32 m0, s14
	v_add_u32_e32 v164, s93, v162
	v_max_i32_e32 v164, 0, v164
	v_min_u32_e32 v164, s40, v164
	v_lshl_or_b32 v164, v164, 7, v220
	global_load_lds_dwordx4 v164, s[20:21]
	s_add_i32 m0, s14, 0x400
	v_add_u32_e32 v165, s93, v163
	v_max_i32_e32 v165, 0, v165
	v_min_u32_e32 v165, s40, v165
	v_lshl_or_b32 v165, v165, 7, v221
	global_load_lds_dwordx4 v165, s[20:21]
	s_waitcnt vmcnt(8)
	v_add_u32_e32 v146, s15, v225
	v_add_u32_e32 v147, s15, v226
	v_add_u32_e32 v148, s15, v227
	v_add_u32_e32 v149, s15, v228
	ds_read_b64_tr_b16 v[88:89], v146
	ds_read_b64_tr_b16 v[90:91], v147
	ds_read_b64_tr_b16 v[92:93], v148
	ds_read_b64_tr_b16 v[94:95], v149
	s_waitcnt lgkmcnt(0)
	v_mfma_f32_16x16x16_bf16 v[112:115], v[88:89], v[68:69], v[112:115]
	v_mfma_f32_16x16x16_bf16 v[116:119], v[90:91], v[68:69], v[116:119]
	v_mfma_f32_16x16x16_bf16 v[120:123], v[92:93], v[68:69], v[120:123]
	v_mfma_f32_16x16x16_bf16 v[124:127], v[94:95], v[68:69], v[124:127]
	s_waitcnt lgkmcnt(0)
	v_max_f32_e32 v146, v144, v184
	v_sub_f32_e32 v148, v144, v146
	v_sub_f32_e32 v150, v184, v146
	v_exp_f32_e32 v148, v148
	v_exp_f32_e32 v150, v150
	v_mov_b32_e32 v184, v146
	v_mul_f32_e32 v185, v185, v150
	v_fmac_f32_e32 v185, v145, v148
	v_pk_mul_f32 v[96:97], v[150:151], v[96:97] op_sel_hi:[0,1]
	v_pk_mul_f32 v[98:99], v[150:151], v[98:99] op_sel_hi:[0,1]
	v_pk_mul_f32 v[100:101], v[150:151], v[100:101] op_sel_hi:[0,1]
	v_pk_mul_f32 v[102:103], v[150:151], v[102:103] op_sel_hi:[0,1]
	v_pk_mul_f32 v[104:105], v[150:151], v[104:105] op_sel_hi:[0,1]
	v_pk_mul_f32 v[106:107], v[150:151], v[106:107] op_sel_hi:[0,1]
	v_pk_mul_f32 v[108:109], v[150:151], v[108:109] op_sel_hi:[0,1]
	v_pk_mul_f32 v[110:111], v[150:151], v[110:111] op_sel_hi:[0,1]
	v_pk_fma_f32 v[96:97], v[148:149], v[128:129], v[96:97] op_sel_hi:[0,1,1]
	v_pk_fma_f32 v[98:99], v[148:149], v[130:131], v[98:99] op_sel_hi:[0,1,1]
	v_pk_fma_f32 v[100:101], v[148:149], v[132:133], v[100:101] op_sel_hi:[0,1,1]
	v_pk_fma_f32 v[102:103], v[148:149], v[134:135], v[102:103] op_sel_hi:[0,1,1]
	v_pk_fma_f32 v[104:105], v[148:149], v[136:137], v[104:105] op_sel_hi:[0,1,1]
	v_pk_fma_f32 v[106:107], v[148:149], v[138:139], v[106:107] op_sel_hi:[0,1,1]
	v_pk_fma_f32 v[108:109], v[148:149], v[140:141], v[108:109] op_sel_hi:[0,1,1]
	v_pk_fma_f32 v[110:111], v[148:149], v[142:143], v[110:111] op_sel_hi:[0,1,1]
	s_and_saveexec_b64 s[80:81], s[74:75]
	ds_write_b64 v194, v[184:185]
	s_mov_b64 exec, s[80:81]
	ds_write_b128 v190, v[96:99]
	ds_write_b128 v191, v[100:103]
	ds_write_b128 v192, v[104:107]
	ds_write_b128 v193, v[108:111]
	s_waitcnt lgkmcnt(0)
	v_max_f32_e32 v146, v182, v186
	v_sub_f32_e32 v148, v182, v146
	v_sub_f32_e32 v150, v186, v146
	v_exp_f32_e32 v148, v148
	v_exp_f32_e32 v150, v150
	v_mov_b32_e32 v186, v146
	v_mul_f32_e32 v187, v187, v150
	v_fmac_f32_e32 v187, v183, v148
	v_pk_mul_f32 v[112:113], v[150:151], v[112:113] op_sel_hi:[0,1]
	v_pk_mul_f32 v[114:115], v[150:151], v[114:115] op_sel_hi:[0,1]
	v_pk_mul_f32 v[116:117], v[150:151], v[116:117] op_sel_hi:[0,1]
	v_pk_mul_f32 v[118:119], v[150:151], v[118:119] op_sel_hi:[0,1]
	v_pk_mul_f32 v[120:121], v[150:151], v[120:121] op_sel_hi:[0,1]
	v_pk_mul_f32 v[122:123], v[150:151], v[122:123] op_sel_hi:[0,1]
	v_pk_mul_f32 v[124:125], v[150:151], v[124:125] op_sel_hi:[0,1]
	v_pk_mul_f32 v[126:127], v[150:151], v[126:127] op_sel_hi:[0,1]
	v_pk_fma_f32 v[112:113], v[148:149], v[166:167], v[112:113] op_sel_hi:[0,1,1]
	v_pk_fma_f32 v[114:115], v[148:149], v[168:169], v[114:115] op_sel_hi:[0,1,1]
	v_pk_fma_f32 v[116:117], v[148:149], v[170:171], v[116:117] op_sel_hi:[0,1,1]
	v_pk_fma_f32 v[118:119], v[148:149], v[172:173], v[118:119] op_sel_hi:[0,1,1]
	v_pk_fma_f32 v[120:121], v[148:149], v[174:175], v[120:121] op_sel_hi:[0,1,1]
	v_pk_fma_f32 v[122:123], v[148:149], v[176:177], v[122:123] op_sel_hi:[0,1,1]
	v_pk_fma_f32 v[124:125], v[148:149], v[178:179], v[124:125] op_sel_hi:[0,1,1]
	v_pk_fma_f32 v[126:127], v[148:149], v[180:181], v[126:127] op_sel_hi:[0,1,1]
	s_and_saveexec_b64 s[80:81], s[74:75]
	ds_write_b64 v199, v[186:187]
	s_mov_b64 exec, s[80:81]
	ds_write_b128 v195, v[112:115]
	ds_write_b128 v196, v[116:119]
	ds_write_b128 v197, v[120:123]
	ds_write_b128 v198, v[124:127]
	s_waitcnt lgkmcnt(0)
	s_barrier
	s_add_i32 s76, s38, s84
	s_add_i32 s79, s38, s85
	v_lshlrev_b32_e32 v231, 4, v218
	v_add_u32_e32 v232, 8, v218
	v_lshlrev_b32_e32 v232, 4, v232
	s_waitcnt lgkmcnt(0)
	s_add_i32 s93, s76, 0xffffff00
	s_mov_b32 m0, s15
	v_add_u32_e32 v164, s93, v231
	v_max_i32_e32 v164, 0, v164
	v_min_u32_e32 v164, s40, v164
	v_lshl_or_b32 v164, v164, 7, v220
	global_load_lds_dwordx4 v164, s[20:21]
	s_add_i32 m0, s15, 0x400
	v_add_u32_e32 v165, s93, v232
	v_max_i32_e32 v165, 0, v165
	v_min_u32_e32 v165, s40, v165
	v_lshl_or_b32 v165, v165, 7, v221
	global_load_lds_dwordx4 v165, s[20:21]
	s_waitcnt vmcnt(8)
	v_add_u32_e32 v146, s16, v223
	v_add_u32_e32 v147, s16, v224
	ds_read_b128 v[72:75], v146
	ds_read_b128 v[76:79], v147
	s_waitcnt lgkmcnt(0)
	s_add_i32 s93, s76, 0
	s_mov_b32 m0, s16
	v_add_u32_e32 v164, s93, v231
	v_max_i32_e32 v164, 0, v164
	v_min_u32_e32 v164, s40, v164
	v_lshl_or_b32 v164, v164, 7, v220
	global_load_lds_dwordx4 v164, s[20:21]
	s_add_i32 m0, s16, 0x400
	v_add_u32_e32 v165, s93, v232
	v_max_i32_e32 v165, 0, v165
	v_min_u32_e32 v165, s40, v165
	v_lshl_or_b32 v165, v165, 7, v221
	global_load_lds_dwordx4 v165, s[20:21]
	s_waitcnt vmcnt(8)
	v_add_u32_e32 v146, s12, v223
	v_add_u32_e32 v147, s12, v224
	ds_read_b128 v[88:91], v146
	ds_read_b128 v[92:95], v147
	s_waitcnt lgkmcnt(0)
	v_mfma_f32_16x16x32_bf16 v[0:3], v[88:91], v[72:75], 0
	v_mfma_f32_16x16x32_bf16 v[0:3], v[92:95], v[76:79], v[0:3]
	s_waitcnt lgkmcnt(0)
	s_add_i32 s93, s76, 0x100
	s_mov_b32 m0, s12
	v_add_u32_e32 v164, s93, v231
	v_max_i32_e32 v164, 0, v164
	v_min_u32_e32 v164, s40, v164
	v_lshl_or_b32 v164, v164, 7, v220
	global_load_lds_dwordx4 v164, s[20:21]
	s_add_i32 m0, s12, 0x400
	v_add_u32_e32 v165, s93, v232
	v_max_i32_e32 v165, 0, v165
	v_min_u32_e32 v165, s40, v165
	v_lshl_or_b32 v165, v165, 7, v221
	global_load_lds_dwordx4 v165, s[20:21]
	s_waitcnt vmcnt(8)
	v_add_u32_e32 v146, s13, v223
	v_add_u32_e32 v147, s13, v224
	ds_read_b128 v[88:91], v146
	ds_read_b128 v[92:95], v147
	s_waitcnt lgkmcnt(0)
	v_mfma_f32_16x16x32_bf16 v[4:7], v[88:91], v[72:75], 0
	v_mfma_f32_16x16x32_bf16 v[4:7], v[92:95], v[76:79], v[4:7]
	s_waitcnt lgkmcnt(0)
	s_add_i32 s93, s76, 0x200
	s_mov_b32 m0, s13
	v_add_u32_e32 v164, s93, v231
	v_max_i32_e32 v164, 0, v164
	v_min_u32_e32 v164, s40, v164
	v_lshl_or_b32 v164, v164, 7, v220
	global_load_lds_dwordx4 v164, s[20:21]
	s_add_i32 m0, s13, 0x400
	v_add_u32_e32 v165, s93, v232
	v_max_i32_e32 v165, 0, v165
	v_min_u32_e32 v165, s40, v165
	v_lshl_or_b32 v165, v165, 7, v221
	global_load_lds_dwordx4 v165, s[20:21]
	s_waitcnt vmcnt(8)
	v_add_u32_e32 v146, s14, v223
	v_add_u32_e32 v147, s14, v224
	ds_read_b128 v[88:91], v146
	ds_read_b128 v[92:95], v147
	s_waitcnt lgkmcnt(0)
	v_mfma_f32_16x16x32_bf16 v[8:11], v[88:91], v[72:75], 0
	v_mfma_f32_16x16x32_bf16 v[8:11], v[92:95], v[76:79], v[8:11]
	s_waitcnt lgkmcnt(0)
	s_add_i32 s93, s76, 0x300
	s_mov_b32 m0, s14
	v_add_u32_e32 v164, s93, v231
	v_max_i32_e32 v164, 0, v164
	v_min_u32_e32 v164, s40, v164
	v_lshl_or_b32 v164, v164, 7, v220
	global_load_lds_dwordx4 v164, s[20:21]
	s_add_i32 m0, s14, 0x400
	v_add_u32_e32 v165, s93, v232
	v_max_i32_e32 v165, 0, v165
	v_min_u32_e32 v165, s40, v165
	v_lshl_or_b32 v165, v165, 7, v221
	global_load_lds_dwordx4 v165, s[20:21]
	s_waitcnt vmcnt(8)
	v_add_u32_e32 v146, s15, v223
	v_add_u32_e32 v147, s15, v224
	ds_read_b128 v[88:91], v146
	ds_read_b128 v[92:95], v147
	s_waitcnt lgkmcnt(0)
	v_mfma_f32_16x16x32_bf16 v[12:15], v[88:91], v[72:75], 0
	v_mfma_f32_16x16x32_bf16 v[12:15], v[92:95], v[76:79], v[12:15]
	s_waitcnt lgkmcnt(0)
	s_add_i32 s93, s76, 0x400
	s_mov_b32 m0, s15
	v_add_u32_e32 v164, s93, v231
	v_max_i32_e32 v164, 0, v164
	v_min_u32_e32 v164, s40, v164
	v_lshl_or_b32 v164, v164, 7, v220
	global_load_lds_dwordx4 v164, s[20:21]
	s_add_i32 m0, s15, 0x400
	v_add_u32_e32 v165, s93, v232
	v_max_i32_e32 v165, 0, v165
	v_min_u32_e32 v165, s40, v165
	v_lshl_or_b32 v165, v165, 7, v221
	global_load_lds_dwordx4 v165, s[20:21]
	s_waitcnt vmcnt(8)
	v_add_u32_e32 v146, s16, v223
	v_add_u32_e32 v147, s16, v224
	ds_read_b128 v[88:91], v146
	ds_read_b128 v[92:95], v147
	s_waitcnt lgkmcnt(0)
	v_mfma_f32_16x16x32_bf16 v[16:19], v[88:91], v[72:75], 0
	v_mfma_f32_16x16x32_bf16 v[16:19], v[92:95], v[76:79], v[16:19]
	s_waitcnt lgkmcnt(0)
	s_add_i32 s93, s76, 0xfffffc00
	s_mov_b32 m0, s16
	v_add_u32_e32 v164, s93, v231
	v_max_i32_e32 v164, 0, v164
	v_min_u32_e32 v164, s40, v164
	v_lshl_or_b32 v164, v164, 7, v222
	global_load_lds_dwordx4 v164, s[24:25]
	s_add_i32 m0, s16, 0x400
	v_add_u32_e32 v165, s93, v232
	v_max_i32_e32 v165, 0, v165
	v_min_u32_e32 v165, s40, v165
	v_lshl_or_b32 v165, v165, 7, v222
	global_load_lds_dwordx4 v165, s[24:25]
	s_waitcnt vmcnt(8)
	v_add_u32_e32 v146, s12, v223
	v_add_u32_e32 v147, s12, v224
	ds_read_b128 v[88:91], v146
	ds_read_b128 v[92:95], v147
	s_waitcnt lgkmcnt(0)
	v_mfma_f32_16x16x32_bf16 v[20:23], v[88:91], v[72:75], 0
	v_mfma_f32_16x16x32_bf16 v[20:23], v[92:95], v[76:79], v[20:23]
	s_waitcnt lgkmcnt(0)
	s_add_i32 s93, s76, 0xfffffd00
	s_mov_b32 m0, s12
	v_add_u32_e32 v164, s93, v231
	v_max_i32_e32 v164, 0, v164
	v_min_u32_e32 v164, s40, v164
	v_lshl_or_b32 v164, v164, 7, v222
	global_load_lds_dwordx4 v164, s[24:25]
	s_add_i32 m0, s12, 0x400
	v_add_u32_e32 v165, s93, v232
	v_max_i32_e32 v165, 0, v165
	v_min_u32_e32 v165, s40, v165
	v_lshl_or_b32 v165, v165, 7, v222
	global_load_lds_dwordx4 v165, s[24:25]
	s_waitcnt vmcnt(8)
	v_add_u32_e32 v146, s13, v223
	v_add_u32_e32 v147, s13, v224
	ds_read_b128 v[88:91], v146
	ds_read_b128 v[92:95], v147
	s_waitcnt lgkmcnt(0)
	v_mfma_f32_16x16x32_bf16 v[24:27], v[88:91], v[72:75], 0
	v_mfma_f32_16x16x32_bf16 v[24:27], v[92:95], v[76:79], v[24:27]
	s_waitcnt lgkmcnt(0)
	s_add_i32 s93, s76, 0xfffffe00
	s_mov_b32 m0, s13
	v_add_u32_e32 v164, s93, v231
	v_max_i32_e32 v164, 0, v164
	v_min_u32_e32 v164, s40, v164
	v_lshl_or_b32 v164, v164, 7, v222
	global_load_lds_dwordx4 v164, s[24:25]
	s_add_i32 m0, s13, 0x400
	v_add_u32_e32 v165, s93, v232
	v_max_i32_e32 v165, 0, v165
	v_min_u32_e32 v165, s40, v165
	v_lshl_or_b32 v165, v165, 7, v222
	global_load_lds_dwordx4 v165, s[24:25]
	s_waitcnt vmcnt(8)
	v_add_u32_e32 v146, s14, v223
	v_add_u32_e32 v147, s14, v224
	ds_read_b128 v[88:91], v146
	ds_read_b128 v[92:95], v147
	s_waitcnt lgkmcnt(0)
	v_mfma_f32_16x16x32_bf16 v[28:31], v[88:91], v[72:75], 0
	v_mfma_f32_16x16x32_bf16 v[28:31], v[92:95], v[76:79], v[28:31]
	s_waitcnt lgkmcnt(0)
	s_add_i32 s93, s76, 0xffffff00
	s_mov_b32 m0, s14
	v_add_u32_e32 v164, s93, v231
	v_max_i32_e32 v164, 0, v164
	v_min_u32_e32 v164, s40, v164
	v_lshl_or_b32 v164, v164, 7, v222
	global_load_lds_dwordx4 v164, s[24:25]
	s_add_i32 m0, s14, 0x400
	v_add_u32_e32 v165, s93, v232
	v_max_i32_e32 v165, 0, v165
	v_min_u32_e32 v165, s40, v165
	v_lshl_or_b32 v165, v165, 7, v222
	global_load_lds_dwordx4 v165, s[24:25]
	s_waitcnt vmcnt(8)
	v_add_u32_e32 v146, s15, v223
	v_add_u32_e32 v147, s15, v224
	ds_read_b128 v[88:91], v146
	ds_read_b128 v[92:95], v147
	s_waitcnt lgkmcnt(0)
	v_mfma_f32_16x16x32_bf16 v[32:35], v[88:91], v[72:75], 0
	v_mfma_f32_16x16x32_bf16 v[32:35], v[92:95], v[76:79], v[32:35]
	v_mov_b32_e32 v188, s84
	v_lshl_add_u32 v188, v216, 4, v188
	v_lshrrev_b32_e32 v146, 4, v188
	v_xor_b32_e32 v146, v146, v188
	v_and_b32_e32 v146, 15, v146
	v_lshlrev_b32_e32 v147, 8, v188
	v_or_b32_e32 v148, 0, v217
	v_xor_b32_e32 v148, v148, v146
	v_lshl_add_u32 v190, v148, 4, v147
	v_or_b32_e32 v148, 4, v217
	v_xor_b32_e32 v148, v148, v146
	v_lshl_add_u32 v191, v148, 4, v147
	v_or_b32_e32 v148, 8, v217
	v_xor_b32_e32 v148, v148, v146
	v_lshl_add_u32 v192, v148, 4, v147
	v_or_b32_e32 v148, 12, v217
	v_xor_b32_e32 v148, v148, v146
	v_lshl_add_u32 v193, v148, 4, v147
	v_lshlrev_b32_e32 v194, 3, v188
	v_add_u32_e32 v194, 0x10000, v194
	ds_read_b64 v[144:145], v194
	ds_read_b128 v[128:131], v190
	ds_read_b128 v[132:135], v191
	ds_read_b128 v[136:139], v192
	ds_read_b128 v[140:143], v193
	s_add_i32 s90, s76, 0x4f0
	s_cmp_gt_i32 s90, s40
	s_cselect_b32 s96, 1, 0
	s_cmp_lt_i32 s76, 0x400
	s_cselect_b32 s96, 1, s96
	s_ashr_i32 s77, s76, 4
	s_sub_i32 s77, 64, s77
	s_sub_i32 s78, s40, s76
	s_ashr_i32 s78, s78, 4
	s_add_i32 s78, s78, 64
	v_cndmask_b32_e64 v0, v0, v230, s[52:53]
	v_cndmask_b32_e64 v32, v32, v230, s[62:63]
	v_cndmask_b32_e64 v1, v1, v230, s[56:57]
	v_cndmask_b32_e64 v33, v33, v230, s[64:65]
	v_cndmask_b32_e64 v2, v2, v230, s[58:59]
	v_cndmask_b32_e64 v34, v34, v230, s[70:71]
	v_cndmask_b32_e64 v3, v3, v230, s[60:61]
	v_cndmask_b32_e64 v35, v35, v230, s[72:73]
	s_cmp_eq_u32 s96, 0
	s_cbranch_scc1 .Latt_noedge_5
	v_sub_u32_e32 v200, s77, v229
	s_sub_i32 s91, s78, s77
	v_sub_u32_e32 v150, 0, v200
	v_sub_u32_e32 v151, 1, v200
	v_sub_u32_e32 v152, 2, v200
	v_sub_u32_e32 v153, 3, v200
	v_cmp_lt_u32_e64 s[94:95], s91, v150
	v_cmp_lt_u32_e64 s[86:87], s91, v151
	v_cmp_lt_u32_e64 s[0:1], s91, v152
	v_cmp_lt_u32_e64 s[2:3], s91, v153
	v_cndmask_b32_e64 v0, v0, v230, s[94:95]
	v_cndmask_b32_e64 v1, v1, v230, s[86:87]
	v_cndmask_b32_e64 v2, v2, v230, s[0:1]
	v_cndmask_b32_e64 v3, v3, v230, s[2:3]
	v_sub_u32_e32 v150, 16, v200
	v_sub_u32_e32 v151, 17, v200
	v_sub_u32_e32 v152, 18, v200
	v_sub_u32_e32 v153, 19, v200
	v_cmp_lt_u32_e64 s[94:95], s91, v150
	v_cmp_lt_u32_e64 s[86:87], s91, v151
	v_cmp_lt_u32_e64 s[0:1], s91, v152
	v_cmp_lt_u32_e64 s[2:3], s91, v153
	v_cndmask_b32_e64 v4, v4, v230, s[94:95]
	v_cndmask_b32_e64 v5, v5, v230, s[86:87]
	v_cndmask_b32_e64 v6, v6, v230, s[0:1]
	v_cndmask_b32_e64 v7, v7, v230, s[2:3]
	v_sub_u32_e32 v150, 32, v200
	v_sub_u32_e32 v151, 33, v200
	v_sub_u32_e32 v152, 34, v200
	v_sub_u32_e32 v153, 35, v200
	v_cmp_lt_u32_e64 s[94:95], s91, v150
	v_cmp_lt_u32_e64 s[86:87], s91, v151
	v_cmp_lt_u32_e64 s[0:1], s91, v152
	v_cmp_lt_u32_e64 s[2:3], s91, v153
	v_cndmask_b32_e64 v8, v8, v230, s[94:95]
	v_cndmask_b32_e64 v9, v9, v230, s[86:87]
	v_cndmask_b32_e64 v10, v10, v230, s[0:1]
	v_cndmask_b32_e64 v11, v11, v230, s[2:3]
	v_sub_u32_e32 v150, 48, v200
	v_sub_u32_e32 v151, 49, v200
	v_sub_u32_e32 v152, 50, v200
	v_sub_u32_e32 v153, 51, v200
	v_cmp_lt_u32_e64 s[94:95], s91, v150
	v_cmp_lt_u32_e64 s[86:87], s91, v151
	v_cmp_lt_u32_e64 s[0:1], s91, v152
	v_cmp_lt_u32_e64 s[2:3], s91, v153
	v_cndmask_b32_e64 v12, v12, v230, s[94:95]
	v_cndmask_b32_e64 v13, v13, v230, s[86:87]
	v_cndmask_b32_e64 v14, v14, v230, s[0:1]
	v_cndmask_b32_e64 v15, v15, v230, s[2:3]
	v_sub_u32_e32 v150, 64, v200
	v_sub_u32_e32 v151, 0x41, v200
	v_sub_u32_e32 v152, 0x42, v200
	v_sub_u32_e32 v153, 0x43, v200
	v_cmp_lt_u32_e64 s[94:95], s91, v150
	v_cmp_lt_u32_e64 s[86:87], s91, v151
	v_cmp_lt_u32_e64 s[0:1], s91, v152
	v_cmp_lt_u32_e64 s[2:3], s91, v153
	v_cndmask_b32_e64 v16, v16, v230, s[94:95]
	v_cndmask_b32_e64 v17, v17, v230, s[86:87]
	v_cndmask_b32_e64 v18, v18, v230, s[0:1]
	v_cndmask_b32_e64 v19, v19, v230, s[2:3]
	v_sub_u32_e32 v150, 0x50, v200
	v_sub_u32_e32 v151, 0x51, v200
	v_sub_u32_e32 v152, 0x52, v200
	v_sub_u32_e32 v153, 0x53, v200
	v_cmp_lt_u32_e64 s[94:95], s91, v150
	v_cmp_lt_u32_e64 s[86:87], s91, v151
	v_cmp_lt_u32_e64 s[0:1], s91, v152
	v_cmp_lt_u32_e64 s[2:3], s91, v153
	v_cndmask_b32_e64 v20, v20, v230, s[94:95]
	v_cndmask_b32_e64 v21, v21, v230, s[86:87]
	v_cndmask_b32_e64 v22, v22, v230, s[0:1]
	v_cndmask_b32_e64 v23, v23, v230, s[2:3]
	v_sub_u32_e32 v150, 0x60, v200
	v_sub_u32_e32 v151, 0x61, v200
	v_sub_u32_e32 v152, 0x62, v200
	v_sub_u32_e32 v153, 0x63, v200
	v_cmp_lt_u32_e64 s[94:95], s91, v150
	v_cmp_lt_u32_e64 s[86:87], s91, v151
	v_cmp_lt_u32_e64 s[0:1], s91, v152
	v_cmp_lt_u32_e64 s[2:3], s91, v153
	v_cndmask_b32_e64 v24, v24, v230, s[94:95]
	v_cndmask_b32_e64 v25, v25, v230, s[86:87]
	v_cndmask_b32_e64 v26, v26, v230, s[0:1]
	v_cndmask_b32_e64 v27, v27, v230, s[2:3]
	v_sub_u32_e32 v150, 0x70, v200
	v_sub_u32_e32 v151, 0x71, v200
	v_sub_u32_e32 v152, 0x72, v200
	v_sub_u32_e32 v153, 0x73, v200
	v_cmp_lt_u32_e64 s[94:95], s91, v150
	v_cmp_lt_u32_e64 s[86:87], s91, v151
	v_cmp_lt_u32_e64 s[0:1], s91, v152
	v_cmp_lt_u32_e64 s[2:3], s91, v153
	v_cndmask_b32_e64 v28, v28, v230, s[94:95]
	v_cndmask_b32_e64 v29, v29, v230, s[86:87]
	v_cndmask_b32_e64 v30, v30, v230, s[0:1]
	v_cndmask_b32_e64 v31, v31, v230, s[2:3]
	v_sub_u32_e32 v150, 0x80, v200
	v_sub_u32_e32 v151, 0x81, v200
	v_sub_u32_e32 v152, 0x82, v200
	v_sub_u32_e32 v153, 0x83, v200
	v_cmp_lt_u32_e64 s[94:95], s91, v150
	v_cmp_lt_u32_e64 s[86:87], s91, v151
	v_cmp_lt_u32_e64 s[0:1], s91, v152
	v_cmp_lt_u32_e64 s[2:3], s91, v153
	v_cndmask_b32_e64 v32, v32, v230, s[94:95]
	v_cndmask_b32_e64 v33, v33, v230, s[86:87]
	v_cndmask_b32_e64 v34, v34, v230, s[0:1]
	v_cndmask_b32_e64 v35, v35, v230, s[2:3]
.Latt_noedge_5:
	s_nop 1
	v_max3_f32 v184, v0, v1, v2
	v_max3_f32 v184, v184, v3, v4
	v_max3_f32 v184, v184, v5, v6
	v_max3_f32 v184, v184, v7, v8
	v_max3_f32 v184, v184, v9, v10
	v_max3_f32 v184, v184, v11, v12
	v_max3_f32 v184, v184, v13, v14
	v_max3_f32 v184, v184, v15, v16
	v_max3_f32 v184, v184, v17, v18
	v_max3_f32 v184, v184, v19, v20
	v_max3_f32 v184, v184, v21, v22
	v_max3_f32 v184, v184, v23, v24
	v_max3_f32 v184, v184, v25, v26
	v_max3_f32 v184, v184, v27, v28
	v_max3_f32 v184, v184, v29, v30
	v_max3_f32 v184, v184, v31, v32
	v_max3_f32 v184, v184, v33, v34
	v_max_f32_e32 v184, v184, v35
	v_mov_b32_e32 v146, v184
	s_nop 1
	v_permlane16_swap_b32_e32 v184, v146
	v_max_f32_e32 v184, v184, v146
	v_mov_b32_e32 v146, v184
	s_nop 1
	v_permlane32_swap_b32_e32 v184, v146
	v_max_f32_e32 v184, v184, v146
	v_sub_f32_e32 v0, v0, v184
	v_sub_f32_e32 v1, v1, v184
	v_sub_f32_e32 v2, v2, v184
	v_sub_f32_e32 v3, v3, v184
	v_exp_f32_e32 v0, v0
	v_exp_f32_e32 v1, v1
	v_exp_f32_e32 v2, v2
	v_exp_f32_e32 v3, v3
	v_sub_f32_e32 v4, v4, v184
	v_sub_f32_e32 v5, v5, v184
	v_sub_f32_e32 v6, v6, v184
	v_sub_f32_e32 v7, v7, v184
	v_exp_f32_e32 v4, v4
	v_exp_f32_e32 v5, v5
	v_exp_f32_e32 v6, v6
	v_exp_f32_e32 v7, v7
	v_sub_f32_e32 v8, v8, v184
	v_sub_f32_e32 v9, v9, v184
	v_sub_f32_e32 v10, v10, v184
	v_sub_f32_e32 v11, v11, v184
	v_exp_f32_e32 v8, v8
	v_exp_f32_e32 v9, v9
	v_exp_f32_e32 v10, v10
	v_exp_f32_e32 v11, v11
	v_sub_f32_e32 v12, v12, v184
	v_sub_f32_e32 v13, v13, v184
	v_sub_f32_e32 v14, v14, v184
	v_sub_f32_e32 v15, v15, v184
	v_exp_f32_e32 v12, v12
	v_exp_f32_e32 v13, v13
	v_exp_f32_e32 v14, v14
	v_exp_f32_e32 v15, v15
	v_sub_f32_e32 v16, v16, v184
	v_sub_f32_e32 v17, v17, v184
	v_sub_f32_e32 v18, v18, v184
	v_sub_f32_e32 v19, v19, v184
	v_exp_f32_e32 v16, v16
	v_exp_f32_e32 v17, v17
	v_exp_f32_e32 v18, v18
	v_exp_f32_e32 v19, v19
	v_sub_f32_e32 v20, v20, v184
	v_sub_f32_e32 v21, v21, v184
	v_sub_f32_e32 v22, v22, v184
	v_sub_f32_e32 v23, v23, v184
	v_exp_f32_e32 v20, v20
	v_exp_f32_e32 v21, v21
	v_exp_f32_e32 v22, v22
	v_exp_f32_e32 v23, v23
	v_sub_f32_e32 v24, v24, v184
	v_sub_f32_e32 v25, v25, v184
	v_sub_f32_e32 v26, v26, v184
	v_sub_f32_e32 v27, v27, v184
	v_exp_f32_e32 v24, v24
	v_exp_f32_e32 v25, v25
	v_exp_f32_e32 v26, v26
	v_exp_f32_e32 v27, v27
	v_sub_f32_e32 v28, v28, v184
	v_sub_f32_e32 v29, v29, v184
	v_sub_f32_e32 v30, v30, v184
	v_sub_f32_e32 v31, v31, v184
	v_exp_f32_e32 v28, v28
	v_exp_f32_e32 v29, v29
	v_exp_f32_e32 v30, v30
	v_exp_f32_e32 v31, v31
	v_sub_f32_e32 v32, v32, v184
	v_sub_f32_e32 v33, v33, v184
	v_sub_f32_e32 v34, v34, v184
	v_sub_f32_e32 v35, v35, v184
	v_exp_f32_e32 v32, v32
	v_exp_f32_e32 v33, v33
	v_exp_f32_e32 v34, v34
	v_exp_f32_e32 v35, v35
	s_nop 0
	v_add_f32_e32 v185, v0, v1
	v_add_f32_e32 v185, v185, v2
	v_add_f32_e32 v185, v185, v3
	v_add_f32_e32 v185, v185, v4
	v_add_f32_e32 v185, v185, v5
	v_add_f32_e32 v185, v185, v6
	v_add_f32_e32 v185, v185, v7
	v_add_f32_e32 v185, v185, v8
	v_add_f32_e32 v185, v185, v9
	v_add_f32_e32 v185, v185, v10
	v_add_f32_e32 v185, v185, v11
	v_add_f32_e32 v185, v185, v12
	v_add_f32_e32 v185, v185, v13
	v_add_f32_e32 v185, v185, v14
	v_add_f32_e32 v185, v185, v15
	v_add_f32_e32 v185, v185, v16
	v_add_f32_e32 v185, v185, v17
	v_add_f32_e32 v185, v185, v18
	v_add_f32_e32 v185, v185, v19
	v_add_f32_e32 v185, v185, v20
	v_add_f32_e32 v185, v185, v21
	v_add_f32_e32 v185, v185, v22
	v_add_f32_e32 v185, v185, v23
	v_add_f32_e32 v185, v185, v24
	v_add_f32_e32 v185, v185, v25
	v_add_f32_e32 v185, v185, v26
	v_add_f32_e32 v185, v185, v27
	v_add_f32_e32 v185, v185, v28
	v_add_f32_e32 v185, v185, v29
	v_add_f32_e32 v185, v185, v30
	v_add_f32_e32 v185, v185, v31
	v_add_f32_e32 v185, v185, v32
	v_add_f32_e32 v185, v185, v33
	v_add_f32_e32 v185, v185, v34
	v_add_f32_e32 v185, v185, v35
	v_cvt_pk_bf16_f32 v0, v0, v1
	v_cvt_pk_bf16_f32 v1, v2, v3
	v_cvt_pk_bf16_f32 v4, v4, v5
	v_cvt_pk_bf16_f32 v5, v6, v7
	v_cvt_pk_bf16_f32 v8, v8, v9
	v_cvt_pk_bf16_f32 v9, v10, v11
	v_cvt_pk_bf16_f32 v12, v12, v13
	v_cvt_pk_bf16_f32 v13, v14, v15
	v_cvt_pk_bf16_f32 v16, v16, v17
	v_cvt_pk_bf16_f32 v17, v18, v19
	v_cvt_pk_bf16_f32 v20, v20, v21
	v_cvt_pk_bf16_f32 v21, v22, v23
	v_cvt_pk_bf16_f32 v24, v24, v25
	v_cvt_pk_bf16_f32 v25, v26, v27
	v_cvt_pk_bf16_f32 v28, v28, v29
	v_cvt_pk_bf16_f32 v29, v30, v31
	v_cvt_pk_bf16_f32 v32, v32, v33
	v_cvt_pk_bf16_f32 v33, v34, v35
	v_mov_b32_e32 v146, v185
	s_nop 1
	v_permlane16_swap_b32_e32 v185, v146
	v_add_f32_e32 v185, v185, v146
	v_mov_b32_e32 v146, v185
	s_nop 1
	v_permlane32_swap_b32_e32 v185, v146
	v_add_f32_e32 v185, v185, v146
	s_waitcnt lgkmcnt(0)
	s_add_i32 s93, s76, 0
	s_mov_b32 m0, s15
	v_add_u32_e32 v164, s93, v231
	v_max_i32_e32 v164, 0, v164
	v_min_u32_e32 v164, s40, v164
	v_lshl_or_b32 v164, v164, 7, v222
	global_load_lds_dwordx4 v164, s[24:25]
	s_add_i32 m0, s15, 0x400
	v_add_u32_e32 v165, s93, v232
	v_max_i32_e32 v165, 0, v165
	v_min_u32_e32 v165, s40, v165
	v_lshl_or_b32 v165, v165, 7, v222
	global_load_lds_dwordx4 v165, s[24:25]
	s_waitcnt vmcnt(8)
	v_add_u32_e32 v146, s16, v225
	v_add_u32_e32 v147, s16, v226
	v_add_u32_e32 v148, s16, v227
	v_add_u32_e32 v149, s16, v228
	ds_read_b64_tr_b16 v[88:89], v146
	ds_read_b64_tr_b16 v[90:91], v147
	ds_read_b64_tr_b16 v[92:93], v148
	ds_read_b64_tr_b16 v[94:95], v149
	s_waitcnt lgkmcnt(0)
	v_mfma_f32_16x16x16_bf16 v[96:99], v[88:89], v[0:1], 0
	v_mfma_f32_16x16x16_bf16 v[100:103], v[90:91], v[0:1], 0
	v_mfma_f32_16x16x16_bf16 v[104:107], v[92:93], v[0:1], 0
	v_mfma_f32_16x16x16_bf16 v[108:111], v[94:95], v[0:1], 0
	s_waitcnt lgkmcnt(0)
	s_add_i32 s93, s76, 0x100
	s_mov_b32 m0, s16
	v_add_u32_e32 v164, s93, v231
	v_max_i32_e32 v164, 0, v164
	v_min_u32_e32 v164, s40, v164
	v_lshl_or_b32 v164, v164, 7, v222
	global_load_lds_dwordx4 v164, s[24:25]
	s_add_i32 m0, s16, 0x400
	v_add_u32_e32 v165, s93, v232
	v_max_i32_e32 v165, 0, v165
	v_min_u32_e32 v165, s40, v165
	v_lshl_or_b32 v165, v165, 7, v222
	global_load_lds_dwordx4 v165, s[24:25]
	s_waitcnt vmcnt(8)
	v_add_u32_e32 v146, s12, v225
	v_add_u32_e32 v147, s12, v226
	v_add_u32_e32 v148, s12, v227
	v_add_u32_e32 v149, s12, v228
	ds_read_b64_tr_b16 v[88:89], v146
	ds_read_b64_tr_b16 v[90:91], v147
	ds_read_b64_tr_b16 v[92:93], v148
	ds_read_b64_tr_b16 v[94:95], v149
	s_waitcnt lgkmcnt(0)
	v_mfma_f32_16x16x16_bf16 v[96:99], v[88:89], v[4:5], v[96:99]
	v_mfma_f32_16x16x16_bf16 v[100:103], v[90:91], v[4:5], v[100:103]
	v_mfma_f32_16x16x16_bf16 v[104:107], v[92:93], v[4:5], v[104:107]
	v_mfma_f32_16x16x16_bf16 v[108:111], v[94:95], v[4:5], v[108:111]
	s_waitcnt lgkmcnt(0)
	s_add_i32 s93, s76, 0x200
	s_mov_b32 m0, s12
	v_add_u32_e32 v164, s93, v231
	v_max_i32_e32 v164, 0, v164
	v_min_u32_e32 v164, s40, v164
	v_lshl_or_b32 v164, v164, 7, v222
	global_load_lds_dwordx4 v164, s[24:25]
	s_add_i32 m0, s12, 0x400
	v_add_u32_e32 v165, s93, v232
	v_max_i32_e32 v165, 0, v165
	v_min_u32_e32 v165, s40, v165
	v_lshl_or_b32 v165, v165, 7, v222
	global_load_lds_dwordx4 v165, s[24:25]
	s_waitcnt vmcnt(8)
	v_add_u32_e32 v146, s13, v225
	v_add_u32_e32 v147, s13, v226
	v_add_u32_e32 v148, s13, v227
	v_add_u32_e32 v149, s13, v228
	ds_read_b64_tr_b16 v[88:89], v146
	ds_read_b64_tr_b16 v[90:91], v147
	ds_read_b64_tr_b16 v[92:93], v148
	ds_read_b64_tr_b16 v[94:95], v149
	s_waitcnt lgkmcnt(0)
	v_mfma_f32_16x16x16_bf16 v[96:99], v[88:89], v[8:9], v[96:99]
	v_mfma_f32_16x16x16_bf16 v[100:103], v[90:91], v[8:9], v[100:103]
	v_mfma_f32_16x16x16_bf16 v[104:107], v[92:93], v[8:9], v[104:107]
	v_mfma_f32_16x16x16_bf16 v[108:111], v[94:95], v[8:9], v[108:111]
	s_waitcnt lgkmcnt(0)
	s_add_i32 s93, s76, 0x300
	s_mov_b32 m0, s13
	v_add_u32_e32 v164, s93, v231
	v_max_i32_e32 v164, 0, v164
	v_min_u32_e32 v164, s40, v164
	v_lshl_or_b32 v164, v164, 7, v222
	global_load_lds_dwordx4 v164, s[24:25]
	s_add_i32 m0, s13, 0x400
	v_add_u32_e32 v165, s93, v232
	v_max_i32_e32 v165, 0, v165
	v_min_u32_e32 v165, s40, v165
	v_lshl_or_b32 v165, v165, 7, v222
	global_load_lds_dwordx4 v165, s[24:25]
	s_waitcnt vmcnt(8)
	v_add_u32_e32 v146, s14, v225
	v_add_u32_e32 v147, s14, v226
	v_add_u32_e32 v148, s14, v227
	v_add_u32_e32 v149, s14, v228
	ds_read_b64_tr_b16 v[88:89], v146
	ds_read_b64_tr_b16 v[90:91], v147
	ds_read_b64_tr_b16 v[92:93], v148
	ds_read_b64_tr_b16 v[94:95], v149
	s_waitcnt lgkmcnt(0)
	v_mfma_f32_16x16x16_bf16 v[96:99], v[88:89], v[12:13], v[96:99]
	v_mfma_f32_16x16x16_bf16 v[100:103], v[90:91], v[12:13], v[100:103]
	v_mfma_f32_16x16x16_bf16 v[104:107], v[92:93], v[12:13], v[104:107]
	v_mfma_f32_16x16x16_bf16 v[108:111], v[94:95], v[12:13], v[108:111]
	s_waitcnt lgkmcnt(0)
	s_add_i32 s93, s76, 0x400
	s_mov_b32 m0, s14
	v_add_u32_e32 v164, s93, v231
	v_max_i32_e32 v164, 0, v164
	v_min_u32_e32 v164, s40, v164
	v_lshl_or_b32 v164, v164, 7, v222
	global_load_lds_dwordx4 v164, s[24:25]
	s_add_i32 m0, s14, 0x400
	v_add_u32_e32 v165, s93, v232
	v_max_i32_e32 v165, 0, v165
	v_min_u32_e32 v165, s40, v165
	v_lshl_or_b32 v165, v165, 7, v222
	global_load_lds_dwordx4 v165, s[24:25]
	s_waitcnt vmcnt(8)
	v_add_u32_e32 v146, s15, v225
	v_add_u32_e32 v147, s15, v226
	v_add_u32_e32 v148, s15, v227
	v_add_u32_e32 v149, s15, v228
	ds_read_b64_tr_b16 v[88:89], v146
	ds_read_b64_tr_b16 v[90:91], v147
	ds_read_b64_tr_b16 v[92:93], v148
	ds_read_b64_tr_b16 v[94:95], v149
	s_waitcnt lgkmcnt(0)
	v_mfma_f32_16x16x16_bf16 v[96:99], v[88:89], v[16:17], v[96:99]
	v_mfma_f32_16x16x16_bf16 v[100:103], v[90:91], v[16:17], v[100:103]
	v_mfma_f32_16x16x16_bf16 v[104:107], v[92:93], v[16:17], v[104:107]
	v_mfma_f32_16x16x16_bf16 v[108:111], v[94:95], v[16:17], v[108:111]
	s_waitcnt lgkmcnt(0)
	s_add_i32 s93, s79, 0
	s_mov_b32 m0, s15
	v_add_u32_e32 v164, s93, v231
	v_lshl_or_b32 v164, v164, 7, v220
	global_load_lds_dwordx4 v164, s[18:19]
	s_add_i32 m0, s15, 0x400
	v_add_u32_e32 v165, s93, v232
	v_lshl_or_b32 v165, v165, 7, v221
	global_load_lds_dwordx4 v165, s[18:19]
	s_waitcnt vmcnt(8)
	v_add_u32_e32 v146, s16, v225
	v_add_u32_e32 v147, s16, v226
	v_add_u32_e32 v148, s16, v227
	v_add_u32_e32 v149, s16, v228
	ds_read_b64_tr_b16 v[88:89], v146
	ds_read_b64_tr_b16 v[90:91], v147
	ds_read_b64_tr_b16 v[92:93], v148
	ds_read_b64_tr_b16 v[94:95], v149
	s_waitcnt lgkmcnt(0)
	v_mfma_f32_16x16x16_bf16 v[96:99], v[88:89], v[20:21], v[96:99]
	v_mfma_f32_16x16x16_bf16 v[100:103], v[90:91], v[20:21], v[100:103]
	v_mfma_f32_16x16x16_bf16 v[104:107], v[92:93], v[20:21], v[104:107]
	v_mfma_f32_16x16x16_bf16 v[108:111], v[94:95], v[20:21], v[108:111]
	s_waitcnt lgkmcnt(0)
	s_add_i32 s93, s79, 0xfffffc00
	s_mov_b32 m0, s16
	v_add_u32_e32 v164, s93, v231
	v_max_i32_e32 v164, 0, v164
	v_min_u32_e32 v164, s40, v164
	v_lshl_or_b32 v164, v164, 7, v220
	global_load_lds_dwordx4 v164, s[20:21]
	s_add_i32 m0, s16, 0x400
	v_add_u32_e32 v165, s93, v232
	v_max_i32_e32 v165, 0, v165
	v_min_u32_e32 v165, s40, v165
	v_lshl_or_b32 v165, v165, 7, v221
	global_load_lds_dwordx4 v165, s[20:21]
	s_waitcnt vmcnt(8)
	v_add_u32_e32 v146, s12, v225
	v_add_u32_e32 v147, s12, v226
	v_add_u32_e32 v148, s12, v227
	v_add_u32_e32 v149, s12, v228
	ds_read_b64_tr_b16 v[88:89], v146
	ds_read_b64_tr_b16 v[90:91], v147
	ds_read_b64_tr_b16 v[92:93], v148
	ds_read_b64_tr_b16 v[94:95], v149
	s_waitcnt lgkmcnt(0)
	v_mfma_f32_16x16x16_bf16 v[96:99], v[88:89], v[24:25], v[96:99]
	v_mfma_f32_16x16x16_bf16 v[100:103], v[90:91], v[24:25], v[100:103]
	v_mfma_f32_16x16x16_bf16 v[104:107], v[92:93], v[24:25], v[104:107]
	v_mfma_f32_16x16x16_bf16 v[108:111], v[94:95], v[24:25], v[108:111]
	s_waitcnt lgkmcnt(0)
	s_add_i32 s93, s79, 0xfffffd00
	s_mov_b32 m0, s12
	v_add_u32_e32 v164, s93, v231
	v_max_i32_e32 v164, 0, v164
	v_min_u32_e32 v164, s40, v164
	v_lshl_or_b32 v164, v164, 7, v220
	global_load_lds_dwordx4 v164, s[20:21]
	s_add_i32 m0, s12, 0x400
	v_add_u32_e32 v165, s93, v232
	v_max_i32_e32 v165, 0, v165
	v_min_u32_e32 v165, s40, v165
	v_lshl_or_b32 v165, v165, 7, v221
	global_load_lds_dwordx4 v165, s[20:21]
	s_waitcnt vmcnt(8)
	v_add_u32_e32 v146, s13, v225
	v_add_u32_e32 v147, s13, v226
	v_add_u32_e32 v148, s13, v227
	v_add_u32_e32 v149, s13, v228
	ds_read_b64_tr_b16 v[88:89], v146
	ds_read_b64_tr_b16 v[90:91], v147
	ds_read_b64_tr_b16 v[92:93], v148
	ds_read_b64_tr_b16 v[94:95], v149
	s_waitcnt lgkmcnt(0)
	v_mfma_f32_16x16x16_bf16 v[96:99], v[88:89], v[28:29], v[96:99]
	v_mfma_f32_16x16x16_bf16 v[100:103], v[90:91], v[28:29], v[100:103]
	v_mfma_f32_16x16x16_bf16 v[104:107], v[92:93], v[28:29], v[104:107]
	v_mfma_f32_16x16x16_bf16 v[108:111], v[94:95], v[28:29], v[108:111]
	s_waitcnt lgkmcnt(0)
	s_add_i32 s93, s79, 0xfffffe00
	s_mov_b32 m0, s13
	v_add_u32_e32 v164, s93, v231
	v_max_i32_e32 v164, 0, v164
	v_min_u32_e32 v164, s40, v164
	v_lshl_or_b32 v164, v164, 7, v220
	global_load_lds_dwordx4 v164, s[20:21]
	s_add_i32 m0, s13, 0x400
	v_add_u32_e32 v165, s93, v232
	v_max_i32_e32 v165, 0, v165
	v_min_u32_e32 v165, s40, v165
	v_lshl_or_b32 v165, v165, 7, v221
	global_load_lds_dwordx4 v165, s[20:21]
	s_waitcnt vmcnt(8)
	v_add_u32_e32 v146, s14, v225
	v_add_u32_e32 v147, s14, v226
	v_add_u32_e32 v148, s14, v227
	v_add_u32_e32 v149, s14, v228
	ds_read_b64_tr_b16 v[88:89], v146
	ds_read_b64_tr_b16 v[90:91], v147
	ds_read_b64_tr_b16 v[92:93], v148
	ds_read_b64_tr_b16 v[94:95], v149
	s_waitcnt lgkmcnt(0)
	v_mfma_f32_16x16x16_bf16 v[96:99], v[88:89], v[32:33], v[96:99]
	v_mfma_f32_16x16x16_bf16 v[100:103], v[90:91], v[32:33], v[100:103]
	v_mfma_f32_16x16x16_bf16 v[104:107], v[92:93], v[32:33], v[104:107]
	v_mfma_f32_16x16x16_bf16 v[108:111], v[94:95], v[32:33], v[108:111]
	s_waitcnt lgkmcnt(0)
	v_max_f32_e32 v146, v144, v184
	v_sub_f32_e32 v148, v144, v146
	v_sub_f32_e32 v150, v184, v146
	v_exp_f32_e32 v148, v148
	v_exp_f32_e32 v150, v150
	v_mov_b32_e32 v184, v146
	v_mul_f32_e32 v185, v185, v150
	v_fmac_f32_e32 v185, v145, v148
	v_pk_mul_f32 v[96:97], v[150:151], v[96:97] op_sel_hi:[0,1]
	v_pk_mul_f32 v[98:99], v[150:151], v[98:99] op_sel_hi:[0,1]
	v_pk_mul_f32 v[100:101], v[150:151], v[100:101] op_sel_hi:[0,1]
	v_pk_mul_f32 v[102:103], v[150:151], v[102:103] op_sel_hi:[0,1]
	v_pk_mul_f32 v[104:105], v[150:151], v[104:105] op_sel_hi:[0,1]
	v_pk_mul_f32 v[106:107], v[150:151], v[106:107] op_sel_hi:[0,1]
	v_pk_mul_f32 v[108:109], v[150:151], v[108:109] op_sel_hi:[0,1]
	v_pk_mul_f32 v[110:111], v[150:151], v[110:111] op_sel_hi:[0,1]
	v_pk_fma_f32 v[96:97], v[148:149], v[128:129], v[96:97] op_sel_hi:[0,1,1]
	v_pk_fma_f32 v[98:99], v[148:149], v[130:131], v[98:99] op_sel_hi:[0,1,1]
	v_pk_fma_f32 v[100:101], v[148:149], v[132:133], v[100:101] op_sel_hi:[0,1,1]
	v_pk_fma_f32 v[102:103], v[148:149], v[134:135], v[102:103] op_sel_hi:[0,1,1]
	v_pk_fma_f32 v[104:105], v[148:149], v[136:137], v[104:105] op_sel_hi:[0,1,1]
	v_pk_fma_f32 v[106:107], v[148:149], v[138:139], v[106:107] op_sel_hi:[0,1,1]
	v_pk_fma_f32 v[108:109], v[148:149], v[140:141], v[108:109] op_sel_hi:[0,1,1]
	v_pk_fma_f32 v[110:111], v[148:149], v[142:143], v[110:111] op_sel_hi:[0,1,1]
	v_div_scale_f32 v147, s[94:95], v185, v185, 1.0
	v_rcp_f32_e32 v148, v147
	v_div_scale_f32 v149, vcc, 1.0, v185, 1.0
	v_fma_f32 v150, -v147, v148, 1.0
	v_fmac_f32_e32 v148, v150, v148
	v_mul_f32_e32 v150, v149, v148
	v_fma_f32 v151, -v147, v150, v149
	v_fmac_f32_e32 v150, v151, v148
	v_fma_f32 v147, -v147, v150, v149
	s_nop 1
	v_div_fmas_f32 v147, v147, v148, v150
	v_div_fixup_f32 v152, v147, v185, 1.0
	v_pk_mul_f32 v[96:97], v[152:153], v[96:97] op_sel_hi:[0,1]
	v_pk_mul_f32 v[98:99], v[152:153], v[98:99] op_sel_hi:[0,1]
	v_pk_mul_f32 v[100:101], v[152:153], v[100:101] op_sel_hi:[0,1]
	v_pk_mul_f32 v[102:103], v[152:153], v[102:103] op_sel_hi:[0,1]
	v_pk_mul_f32 v[104:105], v[152:153], v[104:105] op_sel_hi:[0,1]
	v_pk_mul_f32 v[106:107], v[152:153], v[106:107] op_sel_hi:[0,1]
	v_pk_mul_f32 v[108:109], v[152:153], v[108:109] op_sel_hi:[0,1]
	v_pk_mul_f32 v[110:111], v[152:153], v[110:111] op_sel_hi:[0,1]
	v_mul_f32_e32 v155, v97, v97
	v_mul_f32_e32 v156, v99, v99
	v_fmac_f32_e32 v155, v96, v96
	v_fmac_f32_e32 v156, v98, v98
	v_add_f32_e32 v154, v155, v156
	v_mul_f32_e32 v155, v101, v101
	v_mul_f32_e32 v156, v103, v103
	v_fmac_f32_e32 v155, v100, v100
	v_fmac_f32_e32 v156, v102, v102
	v_add_f32_e32 v155, v155, v156
	v_add_f32_e32 v154, v154, v155
	v_mul_f32_e32 v155, v105, v105
	v_mul_f32_e32 v156, v107, v107
	v_fmac_f32_e32 v155, v104, v104
	v_fmac_f32_e32 v156, v106, v106
	v_add_f32_e32 v155, v155, v156
	v_add_f32_e32 v154, v154, v155
	v_mul_f32_e32 v155, v109, v109
	v_mul_f32_e32 v156, v111, v111
	v_fmac_f32_e32 v155, v108, v108
	v_fmac_f32_e32 v156, v110, v110
	v_add_f32_e32 v155, v155, v156
	v_add_f32_e32 v154, v154, v155
	v_cvt_pk_bf16_f32 v96, v96, v97
	v_cvt_pk_bf16_f32 v97, v98, v99
	v_cvt_pk_bf16_f32 v100, v100, v101
	v_cvt_pk_bf16_f32 v101, v102, v103
	v_cvt_pk_bf16_f32 v104, v104, v105
	v_cvt_pk_bf16_f32 v105, v106, v107
	v_cvt_pk_bf16_f32 v108, v108, v109
	v_cvt_pk_bf16_f32 v109, v110, v111
	v_add_u32_e32 v157, s42, v188
	s_lshl_b32 s90, s43, 7
	v_lshlrev_b32_e32 v158, 11, v157
	v_add3_u32 v158, v158, s90, v233
	v_mov_b32_e32 v160, v96
	v_mov_b32_e32 v161, v97
	v_mov_b32_e32 v162, v100
	v_mov_b32_e32 v163, v101
	s_nop 1
	v_permlane16_swap_b32_e32 v160, v162
	v_permlane16_swap_b32_e32 v161, v163
	s_nop 1
	global_store_dwordx4 v158, v[160:163], s[48:49] offset:0
	s_nop 1
	v_mov_b32_e32 v160, v104
	v_mov_b32_e32 v161, v105
	v_mov_b32_e32 v162, v108
	v_mov_b32_e32 v163, v109
	s_nop 1
	v_permlane16_swap_b32_e32 v160, v162
	v_permlane16_swap_b32_e32 v161, v163
	s_nop 1
	global_store_dwordx4 v158, v[160:163], s[48:49] offset:64
	s_nop 1
	v_mov_b32_e32 v155, v154
	s_nop 1
	v_permlane16_swap_b32_e32 v154, v155
	v_add_f32_e32 v154, v154, v155
	v_mov_b32_e32 v155, v154
	s_nop 1
	v_permlane32_swap_b32_e32 v154, v155
	v_add_f32_e32 v154, v154, v155
	v_mul_u32_u24_e32 v157, 48, v157
	s_lshl_b32 s90, s43, 2
	v_add_u32_e32 v157, s90, v157
	s_and_saveexec_b64 s[80:81], s[74:75]
	global_store_dword v157, v154, s[50:51]
	s_mov_b64 exec, s[80:81]
	s_add_i32 s76, s38, s85
	s_add_i32 s79, s39, s82
	v_lshlrev_b32_e32 v231, 4, v218
	v_add_u32_e32 v232, 8, v218
	v_lshlrev_b32_e32 v232, 4, v232
	v_lshlrev_b32_e32 v162, 0, v218
	v_add_u32_e32 v163, 8, v218
	v_lshlrev_b32_e32 v163, 0, v163
	s_waitcnt lgkmcnt(0)
	s_add_i32 s93, s76, 0xffffff00
	s_mov_b32 m0, s14
	v_add_u32_e32 v164, s93, v231
	v_max_i32_e32 v164, 0, v164
	v_min_u32_e32 v164, s40, v164
	v_lshl_or_b32 v164, v164, 7, v220
	global_load_lds_dwordx4 v164, s[20:21]
	s_add_i32 m0, s14, 0x400
	v_add_u32_e32 v165, s93, v232
	v_max_i32_e32 v165, 0, v165
	v_min_u32_e32 v165, s40, v165
	v_lshl_or_b32 v165, v165, 7, v221
	global_load_lds_dwordx4 v165, s[20:21]
	s_waitcnt vmcnt(8)
	v_add_u32_e32 v146, s15, v223
	v_add_u32_e32 v147, s15, v224
	ds_read_b128 v[72:75], v146
	ds_read_b128 v[76:79], v147
	s_waitcnt lgkmcnt(0)
	s_add_i32 s93, s76, 0
	s_mov_b32 m0, s15
	v_add_u32_e32 v164, s93, v231
	v_max_i32_e32 v164, 0, v164
	v_min_u32_e32 v164, s40, v164
	v_lshl_or_b32 v164, v164, 7, v220
	global_load_lds_dwordx4 v164, s[20:21]
	s_add_i32 m0, s15, 0x400
	v_add_u32_e32 v165, s93, v232
	v_max_i32_e32 v165, 0, v165
	v_min_u32_e32 v165, s40, v165
	v_lshl_or_b32 v165, v165, 7, v221
	global_load_lds_dwordx4 v165, s[20:21]
	s_waitcnt vmcnt(8)
	v_add_u32_e32 v146, s16, v223
	v_add_u32_e32 v147, s16, v224
	ds_read_b128 v[88:91], v146
	ds_read_b128 v[92:95], v147
	s_waitcnt lgkmcnt(0)
	v_mfma_f32_16x16x32_bf16 v[0:3], v[88:91], v[72:75], 0
	v_mfma_f32_16x16x32_bf16 v[0:3], v[92:95], v[76:79], v[0:3]
	s_waitcnt lgkmcnt(0)
	s_add_i32 s93, s76, 0x100
	s_mov_b32 m0, s16
	v_add_u32_e32 v164, s93, v231
	v_max_i32_e32 v164, 0, v164
	v_min_u32_e32 v164, s40, v164
	v_lshl_or_b32 v164, v164, 7, v220
	global_load_lds_dwordx4 v164, s[20:21]
	s_add_i32 m0, s16, 0x400
	v_add_u32_e32 v165, s93, v232
	v_max_i32_e32 v165, 0, v165
	v_min_u32_e32 v165, s40, v165
	v_lshl_or_b32 v165, v165, 7, v221
	global_load_lds_dwordx4 v165, s[20:21]
	s_waitcnt vmcnt(8)
	v_add_u32_e32 v146, s12, v223
	v_add_u32_e32 v147, s12, v224
	ds_read_b128 v[88:91], v146
	ds_read_b128 v[92:95], v147
	s_waitcnt lgkmcnt(0)
	v_mfma_f32_16x16x32_bf16 v[4:7], v[88:91], v[72:75], 0
	v_mfma_f32_16x16x32_bf16 v[4:7], v[92:95], v[76:79], v[4:7]
	s_waitcnt lgkmcnt(0)
	s_add_i32 s93, s76, 0x200
	s_mov_b32 m0, s12
	v_add_u32_e32 v164, s93, v231
	v_max_i32_e32 v164, 0, v164
	v_min_u32_e32 v164, s40, v164
	v_lshl_or_b32 v164, v164, 7, v220
	global_load_lds_dwordx4 v164, s[20:21]
	s_add_i32 m0, s12, 0x400
	v_add_u32_e32 v165, s93, v232
	v_max_i32_e32 v165, 0, v165
	v_min_u32_e32 v165, s40, v165
	v_lshl_or_b32 v165, v165, 7, v221
	global_load_lds_dwordx4 v165, s[20:21]
	s_waitcnt vmcnt(8)
	v_add_u32_e32 v146, s13, v223
	v_add_u32_e32 v147, s13, v224
	ds_read_b128 v[88:91], v146
	ds_read_b128 v[92:95], v147
	s_waitcnt lgkmcnt(0)
	v_mfma_f32_16x16x32_bf16 v[8:11], v[88:91], v[72:75], 0
	v_mfma_f32_16x16x32_bf16 v[8:11], v[92:95], v[76:79], v[8:11]
	s_waitcnt lgkmcnt(0)
	s_add_i32 s93, s76, 0x300
	s_mov_b32 m0, s13
	v_add_u32_e32 v164, s93, v231
	v_max_i32_e32 v164, 0, v164
	v_min_u32_e32 v164, s40, v164
	v_lshl_or_b32 v164, v164, 7, v220
	global_load_lds_dwordx4 v164, s[20:21]
	s_add_i32 m0, s13, 0x400
	v_add_u32_e32 v165, s93, v232
	v_max_i32_e32 v165, 0, v165
	v_min_u32_e32 v165, s40, v165
	v_lshl_or_b32 v165, v165, 7, v221
	global_load_lds_dwordx4 v165, s[20:21]
	s_waitcnt vmcnt(8)
	v_add_u32_e32 v146, s14, v223
	v_add_u32_e32 v147, s14, v224
	ds_read_b128 v[88:91], v146
	ds_read_b128 v[92:95], v147
	s_waitcnt lgkmcnt(0)
	v_mfma_f32_16x16x32_bf16 v[12:15], v[88:91], v[72:75], 0
	v_mfma_f32_16x16x32_bf16 v[12:15], v[92:95], v[76:79], v[12:15]
	s_waitcnt lgkmcnt(0)
	s_add_i32 s93, s76, 0x400
	s_mov_b32 m0, s14
	v_add_u32_e32 v164, s93, v231
	v_max_i32_e32 v164, 0, v164
	v_min_u32_e32 v164, s40, v164
	v_lshl_or_b32 v164, v164, 7, v220
	global_load_lds_dwordx4 v164, s[20:21]
	s_add_i32 m0, s14, 0x400
	v_add_u32_e32 v165, s93, v232
	v_max_i32_e32 v165, 0, v165
	v_min_u32_e32 v165, s40, v165
	v_lshl_or_b32 v165, v165, 7, v221
	global_load_lds_dwordx4 v165, s[20:21]
	s_waitcnt vmcnt(8)
	v_add_u32_e32 v146, s15, v223
	v_add_u32_e32 v147, s15, v224
	ds_read_b128 v[88:91], v146
	ds_read_b128 v[92:95], v147
	s_waitcnt lgkmcnt(0)
	v_mfma_f32_16x16x32_bf16 v[16:19], v[88:91], v[72:75], 0
	v_mfma_f32_16x16x32_bf16 v[16:19], v[92:95], v[76:79], v[16:19]
	s_waitcnt lgkmcnt(0)
	s_add_i32 s93, s76, 0xfffffc00
	s_mov_b32 m0, s15
	v_add_u32_e32 v164, s93, v231
	v_max_i32_e32 v164, 0, v164
	v_min_u32_e32 v164, s40, v164
	v_lshl_or_b32 v164, v164, 7, v222
	global_load_lds_dwordx4 v164, s[24:25]
	s_add_i32 m0, s15, 0x400
	v_add_u32_e32 v165, s93, v232
	v_max_i32_e32 v165, 0, v165
	v_min_u32_e32 v165, s40, v165
	v_lshl_or_b32 v165, v165, 7, v222
	global_load_lds_dwordx4 v165, s[24:25]
	s_waitcnt vmcnt(8)
	v_add_u32_e32 v146, s16, v223
	v_add_u32_e32 v147, s16, v224
	ds_read_b128 v[88:91], v146
	ds_read_b128 v[92:95], v147
	s_waitcnt lgkmcnt(0)
	v_mfma_f32_16x16x32_bf16 v[20:23], v[88:91], v[72:75], 0
	v_mfma_f32_16x16x32_bf16 v[20:23], v[92:95], v[76:79], v[20:23]
	s_waitcnt lgkmcnt(0)
	s_add_i32 s93, s76, 0xfffffd00
	s_mov_b32 m0, s16
	v_add_u32_e32 v164, s93, v231
	v_max_i32_e32 v164, 0, v164
	v_min_u32_e32 v164, s40, v164
	v_lshl_or_b32 v164, v164, 7, v222
	global_load_lds_dwordx4 v164, s[24:25]
	s_add_i32 m0, s16, 0x400
	v_add_u32_e32 v165, s93, v232
	v_max_i32_e32 v165, 0, v165
	v_min_u32_e32 v165, s40, v165
	v_lshl_or_b32 v165, v165, 7, v222
	global_load_lds_dwordx4 v165, s[24:25]
	s_waitcnt vmcnt(8)
	v_add_u32_e32 v146, s12, v223
	v_add_u32_e32 v147, s12, v224
	ds_read_b128 v[88:91], v146
	ds_read_b128 v[92:95], v147
	s_waitcnt lgkmcnt(0)
	v_mfma_f32_16x16x32_bf16 v[24:27], v[88:91], v[72:75], 0
	v_mfma_f32_16x16x32_bf16 v[24:27], v[92:95], v[76:79], v[24:27]
	s_waitcnt lgkmcnt(0)
	s_add_i32 s93, s76, 0xfffffe00
	s_mov_b32 m0, s12
	v_add_u32_e32 v164, s93, v231
	v_max_i32_e32 v164, 0, v164
	v_min_u32_e32 v164, s40, v164
	v_lshl_or_b32 v164, v164, 7, v222
	global_load_lds_dwordx4 v164, s[24:25]
	s_add_i32 m0, s12, 0x400
	v_add_u32_e32 v165, s93, v232
	v_max_i32_e32 v165, 0, v165
	v_min_u32_e32 v165, s40, v165
	v_lshl_or_b32 v165, v165, 7, v222
	global_load_lds_dwordx4 v165, s[24:25]
	s_waitcnt vmcnt(8)
	v_add_u32_e32 v146, s13, v223
	v_add_u32_e32 v147, s13, v224
	ds_read_b128 v[88:91], v146
	ds_read_b128 v[92:95], v147
	s_waitcnt lgkmcnt(0)
	v_mfma_f32_16x16x32_bf16 v[28:31], v[88:91], v[72:75], 0
	v_mfma_f32_16x16x32_bf16 v[28:31], v[92:95], v[76:79], v[28:31]
	s_waitcnt lgkmcnt(0)
	s_add_i32 s93, s76, 0xffffff00
	s_mov_b32 m0, s13
	v_add_u32_e32 v164, s93, v231
	v_max_i32_e32 v164, 0, v164
	v_min_u32_e32 v164, s40, v164
	v_lshl_or_b32 v164, v164, 7, v222
	global_load_lds_dwordx4 v164, s[24:25]
	s_add_i32 m0, s13, 0x400
	v_add_u32_e32 v165, s93, v232
	v_max_i32_e32 v165, 0, v165
	v_min_u32_e32 v165, s40, v165
	v_lshl_or_b32 v165, v165, 7, v222
	global_load_lds_dwordx4 v165, s[24:25]
	s_waitcnt vmcnt(8)
	v_add_u32_e32 v146, s14, v223
	v_add_u32_e32 v147, s14, v224
	ds_read_b128 v[88:91], v146
	ds_read_b128 v[92:95], v147
	s_waitcnt lgkmcnt(0)
	v_mfma_f32_16x16x32_bf16 v[32:35], v[88:91], v[72:75], 0
	v_mfma_f32_16x16x32_bf16 v[32:35], v[92:95], v[76:79], v[32:35]
	v_mov_b32_e32 v188, s85
	v_lshl_add_u32 v188, v216, 4, v188
	v_lshrrev_b32_e32 v146, 4, v188
	v_xor_b32_e32 v146, v146, v188
	v_and_b32_e32 v146, 15, v146
	v_lshlrev_b32_e32 v147, 8, v188
	v_or_b32_e32 v148, 0, v217
	v_xor_b32_e32 v148, v148, v146
	v_lshl_add_u32 v190, v148, 4, v147
	v_or_b32_e32 v148, 4, v217
	v_xor_b32_e32 v148, v148, v146
	v_lshl_add_u32 v191, v148, 4, v147
	v_or_b32_e32 v148, 8, v217
	v_xor_b32_e32 v148, v148, v146
	v_lshl_add_u32 v192, v148, 4, v147
	v_or_b32_e32 v148, 12, v217
	v_xor_b32_e32 v148, v148, v146
	v_lshl_add_u32 v193, v148, 4, v147
	v_lshlrev_b32_e32 v194, 3, v188
	v_add_u32_e32 v194, 0x10000, v194
	ds_read_b64 v[144:145], v194
	ds_read_b128 v[128:131], v190
	ds_read_b128 v[132:135], v191
	ds_read_b128 v[136:139], v192
	ds_read_b128 v[140:143], v193
	s_add_i32 s90, s76, 0x4f0
	s_cmp_gt_i32 s90, s40
	s_cselect_b32 s96, 1, 0
	s_cmp_lt_i32 s76, 0x400
	s_cselect_b32 s96, 1, s96
	s_ashr_i32 s77, s76, 4
	s_sub_i32 s77, 64, s77
	s_sub_i32 s78, s40, s76
	s_ashr_i32 s78, s78, 4
	s_add_i32 s78, s78, 64
	v_cndmask_b32_e64 v0, v0, v230, s[52:53]
	v_cndmask_b32_e64 v32, v32, v230, s[62:63]
	v_cndmask_b32_e64 v1, v1, v230, s[56:57]
	v_cndmask_b32_e64 v33, v33, v230, s[64:65]
	v_cndmask_b32_e64 v2, v2, v230, s[58:59]
	v_cndmask_b32_e64 v34, v34, v230, s[70:71]
	v_cndmask_b32_e64 v3, v3, v230, s[60:61]
	v_cndmask_b32_e64 v35, v35, v230, s[72:73]
	s_cmp_eq_u32 s96, 0
	s_cbranch_scc1 .Latt_noedge_6
	v_sub_u32_e32 v200, s77, v229
	s_sub_i32 s91, s78, s77
	v_sub_u32_e32 v150, 0, v200
	v_sub_u32_e32 v151, 1, v200
	v_sub_u32_e32 v152, 2, v200
	v_sub_u32_e32 v153, 3, v200
	v_cmp_lt_u32_e64 s[94:95], s91, v150
	v_cmp_lt_u32_e64 s[86:87], s91, v151
	v_cmp_lt_u32_e64 s[0:1], s91, v152
	v_cmp_lt_u32_e64 s[2:3], s91, v153
	v_cndmask_b32_e64 v0, v0, v230, s[94:95]
	v_cndmask_b32_e64 v1, v1, v230, s[86:87]
	v_cndmask_b32_e64 v2, v2, v230, s[0:1]
	v_cndmask_b32_e64 v3, v3, v230, s[2:3]
	v_sub_u32_e32 v150, 16, v200
	v_sub_u32_e32 v151, 17, v200
	v_sub_u32_e32 v152, 18, v200
	v_sub_u32_e32 v153, 19, v200
	v_cmp_lt_u32_e64 s[94:95], s91, v150
	v_cmp_lt_u32_e64 s[86:87], s91, v151
	v_cmp_lt_u32_e64 s[0:1], s91, v152
	v_cmp_lt_u32_e64 s[2:3], s91, v153
	v_cndmask_b32_e64 v4, v4, v230, s[94:95]
	v_cndmask_b32_e64 v5, v5, v230, s[86:87]
	v_cndmask_b32_e64 v6, v6, v230, s[0:1]
	v_cndmask_b32_e64 v7, v7, v230, s[2:3]
	v_sub_u32_e32 v150, 32, v200
	v_sub_u32_e32 v151, 33, v200
	v_sub_u32_e32 v152, 34, v200
	v_sub_u32_e32 v153, 35, v200
	v_cmp_lt_u32_e64 s[94:95], s91, v150
	v_cmp_lt_u32_e64 s[86:87], s91, v151
	v_cmp_lt_u32_e64 s[0:1], s91, v152
	v_cmp_lt_u32_e64 s[2:3], s91, v153
	v_cndmask_b32_e64 v8, v8, v230, s[94:95]
	v_cndmask_b32_e64 v9, v9, v230, s[86:87]
	v_cndmask_b32_e64 v10, v10, v230, s[0:1]
	v_cndmask_b32_e64 v11, v11, v230, s[2:3]
	v_sub_u32_e32 v150, 48, v200
	v_sub_u32_e32 v151, 49, v200
	v_sub_u32_e32 v152, 50, v200
	v_sub_u32_e32 v153, 51, v200
	v_cmp_lt_u32_e64 s[94:95], s91, v150
	v_cmp_lt_u32_e64 s[86:87], s91, v151
	v_cmp_lt_u32_e64 s[0:1], s91, v152
	v_cmp_lt_u32_e64 s[2:3], s91, v153
	v_cndmask_b32_e64 v12, v12, v230, s[94:95]
	v_cndmask_b32_e64 v13, v13, v230, s[86:87]
	v_cndmask_b32_e64 v14, v14, v230, s[0:1]
	v_cndmask_b32_e64 v15, v15, v230, s[2:3]
	v_sub_u32_e32 v150, 64, v200
	v_sub_u32_e32 v151, 0x41, v200
	v_sub_u32_e32 v152, 0x42, v200
	v_sub_u32_e32 v153, 0x43, v200
	v_cmp_lt_u32_e64 s[94:95], s91, v150
	v_cmp_lt_u32_e64 s[86:87], s91, v151
	v_cmp_lt_u32_e64 s[0:1], s91, v152
	v_cmp_lt_u32_e64 s[2:3], s91, v153
	v_cndmask_b32_e64 v16, v16, v230, s[94:95]
	v_cndmask_b32_e64 v17, v17, v230, s[86:87]
	v_cndmask_b32_e64 v18, v18, v230, s[0:1]
	v_cndmask_b32_e64 v19, v19, v230, s[2:3]
	v_sub_u32_e32 v150, 0x50, v200
	v_sub_u32_e32 v151, 0x51, v200
	v_sub_u32_e32 v152, 0x52, v200
	v_sub_u32_e32 v153, 0x53, v200
	v_cmp_lt_u32_e64 s[94:95], s91, v150
	v_cmp_lt_u32_e64 s[86:87], s91, v151
	v_cmp_lt_u32_e64 s[0:1], s91, v152
	v_cmp_lt_u32_e64 s[2:3], s91, v153
	v_cndmask_b32_e64 v20, v20, v230, s[94:95]
	v_cndmask_b32_e64 v21, v21, v230, s[86:87]
	v_cndmask_b32_e64 v22, v22, v230, s[0:1]
	v_cndmask_b32_e64 v23, v23, v230, s[2:3]
	v_sub_u32_e32 v150, 0x60, v200
	v_sub_u32_e32 v151, 0x61, v200
	v_sub_u32_e32 v152, 0x62, v200
	v_sub_u32_e32 v153, 0x63, v200
	v_cmp_lt_u32_e64 s[94:95], s91, v150
	v_cmp_lt_u32_e64 s[86:87], s91, v151
	v_cmp_lt_u32_e64 s[0:1], s91, v152
	v_cmp_lt_u32_e64 s[2:3], s91, v153
	v_cndmask_b32_e64 v24, v24, v230, s[94:95]
	v_cndmask_b32_e64 v25, v25, v230, s[86:87]
	v_cndmask_b32_e64 v26, v26, v230, s[0:1]
	v_cndmask_b32_e64 v27, v27, v230, s[2:3]
	v_sub_u32_e32 v150, 0x70, v200
	v_sub_u32_e32 v151, 0x71, v200
	v_sub_u32_e32 v152, 0x72, v200
	v_sub_u32_e32 v153, 0x73, v200
	v_cmp_lt_u32_e64 s[94:95], s91, v150
	v_cmp_lt_u32_e64 s[86:87], s91, v151
	v_cmp_lt_u32_e64 s[0:1], s91, v152
	v_cmp_lt_u32_e64 s[2:3], s91, v153
	v_cndmask_b32_e64 v28, v28, v230, s[94:95]
	v_cndmask_b32_e64 v29, v29, v230, s[86:87]
	v_cndmask_b32_e64 v30, v30, v230, s[0:1]
	v_cndmask_b32_e64 v31, v31, v230, s[2:3]
	v_sub_u32_e32 v150, 0x80, v200
	v_sub_u32_e32 v151, 0x81, v200
	v_sub_u32_e32 v152, 0x82, v200
	v_sub_u32_e32 v153, 0x83, v200
	v_cmp_lt_u32_e64 s[94:95], s91, v150
	v_cmp_lt_u32_e64 s[86:87], s91, v151
	v_cmp_lt_u32_e64 s[0:1], s91, v152
	v_cmp_lt_u32_e64 s[2:3], s91, v153
	v_cndmask_b32_e64 v32, v32, v230, s[94:95]
	v_cndmask_b32_e64 v33, v33, v230, s[86:87]
	v_cndmask_b32_e64 v34, v34, v230, s[0:1]
	v_cndmask_b32_e64 v35, v35, v230, s[2:3]
.Latt_noedge_6:
	s_nop 1
	v_max3_f32 v184, v0, v1, v2
	v_max3_f32 v184, v184, v3, v4
	v_max3_f32 v184, v184, v5, v6
	v_max3_f32 v184, v184, v7, v8
	v_max3_f32 v184, v184, v9, v10
	v_max3_f32 v184, v184, v11, v12
	v_max3_f32 v184, v184, v13, v14
	v_max3_f32 v184, v184, v15, v16
	v_max3_f32 v184, v184, v17, v18
	v_max3_f32 v184, v184, v19, v20
	v_max3_f32 v184, v184, v21, v22
	v_max3_f32 v184, v184, v23, v24
	v_max3_f32 v184, v184, v25, v26
	v_max3_f32 v184, v184, v27, v28
	v_max3_f32 v184, v184, v29, v30
	v_max3_f32 v184, v184, v31, v32
	v_max3_f32 v184, v184, v33, v34
	v_max_f32_e32 v184, v184, v35
	v_mov_b32_e32 v146, v184
	s_nop 1
	v_permlane16_swap_b32_e32 v184, v146
	v_max_f32_e32 v184, v184, v146
	v_mov_b32_e32 v146, v184
	s_nop 1
	v_permlane32_swap_b32_e32 v184, v146
	v_max_f32_e32 v184, v184, v146
	v_sub_f32_e32 v0, v0, v184
	v_sub_f32_e32 v1, v1, v184
	v_sub_f32_e32 v2, v2, v184
	v_sub_f32_e32 v3, v3, v184
	v_exp_f32_e32 v0, v0
	v_exp_f32_e32 v1, v1
	v_exp_f32_e32 v2, v2
	v_exp_f32_e32 v3, v3
	v_sub_f32_e32 v4, v4, v184
	v_sub_f32_e32 v5, v5, v184
	v_sub_f32_e32 v6, v6, v184
	v_sub_f32_e32 v7, v7, v184
	v_exp_f32_e32 v4, v4
	v_exp_f32_e32 v5, v5
	v_exp_f32_e32 v6, v6
	v_exp_f32_e32 v7, v7
	v_sub_f32_e32 v8, v8, v184
	v_sub_f32_e32 v9, v9, v184
	v_sub_f32_e32 v10, v10, v184
	v_sub_f32_e32 v11, v11, v184
	v_exp_f32_e32 v8, v8
	v_exp_f32_e32 v9, v9
	v_exp_f32_e32 v10, v10
	v_exp_f32_e32 v11, v11
	v_sub_f32_e32 v12, v12, v184
	v_sub_f32_e32 v13, v13, v184
	v_sub_f32_e32 v14, v14, v184
	v_sub_f32_e32 v15, v15, v184
	v_exp_f32_e32 v12, v12
	v_exp_f32_e32 v13, v13
	v_exp_f32_e32 v14, v14
	v_exp_f32_e32 v15, v15
	v_sub_f32_e32 v16, v16, v184
	v_sub_f32_e32 v17, v17, v184
	v_sub_f32_e32 v18, v18, v184
	v_sub_f32_e32 v19, v19, v184
	v_exp_f32_e32 v16, v16
	v_exp_f32_e32 v17, v17
	v_exp_f32_e32 v18, v18
	v_exp_f32_e32 v19, v19
	v_sub_f32_e32 v20, v20, v184
	v_sub_f32_e32 v21, v21, v184
	v_sub_f32_e32 v22, v22, v184
	v_sub_f32_e32 v23, v23, v184
	v_exp_f32_e32 v20, v20
	v_exp_f32_e32 v21, v21
	v_exp_f32_e32 v22, v22
	v_exp_f32_e32 v23, v23
	v_sub_f32_e32 v24, v24, v184
	v_sub_f32_e32 v25, v25, v184
	v_sub_f32_e32 v26, v26, v184
	v_sub_f32_e32 v27, v27, v184
	v_exp_f32_e32 v24, v24
	v_exp_f32_e32 v25, v25
	v_exp_f32_e32 v26, v26
	v_exp_f32_e32 v27, v27
	v_sub_f32_e32 v28, v28, v184
	v_sub_f32_e32 v29, v29, v184
	v_sub_f32_e32 v30, v30, v184
	v_sub_f32_e32 v31, v31, v184
	v_exp_f32_e32 v28, v28
	v_exp_f32_e32 v29, v29
	v_exp_f32_e32 v30, v30
	v_exp_f32_e32 v31, v31
	v_sub_f32_e32 v32, v32, v184
	v_sub_f32_e32 v33, v33, v184
	v_sub_f32_e32 v34, v34, v184
	v_sub_f32_e32 v35, v35, v184
	v_exp_f32_e32 v32, v32
	v_exp_f32_e32 v33, v33
	v_exp_f32_e32 v34, v34
	v_exp_f32_e32 v35, v35
	s_nop 0
	v_add_f32_e32 v185, v0, v1
	v_add_f32_e32 v185, v185, v2
	v_add_f32_e32 v185, v185, v3
	v_add_f32_e32 v185, v185, v4
	v_add_f32_e32 v185, v185, v5
	v_add_f32_e32 v185, v185, v6
	v_add_f32_e32 v185, v185, v7
	v_add_f32_e32 v185, v185, v8
	v_add_f32_e32 v185, v185, v9
	v_add_f32_e32 v185, v185, v10
	v_add_f32_e32 v185, v185, v11
	v_add_f32_e32 v185, v185, v12
	v_add_f32_e32 v185, v185, v13
	v_add_f32_e32 v185, v185, v14
	v_add_f32_e32 v185, v185, v15
	v_add_f32_e32 v185, v185, v16
	v_add_f32_e32 v185, v185, v17
	v_add_f32_e32 v185, v185, v18
	v_add_f32_e32 v185, v185, v19
	v_add_f32_e32 v185, v185, v20
	v_add_f32_e32 v185, v185, v21
	v_add_f32_e32 v185, v185, v22
	v_add_f32_e32 v185, v185, v23
	v_add_f32_e32 v185, v185, v24
	v_add_f32_e32 v185, v185, v25
	v_add_f32_e32 v185, v185, v26
	v_add_f32_e32 v185, v185, v27
	v_add_f32_e32 v185, v185, v28
	v_add_f32_e32 v185, v185, v29
	v_add_f32_e32 v185, v185, v30
	v_add_f32_e32 v185, v185, v31
	v_add_f32_e32 v185, v185, v32
	v_add_f32_e32 v185, v185, v33
	v_add_f32_e32 v185, v185, v34
	v_add_f32_e32 v185, v185, v35
	v_cvt_pk_bf16_f32 v0, v0, v1
	v_cvt_pk_bf16_f32 v1, v2, v3
	v_cvt_pk_bf16_f32 v4, v4, v5
	v_cvt_pk_bf16_f32 v5, v6, v7
	v_cvt_pk_bf16_f32 v8, v8, v9
	v_cvt_pk_bf16_f32 v9, v10, v11
	v_cvt_pk_bf16_f32 v12, v12, v13
	v_cvt_pk_bf16_f32 v13, v14, v15
	v_cvt_pk_bf16_f32 v16, v16, v17
	v_cvt_pk_bf16_f32 v17, v18, v19
	v_cvt_pk_bf16_f32 v20, v20, v21
	v_cvt_pk_bf16_f32 v21, v22, v23
	v_cvt_pk_bf16_f32 v24, v24, v25
	v_cvt_pk_bf16_f32 v25, v26, v27
	v_cvt_pk_bf16_f32 v28, v28, v29
	v_cvt_pk_bf16_f32 v29, v30, v31
	v_cvt_pk_bf16_f32 v32, v32, v33
	v_cvt_pk_bf16_f32 v33, v34, v35
	v_mov_b32_e32 v146, v185
	s_nop 1
	v_permlane16_swap_b32_e32 v185, v146
	v_add_f32_e32 v185, v185, v146
	v_mov_b32_e32 v146, v185
	s_nop 1
	v_permlane32_swap_b32_e32 v185, v146
	v_add_f32_e32 v185, v185, v146
	s_waitcnt lgkmcnt(0)
	s_add_i32 s93, s76, 0
	s_mov_b32 m0, s14
	v_add_u32_e32 v164, s93, v231
	v_max_i32_e32 v164, 0, v164
	v_min_u32_e32 v164, s40, v164
	v_lshl_or_b32 v164, v164, 7, v222
	global_load_lds_dwordx4 v164, s[24:25]
	s_add_i32 m0, s14, 0x400
	v_add_u32_e32 v165, s93, v232
	v_max_i32_e32 v165, 0, v165
	v_min_u32_e32 v165, s40, v165
	v_lshl_or_b32 v165, v165, 7, v222
	global_load_lds_dwordx4 v165, s[24:25]
	s_waitcnt vmcnt(8)
	v_add_u32_e32 v146, s15, v225
	v_add_u32_e32 v147, s15, v226
	v_add_u32_e32 v148, s15, v227
	v_add_u32_e32 v149, s15, v228
	ds_read_b64_tr_b16 v[88:89], v146
	ds_read_b64_tr_b16 v[90:91], v147
	ds_read_b64_tr_b16 v[92:93], v148
	ds_read_b64_tr_b16 v[94:95], v149
	s_waitcnt lgkmcnt(0)
	v_mfma_f32_16x16x16_bf16 v[96:99], v[88:89], v[0:1], 0
	v_mfma_f32_16x16x16_bf16 v[100:103], v[90:91], v[0:1], 0
	v_mfma_f32_16x16x16_bf16 v[104:107], v[92:93], v[0:1], 0
	v_mfma_f32_16x16x16_bf16 v[108:111], v[94:95], v[0:1], 0
	s_waitcnt lgkmcnt(0)
	s_add_i32 s93, s76, 0x100
	s_mov_b32 m0, s15
	v_add_u32_e32 v164, s93, v231
	v_max_i32_e32 v164, 0, v164
	v_min_u32_e32 v164, s40, v164
	v_lshl_or_b32 v164, v164, 7, v222
	global_load_lds_dwordx4 v164, s[24:25]
	s_add_i32 m0, s15, 0x400
	v_add_u32_e32 v165, s93, v232
	v_max_i32_e32 v165, 0, v165
	v_min_u32_e32 v165, s40, v165
	v_lshl_or_b32 v165, v165, 7, v222
	global_load_lds_dwordx4 v165, s[24:25]
	s_waitcnt vmcnt(8)
	v_add_u32_e32 v146, s16, v225
	v_add_u32_e32 v147, s16, v226
	v_add_u32_e32 v148, s16, v227
	v_add_u32_e32 v149, s16, v228
	ds_read_b64_tr_b16 v[88:89], v146
	ds_read_b64_tr_b16 v[90:91], v147
	ds_read_b64_tr_b16 v[92:93], v148
	ds_read_b64_tr_b16 v[94:95], v149
	s_waitcnt lgkmcnt(0)
	v_mfma_f32_16x16x16_bf16 v[96:99], v[88:89], v[4:5], v[96:99]
	v_mfma_f32_16x16x16_bf16 v[100:103], v[90:91], v[4:5], v[100:103]
	v_mfma_f32_16x16x16_bf16 v[104:107], v[92:93], v[4:5], v[104:107]
	v_mfma_f32_16x16x16_bf16 v[108:111], v[94:95], v[4:5], v[108:111]
	s_waitcnt lgkmcnt(0)
	s_add_i32 s93, s76, 0x200
	s_mov_b32 m0, s16
	v_add_u32_e32 v164, s93, v231
	v_max_i32_e32 v164, 0, v164
	v_min_u32_e32 v164, s40, v164
	v_lshl_or_b32 v164, v164, 7, v222
	global_load_lds_dwordx4 v164, s[24:25]
	s_add_i32 m0, s16, 0x400
	v_add_u32_e32 v165, s93, v232
	v_max_i32_e32 v165, 0, v165
	v_min_u32_e32 v165, s40, v165
	v_lshl_or_b32 v165, v165, 7, v222
	global_load_lds_dwordx4 v165, s[24:25]
	s_waitcnt vmcnt(8)
	v_add_u32_e32 v146, s12, v225
	v_add_u32_e32 v147, s12, v226
	v_add_u32_e32 v148, s12, v227
	v_add_u32_e32 v149, s12, v228
	ds_read_b64_tr_b16 v[88:89], v146
	ds_read_b64_tr_b16 v[90:91], v147
	ds_read_b64_tr_b16 v[92:93], v148
	ds_read_b64_tr_b16 v[94:95], v149
	s_waitcnt lgkmcnt(0)
	v_mfma_f32_16x16x16_bf16 v[96:99], v[88:89], v[8:9], v[96:99]
	v_mfma_f32_16x16x16_bf16 v[100:103], v[90:91], v[8:9], v[100:103]
	v_mfma_f32_16x16x16_bf16 v[104:107], v[92:93], v[8:9], v[104:107]
	v_mfma_f32_16x16x16_bf16 v[108:111], v[94:95], v[8:9], v[108:111]
	s_waitcnt lgkmcnt(0)
	s_add_i32 s93, s76, 0x300
	s_mov_b32 m0, s12
	v_add_u32_e32 v164, s93, v231
	v_max_i32_e32 v164, 0, v164
	v_min_u32_e32 v164, s40, v164
	v_lshl_or_b32 v164, v164, 7, v222
	global_load_lds_dwordx4 v164, s[24:25]
	s_add_i32 m0, s12, 0x400
	v_add_u32_e32 v165, s93, v232
	v_max_i32_e32 v165, 0, v165
	v_min_u32_e32 v165, s40, v165
	v_lshl_or_b32 v165, v165, 7, v222
	global_load_lds_dwordx4 v165, s[24:25]
	s_waitcnt vmcnt(8)
	v_add_u32_e32 v146, s13, v225
	v_add_u32_e32 v147, s13, v226
	v_add_u32_e32 v148, s13, v227
	v_add_u32_e32 v149, s13, v228
	ds_read_b64_tr_b16 v[88:89], v146
	ds_read_b64_tr_b16 v[90:91], v147
	ds_read_b64_tr_b16 v[92:93], v148
	ds_read_b64_tr_b16 v[94:95], v149
	s_waitcnt lgkmcnt(0)
	v_mfma_f32_16x16x16_bf16 v[96:99], v[88:89], v[12:13], v[96:99]
	v_mfma_f32_16x16x16_bf16 v[100:103], v[90:91], v[12:13], v[100:103]
	v_mfma_f32_16x16x16_bf16 v[104:107], v[92:93], v[12:13], v[104:107]
	v_mfma_f32_16x16x16_bf16 v[108:111], v[94:95], v[12:13], v[108:111]
	s_waitcnt lgkmcnt(0)
	s_add_i32 s93, s76, 0x400
	s_mov_b32 m0, s13
	v_add_u32_e32 v164, s93, v231
	v_max_i32_e32 v164, 0, v164
	v_min_u32_e32 v164, s40, v164
	v_lshl_or_b32 v164, v164, 7, v222
	global_load_lds_dwordx4 v164, s[24:25]
	s_add_i32 m0, s13, 0x400
	v_add_u32_e32 v165, s93, v232
	v_max_i32_e32 v165, 0, v165
	v_min_u32_e32 v165, s40, v165
	v_lshl_or_b32 v165, v165, 7, v222
	global_load_lds_dwordx4 v165, s[24:25]
	s_waitcnt vmcnt(8)
	v_add_u32_e32 v146, s14, v225
	v_add_u32_e32 v147, s14, v226
	v_add_u32_e32 v148, s14, v227
	v_add_u32_e32 v149, s14, v228
	ds_read_b64_tr_b16 v[88:89], v146
	ds_read_b64_tr_b16 v[90:91], v147
	ds_read_b64_tr_b16 v[92:93], v148
	ds_read_b64_tr_b16 v[94:95], v149
	s_waitcnt lgkmcnt(0)
	v_mfma_f32_16x16x16_bf16 v[96:99], v[88:89], v[16:17], v[96:99]
	v_mfma_f32_16x16x16_bf16 v[100:103], v[90:91], v[16:17], v[100:103]
	v_mfma_f32_16x16x16_bf16 v[104:107], v[92:93], v[16:17], v[104:107]
	v_mfma_f32_16x16x16_bf16 v[108:111], v[94:95], v[16:17], v[108:111]
	s_waitcnt lgkmcnt(0)
	s_add_i32 s93, s79, 0
	s_mov_b32 m0, s14
	v_add_u32_e32 v164, s93, v162
	v_lshl_or_b32 v164, v164, 7, v220
	global_load_lds_dwordx4 v164, s[30:31]
	s_add_i32 m0, s14, 0x400
	v_add_u32_e32 v165, s93, v163
	v_lshl_or_b32 v165, v165, 7, v221
	global_load_lds_dwordx4 v165, s[30:31]
	s_waitcnt vmcnt(8)
	v_add_u32_e32 v146, s15, v225
	v_add_u32_e32 v147, s15, v226
	v_add_u32_e32 v148, s15, v227
	v_add_u32_e32 v149, s15, v228
	ds_read_b64_tr_b16 v[88:89], v146
	ds_read_b64_tr_b16 v[90:91], v147
	ds_read_b64_tr_b16 v[92:93], v148
	ds_read_b64_tr_b16 v[94:95], v149
	s_waitcnt lgkmcnt(0)
	v_mfma_f32_16x16x16_bf16 v[96:99], v[88:89], v[20:21], v[96:99]
	v_mfma_f32_16x16x16_bf16 v[100:103], v[90:91], v[20:21], v[100:103]
	v_mfma_f32_16x16x16_bf16 v[104:107], v[92:93], v[20:21], v[104:107]
	v_mfma_f32_16x16x16_bf16 v[108:111], v[94:95], v[20:21], v[108:111]
	s_waitcnt lgkmcnt(0)
	s_add_i32 s93, s79, 16
	s_mov_b32 m0, s15
	v_add_u32_e32 v164, s93, v162
	v_lshl_or_b32 v164, v164, 7, v220
	global_load_lds_dwordx4 v164, s[30:31]
	s_add_i32 m0, s15, 0x400
	v_add_u32_e32 v165, s93, v163
	v_lshl_or_b32 v165, v165, 7, v221
	global_load_lds_dwordx4 v165, s[30:31]
	s_waitcnt vmcnt(8)
	v_add_u32_e32 v146, s16, v225
	v_add_u32_e32 v147, s16, v226
	v_add_u32_e32 v148, s16, v227
	v_add_u32_e32 v149, s16, v228
	ds_read_b64_tr_b16 v[88:89], v146
	ds_read_b64_tr_b16 v[90:91], v147
	ds_read_b64_tr_b16 v[92:93], v148
	ds_read_b64_tr_b16 v[94:95], v149
	s_waitcnt lgkmcnt(0)
	v_mfma_f32_16x16x16_bf16 v[96:99], v[88:89], v[24:25], v[96:99]
	v_mfma_f32_16x16x16_bf16 v[100:103], v[90:91], v[24:25], v[100:103]
	v_mfma_f32_16x16x16_bf16 v[104:107], v[92:93], v[24:25], v[104:107]
	v_mfma_f32_16x16x16_bf16 v[108:111], v[94:95], v[24:25], v[108:111]
	s_waitcnt lgkmcnt(0)
	s_add_i32 s93, s79, 0xffffffc0
	s_mov_b32 m0, s16
	v_add_u32_e32 v164, s93, v162
	v_max_i32_e32 v164, 0, v164
	v_min_u32_e32 v164, s41, v164
	v_lshl_or_b32 v164, v164, 7, v220
	global_load_lds_dwordx4 v164, s[34:35]
	s_add_i32 m0, s16, 0x400
	v_add_u32_e32 v165, s93, v163
	v_max_i32_e32 v165, 0, v165
	v_min_u32_e32 v165, s41, v165
	v_lshl_or_b32 v165, v165, 7, v221
	global_load_lds_dwordx4 v165, s[34:35]
	s_waitcnt vmcnt(8)
	v_add_u32_e32 v146, s12, v225
	v_add_u32_e32 v147, s12, v226
	v_add_u32_e32 v148, s12, v227
	v_add_u32_e32 v149, s12, v228
	ds_read_b64_tr_b16 v[88:89], v146
	ds_read_b64_tr_b16 v[90:91], v147
	ds_read_b64_tr_b16 v[92:93], v148
	ds_read_b64_tr_b16 v[94:95], v149
	s_waitcnt lgkmcnt(0)
	v_mfma_f32_16x16x16_bf16 v[96:99], v[88:89], v[28:29], v[96:99]
	v_mfma_f32_16x16x16_bf16 v[100:103], v[90:91], v[28:29], v[100:103]
	v_mfma_f32_16x16x16_bf16 v[104:107], v[92:93], v[28:29], v[104:107]
	v_mfma_f32_16x16x16_bf16 v[108:111], v[94:95], v[28:29], v[108:111]
	s_waitcnt lgkmcnt(0)
	s_add_i32 s93, s79, 0xffffffd0
	s_mov_b32 m0, s12
	v_add_u32_e32 v164, s93, v162
	v_max_i32_e32 v164, 0, v164
	v_min_u32_e32 v164, s41, v164
	v_lshl_or_b32 v164, v164, 7, v220
	global_load_lds_dwordx4 v164, s[34:35]
	s_add_i32 m0, s12, 0x400
	v_add_u32_e32 v165, s93, v163
	v_max_i32_e32 v165, 0, v165
	v_min_u32_e32 v165, s41, v165
	v_lshl_or_b32 v165, v165, 7, v221
	global_load_lds_dwordx4 v165, s[34:35]
	s_waitcnt vmcnt(8)
	v_add_u32_e32 v146, s13, v225
	v_add_u32_e32 v147, s13, v226
	v_add_u32_e32 v148, s13, v227
	v_add_u32_e32 v149, s13, v228
	ds_read_b64_tr_b16 v[88:89], v146
	ds_read_b64_tr_b16 v[90:91], v147
	ds_read_b64_tr_b16 v[92:93], v148
	ds_read_b64_tr_b16 v[94:95], v149
	s_waitcnt lgkmcnt(0)
	v_mfma_f32_16x16x16_bf16 v[96:99], v[88:89], v[32:33], v[96:99]
	v_mfma_f32_16x16x16_bf16 v[100:103], v[90:91], v[32:33], v[100:103]
	v_mfma_f32_16x16x16_bf16 v[104:107], v[92:93], v[32:33], v[104:107]
	v_mfma_f32_16x16x16_bf16 v[108:111], v[94:95], v[32:33], v[108:111]
	s_waitcnt lgkmcnt(0)
	v_max_f32_e32 v146, v144, v184
	v_sub_f32_e32 v148, v144, v146
	v_sub_f32_e32 v150, v184, v146
	v_exp_f32_e32 v148, v148
	v_exp_f32_e32 v150, v150
	v_mov_b32_e32 v184, v146
	v_mul_f32_e32 v185, v185, v150
	v_fmac_f32_e32 v185, v145, v148
	v_pk_mul_f32 v[96:97], v[150:151], v[96:97] op_sel_hi:[0,1]
	v_pk_mul_f32 v[98:99], v[150:151], v[98:99] op_sel_hi:[0,1]
	v_pk_mul_f32 v[100:101], v[150:151], v[100:101] op_sel_hi:[0,1]
	v_pk_mul_f32 v[102:103], v[150:151], v[102:103] op_sel_hi:[0,1]
	v_pk_mul_f32 v[104:105], v[150:151], v[104:105] op_sel_hi:[0,1]
	v_pk_mul_f32 v[106:107], v[150:151], v[106:107] op_sel_hi:[0,1]
	v_pk_mul_f32 v[108:109], v[150:151], v[108:109] op_sel_hi:[0,1]
	v_pk_mul_f32 v[110:111], v[150:151], v[110:111] op_sel_hi:[0,1]
	v_pk_fma_f32 v[96:97], v[148:149], v[128:129], v[96:97] op_sel_hi:[0,1,1]
	v_pk_fma_f32 v[98:99], v[148:149], v[130:131], v[98:99] op_sel_hi:[0,1,1]
	v_pk_fma_f32 v[100:101], v[148:149], v[132:133], v[100:101] op_sel_hi:[0,1,1]
	v_pk_fma_f32 v[102:103], v[148:149], v[134:135], v[102:103] op_sel_hi:[0,1,1]
	v_pk_fma_f32 v[104:105], v[148:149], v[136:137], v[104:105] op_sel_hi:[0,1,1]
	v_pk_fma_f32 v[106:107], v[148:149], v[138:139], v[106:107] op_sel_hi:[0,1,1]
	v_pk_fma_f32 v[108:109], v[148:149], v[140:141], v[108:109] op_sel_hi:[0,1,1]
	v_pk_fma_f32 v[110:111], v[148:149], v[142:143], v[110:111] op_sel_hi:[0,1,1]
	v_div_scale_f32 v147, s[94:95], v185, v185, 1.0
	v_rcp_f32_e32 v148, v147
	v_div_scale_f32 v149, vcc, 1.0, v185, 1.0
	v_fma_f32 v150, -v147, v148, 1.0
	v_fmac_f32_e32 v148, v150, v148
	v_mul_f32_e32 v150, v149, v148
	v_fma_f32 v151, -v147, v150, v149
	v_fmac_f32_e32 v150, v151, v148
	v_fma_f32 v147, -v147, v150, v149
	s_nop 1
	v_div_fmas_f32 v147, v147, v148, v150
	v_div_fixup_f32 v152, v147, v185, 1.0
	v_pk_mul_f32 v[96:97], v[152:153], v[96:97] op_sel_hi:[0,1]
	v_pk_mul_f32 v[98:99], v[152:153], v[98:99] op_sel_hi:[0,1]
	v_pk_mul_f32 v[100:101], v[152:153], v[100:101] op_sel_hi:[0,1]
	v_pk_mul_f32 v[102:103], v[152:153], v[102:103] op_sel_hi:[0,1]
	v_pk_mul_f32 v[104:105], v[152:153], v[104:105] op_sel_hi:[0,1]
	v_pk_mul_f32 v[106:107], v[152:153], v[106:107] op_sel_hi:[0,1]
	v_pk_mul_f32 v[108:109], v[152:153], v[108:109] op_sel_hi:[0,1]
	v_pk_mul_f32 v[110:111], v[152:153], v[110:111] op_sel_hi:[0,1]
	v_mul_f32_e32 v155, v97, v97
	v_mul_f32_e32 v156, v99, v99
	v_fmac_f32_e32 v155, v96, v96
	v_fmac_f32_e32 v156, v98, v98
	v_add_f32_e32 v154, v155, v156
	v_mul_f32_e32 v155, v101, v101
	v_mul_f32_e32 v156, v103, v103
	v_fmac_f32_e32 v155, v100, v100
	v_fmac_f32_e32 v156, v102, v102
	v_add_f32_e32 v155, v155, v156
	v_add_f32_e32 v154, v154, v155
	v_mul_f32_e32 v155, v105, v105
	v_mul_f32_e32 v156, v107, v107
	v_fmac_f32_e32 v155, v104, v104
	v_fmac_f32_e32 v156, v106, v106
	v_add_f32_e32 v155, v155, v156
	v_add_f32_e32 v154, v154, v155
	v_mul_f32_e32 v155, v109, v109
	v_mul_f32_e32 v156, v111, v111
	v_fmac_f32_e32 v155, v108, v108
	v_fmac_f32_e32 v156, v110, v110
	v_add_f32_e32 v155, v155, v156
	v_add_f32_e32 v154, v154, v155
	v_cvt_pk_bf16_f32 v96, v96, v97
	v_cvt_pk_bf16_f32 v97, v98, v99
	v_cvt_pk_bf16_f32 v100, v100, v101
	v_cvt_pk_bf16_f32 v101, v102, v103
	v_cvt_pk_bf16_f32 v104, v104, v105
	v_cvt_pk_bf16_f32 v105, v106, v107
	v_cvt_pk_bf16_f32 v108, v108, v109
	v_cvt_pk_bf16_f32 v109, v110, v111
	v_add_u32_e32 v157, s42, v188
	s_lshl_b32 s90, s43, 7
	v_lshlrev_b32_e32 v158, 11, v157
	v_add3_u32 v158, v158, s90, v233
	v_mov_b32_e32 v160, v96
	v_mov_b32_e32 v161, v97
	v_mov_b32_e32 v162, v100
	v_mov_b32_e32 v163, v101
	s_nop 1
	v_permlane16_swap_b32_e32 v160, v162
	v_permlane16_swap_b32_e32 v161, v163
	s_nop 1
	global_store_dwordx4 v158, v[160:163], s[48:49] offset:0
	s_nop 1
	v_mov_b32_e32 v160, v104
	v_mov_b32_e32 v161, v105
	v_mov_b32_e32 v162, v108
	v_mov_b32_e32 v163, v109
	s_nop 1
	v_permlane16_swap_b32_e32 v160, v162
	v_permlane16_swap_b32_e32 v161, v163
	s_nop 1
	global_store_dwordx4 v158, v[160:163], s[48:49] offset:64
	s_nop 1
	v_mov_b32_e32 v155, v154
	s_nop 1
	v_permlane16_swap_b32_e32 v154, v155
	v_add_f32_e32 v154, v154, v155
	v_mov_b32_e32 v155, v154
	s_nop 1
	v_permlane32_swap_b32_e32 v154, v155
	v_add_f32_e32 v154, v154, v155
	v_mul_u32_u24_e32 v157, 48, v157
	s_lshl_b32 s90, s43, 2
	v_add_u32_e32 v157, s90, v157
	s_and_saveexec_b64 s[80:81], s[74:75]
	global_store_dword v157, v154, s[50:51]
	s_mov_b64 exec, s[80:81]
	s_waitcnt lgkmcnt(0)
	s_barrier
	s_mov_b32 s90, s14
	s_mov_b32 s91, s15
	s_mov_b32 s92, s16
	s_mov_b32 s93, s12
	s_mov_b32 s97, s13
	s_mov_b32 s12, s90
	s_mov_b32 s13, s91
	s_mov_b32 s14, s92
	s_mov_b32 s15, s93
	s_mov_b32 s16, s97
	s_mov_b64 s[18:19], s[30:31]
	s_mov_b64 s[20:21], s[34:35]
	s_mov_b64 s[24:25], s[36:37]
	s_mov_b32 s38, s39
	s_mov_b32 s40, s41
	s_mov_b32 s42, s44
	s_mov_b32 s43, s45
	s_add_i32 s11, s11, s66
	s_cmpk_lt_u32 s11, 0x900
	s_cbranch_scc1 .Latt_unit
	v_readlane_b32 s0, v244, 20
	s_bfe_u32 s3, s0, 0x20006
